# P1 epilogue global stores carry the nt (streaming) hint
# speedup vs baseline: 1.0074x; 1.0074x over previous
; DI u32x2 pk4(f32x4 v) { u32x2 r; r.x = pk2(v[0], v[1]); r.y = pk2(v[2], v[3]); return r; }
; DI float sigmoidf_(float v) { return __builtin_amdgcn_rcpf(1.f + fast_exp2(-1.4426950408889634f * v)); }
; template <int REG>
; DI void epi_inproj(const Params& p, f32x4 (&acc)[2][2][4][2], int pm, int pn, LAS unsigned char* shm) {
;     ...
;     const f32x4 q0 = *(const f32x4*)((const float*)(ws + OFF_RSTD1Q) + T0 + (wr * 16 + fr) * 8), q1 = *(const f32x4*)((const float*)(ws + OFF_RSTD1Q) + T0 + (wr * 16 + fr) * 8 + 4);
; #pragma unroll
;     for (int m = 0; m < 4; ++m) { rsr[0][m] = q0[m]; rsr[1][m] = q1[m]; }
;     ...
;     bf16_t* dstb; int cb;
;     if (pn < 12) { dstb = (bf16_t*)(ws + OFF_G); cb = (pn - 8) * 256; }
;     else if (pn < 22) { dstb = (bf16_t*)(ws + OFF_GA); cb = (pn - 18) * 256; }
;     else { dstb = (bf16_t*)(ws + OFF_GB); cb = (pn - 22) * 256; }
;     const bool silu = pn < 12;
; #pragma unroll
;     for (int ai = 0; ai < 2; ++ai)
; #pragma unroll
;       for (int m = 0; m < 4; ++m) { asm volatile("" ::: "memory");
;         const int r = 128 * ai + 64 * wr + 16 * m + fr;
;         const float rs = rsr[ai][m];
; #pragma unroll
;         for (int bj = 0; bj < 2; ++bj) {
;           u32x2 h[2];
; #pragma unroll
;           for (int n = 0; n < 2; ++n) {
;             f32x4 v = acc[ai][bj][m][n] * rs, o;
; #pragma unroll
;             for (int j = 0; j < 4; ++j) { const float sg = sigmoidf_(v[j]); o[j] = silu ? v[j] * sg : sg; }
;             h[n] = pk4(o);
;           }
;           *(u32x4*)(dstb + (long)(T0 + r) * 1024 + cb + 128 * bj + 32 * wc + 8 * fq) = (u32x4){h[0].x, h[0].y, h[1].x, h[1].y};
;         }
.LBB0_207:
	v_mov_b32_e32 v163, v194
	s_lshl_b32 s50, s46, 8
	s_ashr_i32 s51, s50, 31
	v_and_b32_e32 v148, 15, v163
	v_ashrrev_i32_e32 v149, 8, v163
	s_lshl_b64 s[52:53], s[50:51], 2
	v_lshlrev_b32_e32 v72, 3, v148
	s_add_u32 s52, s74, s52
	v_lshl_or_b32 v72, v149, 7, v72
	s_addc_u32 s53, s75, s53
	v_ashrrev_i32_e32 v73, 31, v72
	v_lshl_add_u64 v[72:73], v[72:73], 2, s[52:53]
	global_load_dwordx4 v[132:135], v[72:73], off
	s_nop 0
	global_load_dwordx4 v[72:75], v[72:73], off offset:16
	v_or_b32_e32 v148, s50, v148
	s_lshl_b32 s46, s48, 8
	v_lshl_add_u32 v148, v149, 6, v148
	s_cmp_lt_u32 s48, 22
	v_ashrrev_i32_e32 v149, 31, v148
	s_cselect_b64 s[50:51], -1, 0
	v_lshlrev_b64 v[164:165], 11, v[148:149]
	s_and_b64 s[50:51], s[50:51], exec
	s_cselect_b32 s52, s78, 0x1a300000
	s_cselect_b32 s53, s79, 0xffffea00
	s_cmp_lt_i32 s48, 12
	s_cselect_b64 vcc, -1, 0
	s_and_b64 s[50:51], vcc, exec
	s_cselect_b32 s48, 0xc300000, s52
	s_cselect_b32 s50, 0xfffff800, s53
	s_add_u32 s48, s26, s48
	s_addc_u32 s52, s27, 0
	s_add_i32 s50, s50, s46
	s_ashr_i32 s51, s50, 31
	s_lshl_b64 s[50:51], s[50:51], 1
	s_add_u32 s50, s48, s50
	v_and_b32_e32 v144, 0xc0, v163
	s_addc_u32 s51, s52, s51
	s_waitcnt vmcnt(0)
	v_mul_f32_e32 v128, v128, v132
	v_mul_f32_e32 v129, v129, v132
	v_mul_f32_e32 v130, v130, v132
	v_mul_f32_e32 v124, v124, v132
	v_mul_f32_e32 v149, v120, v132
	v_mul_f32_e32 v166, v121, v132
	v_mul_f32_e32 v120, 0xbfb8aa3b, v128
	v_mul_f32_e32 v121, 0xbfb8aa3b, v129
	v_mul_f32_e32 v131, v131, v132
	v_mul_f32_e32 v125, v125, v132
	v_mul_f32_e32 v126, v126, v132
	v_mul_f32_e32 v127, v127, v132
	v_mul_f32_e32 v167, 0xbfb8aa3b, v130
	v_mul_f32_e32 v169, 0xbfb8aa3b, v124
	v_exp_f32_e32 v120, v120
	v_exp_f32_e32 v121, v121
	v_mul_f32_e32 v168, 0xbfb8aa3b, v131
	v_mul_f32_e32 v170, 0xbfb8aa3b, v125
	v_mul_f32_e32 v171, 0xbfb8aa3b, v126
	v_mul_f32_e32 v172, 0xbfb8aa3b, v127
	v_exp_f32_e32 v167, v167
	v_exp_f32_e32 v169, v169
	v_exp_f32_e32 v168, v168
	v_exp_f32_e32 v170, v170
	v_exp_f32_e32 v171, v171
	v_exp_f32_e32 v172, v172
	v_add_f32_e32 v120, 1.0, v120
	v_add_f32_e32 v121, 1.0, v121
	v_add_f32_e32 v167, 1.0, v167
	v_add_f32_e32 v169, 1.0, v169
	v_rcp_f32_e32 v120, v120
	v_rcp_f32_e32 v121, v121
	v_add_f32_e32 v168, 1.0, v168
	v_add_f32_e32 v170, 1.0, v170
	v_add_f32_e32 v171, 1.0, v171
	v_add_f32_e32 v172, 1.0, v172
	v_rcp_f32_e32 v167, v167
	v_rcp_f32_e32 v169, v169
	v_rcp_f32_e32 v168, v168
	v_rcp_f32_e32 v170, v170
	v_rcp_f32_e32 v171, v171
	v_rcp_f32_e32 v172, v172
	v_mul_f32_e32 v128, v128, v120
	v_mul_f32_e32 v129, v129, v121
	v_mul_f32_e32 v130, v130, v167
	v_mul_f32_e32 v124, v124, v169
	v_cndmask_b32_e32 v120, v120, v128, vcc
	v_cndmask_b32_e32 v121, v121, v129, vcc
	v_mul_f32_e32 v131, v131, v168
	v_mul_f32_e32 v125, v125, v170
	v_mul_f32_e32 v126, v126, v171
	v_mul_f32_e32 v127, v127, v172
	v_cndmask_b32_e32 v128, v167, v130, vcc
	v_cndmask_b32_e32 v130, v169, v124, vcc
	v_cvt_pk_bf16_f32 v124, v120, v121
	v_lshl_add_u64 v[120:121], s[50:51], 0, v[144:145]
	v_and_b32_e32 v144, 48, v163
	v_cndmask_b32_e32 v129, v168, v131, vcc
	v_cndmask_b32_e32 v131, v170, v125, vcc
	v_cndmask_b32_e32 v167, v171, v126, vcc
	v_cndmask_b32_e32 v127, v172, v127, vcc
	v_lshl_add_u64 v[120:121], v[120:121], 0, v[144:145]
	v_mul_f32_e32 v173, 0xbfb8aa3b, v149
	v_cvt_pk_bf16_f32 v125, v128, v129
	v_cvt_pk_bf16_f32 v126, v130, v131
	v_cvt_pk_bf16_f32 v127, v167, v127
	v_lshl_add_u64 v[128:129], v[120:121], 0, v[164:165]
	v_mul_f32_e32 v122, v122, v132
	v_mul_f32_e32 v174, 0xbfb8aa3b, v166
	v_exp_f32_e32 v173, v173
	global_store_dwordx4 v[128:129], v[124:127], off nt
	v_exp_f32_e32 v174, v174
	v_mul_f32_e32 v123, v123, v132
	v_mul_f32_e32 v126, 0xbfb8aa3b, v122
	v_exp_f32_e32 v126, v126
	v_add_f32_e32 v124, 1.0, v173
	v_rcp_f32_e32 v124, v124
	v_add_f32_e32 v125, 1.0, v174
	v_add_f32_e32 v126, 1.0, v126
	v_rcp_f32_e32 v125, v125
	v_rcp_f32_e32 v126, v126
	v_mul_f32_e32 v130, 0xbfb8aa3b, v123
	v_exp_f32_e32 v130, v130
	v_mul_f32_e32 v127, v149, v124
	v_cndmask_b32_e32 v124, v124, v127, vcc
	v_mul_f32_e32 v127, v166, v125
	v_mul_f32_e32 v122, v122, v126
	v_cndmask_b32_e32 v125, v125, v127, vcc
	v_cndmask_b32_e32 v122, v126, v122, vcc
	v_add_f32_e32 v126, 1.0, v130
	v_mul_f32_e32 v127, v116, v132
	v_rcp_f32_e32 v126, v126
	v_mul_f32_e32 v116, 0xbfb8aa3b, v127
	v_exp_f32_e32 v130, v116
	v_mul_f32_e32 v118, v118, v132
	v_mul_f32_e32 v116, v123, v126
	v_cndmask_b32_e32 v123, v126, v116, vcc
	v_cvt_pk_bf16_f32 v116, v124, v125
	v_add_f32_e32 v124, 1.0, v130
	v_rcp_f32_e32 v124, v124
	v_mul_f32_e32 v125, v117, v132
	v_mul_f32_e32 v117, 0xbfb8aa3b, v125
	v_exp_f32_e32 v126, v117
	v_cvt_pk_bf16_f32 v117, v122, v123
	v_mul_f32_e32 v122, v127, v124
	v_cndmask_b32_e32 v122, v124, v122, vcc
	v_mul_f32_e32 v124, 0xbfb8aa3b, v118
	v_mul_f32_e32 v119, v119, v132
	v_add_f32_e32 v123, 1.0, v126
	v_exp_f32_e32 v124, v124
	v_mul_f32_e32 v126, 0xbfb8aa3b, v119
	v_exp_f32_e32 v126, v126
	v_rcp_f32_e32 v123, v123
	v_add_f32_e32 v124, 1.0, v124
	v_rcp_f32_e32 v124, v124
	v_add_f32_e32 v126, 1.0, v126
	v_rcp_f32_e32 v126, v126
	v_mul_f32_e32 v125, v125, v123
	v_mul_f32_e32 v118, v118, v124
	v_cndmask_b32_e32 v124, v124, v118, vcc
	v_mul_f32_e32 v118, v119, v126
	v_cndmask_b32_e32 v123, v123, v125, vcc
	v_cndmask_b32_e32 v119, v126, v118, vcc
	v_cvt_pk_bf16_f32 v118, v122, v123
	v_cvt_pk_bf16_f32 v119, v124, v119
	global_store_dwordx4 v[128:129], v[116:119], off offset:256 nt
	v_mul_f32_e32 v122, v113, v133
	v_mul_f32_e32 v114, v114, v133
	v_mul_f32_e32 v118, v112, v133
	v_mul_f32_e32 v112, 0xbfb8aa3b, v118
	v_exp_f32_e32 v119, v112
	v_mul_f32_e32 v112, 0xbfb8aa3b, v122
	v_or_b32_e32 v116, 16, v148
; DI u32x2 pk4(f32x4 v) { u32x2 r; r.x = pk2(v[0], v[1]); r.y = pk2(v[2], v[3]); return r; }
; DI float sigmoidf_(float v) { return __builtin_amdgcn_rcpf(1.f + fast_exp2(-1.4426950408889634f * v)); }
; template <int REG>
; DI void epi_inproj(const Params& p, f32x4 (&acc)[2][2][4][2], int pm, int pn, LAS unsigned char* shm) {
;     ...
;       for (int m = 0; m < 4; ++m) { asm volatile("" ::: "memory");
;         const int r = 128 * ai + 64 * wr + 16 * m + fr;
;         const float rs = rsr[ai][m];
; #pragma unroll
;         for (int bj = 0; bj < 2; ++bj) {
;           u32x2 h[2];
; #pragma unroll
;           for (int n = 0; n < 2; ++n) {
;             f32x4 v = acc[ai][bj][m][n] * rs, o;
; #pragma unroll
;             for (int j = 0; j < 4; ++j) { const float sg = sigmoidf_(v[j]); o[j] = silu ? v[j] * sg : sg; }
;             h[n] = pk4(o);
;           }
;           *(u32x4*)(dstb + (long)(T0 + r) * 1024 + cb + 128 * bj + 32 * wc + 8 * fq) = (u32x4){h[0].x, h[0].y, h[1].x, h[1].y};
;         }
	v_exp_f32_e32 v123, v112
	v_ashrrev_i32_e32 v117, 31, v116
	v_lshlrev_b64 v[116:117], 11, v[116:117]
	v_lshl_add_u64 v[112:113], v[120:121], 0, v[116:117]
	v_add_f32_e32 v116, 1.0, v119
	v_mul_f32_e32 v119, 0xbfb8aa3b, v114
	v_rcp_f32_e32 v116, v116
	v_add_f32_e32 v117, 1.0, v123
	v_exp_f32_e32 v119, v119
	v_rcp_f32_e32 v117, v117
	v_mul_f32_e32 v118, v118, v116
	v_mul_f32_e32 v115, v115, v133
	v_add_f32_e32 v119, 1.0, v119
	v_cndmask_b32_e32 v116, v116, v118, vcc
	v_mul_f32_e32 v118, v122, v117
	v_rcp_f32_e32 v119, v119
	v_mul_f32_e32 v122, 0xbfb8aa3b, v115
	v_exp_f32_e32 v122, v122
	v_cndmask_b32_e32 v117, v117, v118, vcc
	v_mul_f32_e32 v114, v114, v119
	v_cndmask_b32_e32 v114, v119, v114, vcc
	v_add_f32_e32 v118, 1.0, v122
	v_mul_f32_e32 v119, v108, v133
	v_rcp_f32_e32 v118, v118
	v_mul_f32_e32 v108, 0xbfb8aa3b, v119
	v_exp_f32_e32 v122, v108
	v_mul_f32_e32 v110, v110, v133
	v_mul_f32_e32 v108, v115, v118
	v_cndmask_b32_e32 v115, v118, v108, vcc
	v_cvt_pk_bf16_f32 v108, v116, v117
	v_add_f32_e32 v116, 1.0, v122
	v_rcp_f32_e32 v116, v116
	v_mul_f32_e32 v117, v109, v133
	v_mul_f32_e32 v109, 0xbfb8aa3b, v117
	v_exp_f32_e32 v118, v109
	v_cvt_pk_bf16_f32 v109, v114, v115
	v_mul_f32_e32 v114, v119, v116
	v_cndmask_b32_e32 v114, v116, v114, vcc
	v_mul_f32_e32 v116, 0xbfb8aa3b, v110
	v_mul_f32_e32 v111, v111, v133
	v_add_f32_e32 v115, 1.0, v118
	v_exp_f32_e32 v116, v116
	v_mul_f32_e32 v118, 0xbfb8aa3b, v111
	v_exp_f32_e32 v118, v118
	v_rcp_f32_e32 v115, v115
	v_add_f32_e32 v116, 1.0, v116
	v_rcp_f32_e32 v116, v116
	v_add_f32_e32 v118, 1.0, v118
	v_rcp_f32_e32 v118, v118
	v_mul_f32_e32 v117, v117, v115
	v_mul_f32_e32 v110, v110, v116
	v_cndmask_b32_e32 v115, v115, v117, vcc
	v_cndmask_b32_e32 v116, v116, v110, vcc
	v_mul_f32_e32 v110, v111, v118
	v_mul_f32_e32 v104, v104, v133
	v_cndmask_b32_e32 v111, v118, v110, vcc
	v_cvt_pk_bf16_f32 v110, v114, v115
	v_mul_f32_e32 v114, 0xbfb8aa3b, v104
	v_exp_f32_e32 v114, v114
	v_cvt_pk_bf16_f32 v111, v116, v111
	v_mul_f32_e32 v105, v105, v133
	global_store_dwordx4 v[112:113], v[108:111], off nt
	v_mul_f32_e32 v106, v106, v133
	v_mul_f32_e32 v115, 0xbfb8aa3b, v105
	v_add_f32_e32 v108, 1.0, v114
	v_rcp_f32_e32 v108, v108
	v_mul_f32_e32 v110, 0xbfb8aa3b, v106
	v_exp_f32_e32 v115, v115
	v_exp_f32_e32 v110, v110
	v_mul_f32_e32 v104, v104, v108
	v_cndmask_b32_e32 v104, v108, v104, vcc
	v_add_f32_e32 v109, 1.0, v115
	v_add_f32_e32 v108, 1.0, v110
	v_mul_f32_e32 v107, v107, v133
	v_rcp_f32_e32 v109, v109
	v_rcp_f32_e32 v108, v108
	v_mul_f32_e32 v110, 0xbfb8aa3b, v107
	v_exp_f32_e32 v110, v110
	v_mul_f32_e32 v105, v105, v109
	v_mul_f32_e32 v106, v106, v108
	v_cndmask_b32_e32 v105, v109, v105, vcc
	v_cndmask_b32_e32 v106, v108, v106, vcc
	v_add_f32_e32 v108, 1.0, v110
	v_mul_f32_e32 v109, v100, v133
	v_rcp_f32_e32 v108, v108
	v_mul_f32_e32 v100, 0xbfb8aa3b, v109
	v_exp_f32_e32 v110, v100
	v_mul_f32_e32 v102, v102, v133
	v_mul_f32_e32 v100, v107, v108
	v_cndmask_b32_e32 v107, v108, v100, vcc
	v_cvt_pk_bf16_f32 v100, v104, v105
	v_add_f32_e32 v104, 1.0, v110
	v_mul_f32_e32 v105, v101, v133
	v_rcp_f32_e32 v104, v104
	v_mul_f32_e32 v101, 0xbfb8aa3b, v105
	v_exp_f32_e32 v108, v101
	v_cvt_pk_bf16_f32 v101, v106, v107
	v_mul_f32_e32 v106, v109, v104
	v_mul_f32_e32 v107, 0xbfb8aa3b, v102
	v_mul_f32_e32 v103, v103, v133
	v_cndmask_b32_e32 v104, v104, v106, vcc
	v_add_f32_e32 v106, 1.0, v108
	v_exp_f32_e32 v107, v107
	v_mul_f32_e32 v108, 0xbfb8aa3b, v103
	v_exp_f32_e32 v108, v108
	v_rcp_f32_e32 v106, v106
	v_add_f32_e32 v107, 1.0, v107
	v_rcp_f32_e32 v107, v107
	v_add_f32_e32 v108, 1.0, v108
	v_rcp_f32_e32 v108, v108
	v_mul_f32_e32 v105, v105, v106
	v_mul_f32_e32 v102, v102, v107
	v_cndmask_b32_e32 v105, v106, v105, vcc
	v_cndmask_b32_e32 v106, v107, v102, vcc
	v_mul_f32_e32 v102, v103, v108
	v_cndmask_b32_e32 v103, v108, v102, vcc
	v_cvt_pk_bf16_f32 v102, v104, v105
	v_cvt_pk_bf16_f32 v103, v106, v103
	global_store_dwordx4 v[112:113], v[100:103], off offset:256 nt
	v_mul_f32_e32 v104, v97, v134
	v_mul_f32_e32 v98, v98, v134
	v_mul_f32_e32 v102, v96, v134
	v_mul_f32_e32 v96, 0xbfb8aa3b, v102
	v_exp_f32_e32 v103, v96
	v_mul_f32_e32 v96, 0xbfb8aa3b, v104
	v_or_b32_e32 v100, 32, v148
	v_exp_f32_e32 v105, v96
	v_ashrrev_i32_e32 v101, 31, v100
	v_lshlrev_b64 v[100:101], 11, v[100:101]
	v_lshl_add_u64 v[96:97], v[120:121], 0, v[100:101]
	v_add_f32_e32 v100, 1.0, v103
	v_mul_f32_e32 v103, 0xbfb8aa3b, v98
	v_rcp_f32_e32 v100, v100
	v_add_f32_e32 v101, 1.0, v105
	v_exp_f32_e32 v103, v103
	v_rcp_f32_e32 v101, v101
	v_mul_f32_e32 v102, v102, v100
	v_mul_f32_e32 v99, v99, v134
	v_add_f32_e32 v103, 1.0, v103
	v_cndmask_b32_e32 v100, v100, v102, vcc
	v_mul_f32_e32 v102, v104, v101
	v_rcp_f32_e32 v103, v103
	v_mul_f32_e32 v104, 0xbfb8aa3b, v99
	v_exp_f32_e32 v104, v104
	v_cndmask_b32_e32 v101, v101, v102, vcc
	v_mul_f32_e32 v98, v98, v103
	v_cndmask_b32_e32 v98, v103, v98, vcc
	v_add_f32_e32 v102, 1.0, v104
	v_mul_f32_e32 v103, v92, v134
	v_rcp_f32_e32 v102, v102
	v_mul_f32_e32 v92, 0xbfb8aa3b, v103
	v_exp_f32_e32 v104, v92
	v_mul_f32_e32 v94, v94, v134
	v_mul_f32_e32 v92, v99, v102
	v_cndmask_b32_e32 v99, v102, v92, vcc
	v_cvt_pk_bf16_f32 v92, v100, v101
	v_add_f32_e32 v100, 1.0, v104
	v_rcp_f32_e32 v100, v100
	v_mul_f32_e32 v101, v93, v134
	v_mul_f32_e32 v93, 0xbfb8aa3b, v101
	v_exp_f32_e32 v102, v93
	v_cvt_pk_bf16_f32 v93, v98, v99
	v_mul_f32_e32 v98, v103, v100
	v_cndmask_b32_e32 v98, v100, v98, vcc
	v_mul_f32_e32 v100, 0xbfb8aa3b, v94
	v_mul_f32_e32 v95, v95, v134
	v_add_f32_e32 v99, 1.0, v102
	v_exp_f32_e32 v100, v100
	v_mul_f32_e32 v102, 0xbfb8aa3b, v95
	v_exp_f32_e32 v102, v102
	v_rcp_f32_e32 v99, v99
	v_add_f32_e32 v100, 1.0, v100
; DI u32x2 pk4(f32x4 v) { u32x2 r; r.x = pk2(v[0], v[1]); r.y = pk2(v[2], v[3]); return r; }
; DI float sigmoidf_(float v) { return __builtin_amdgcn_rcpf(1.f + fast_exp2(-1.4426950408889634f * v)); }
; template <int REG>
; DI void epi_inproj(const Params& p, f32x4 (&acc)[2][2][4][2], int pm, int pn, LAS unsigned char* shm) {
;     ...
;       for (int m = 0; m < 4; ++m) { asm volatile("" ::: "memory");
;         const int r = 128 * ai + 64 * wr + 16 * m + fr;
;         const float rs = rsr[ai][m];
; #pragma unroll
;         for (int bj = 0; bj < 2; ++bj) {
;           u32x2 h[2];
; #pragma unroll
;           for (int n = 0; n < 2; ++n) {
;             f32x4 v = acc[ai][bj][m][n] * rs, o;
; #pragma unroll
;             for (int j = 0; j < 4; ++j) { const float sg = sigmoidf_(v[j]); o[j] = silu ? v[j] * sg : sg; }
;             h[n] = pk4(o);
;           }
;           *(u32x4*)(dstb + (long)(T0 + r) * 1024 + cb + 128 * bj + 32 * wc + 8 * fq) = (u32x4){h[0].x, h[0].y, h[1].x, h[1].y};
;         }
	v_rcp_f32_e32 v100, v100
	v_add_f32_e32 v102, 1.0, v102
	v_rcp_f32_e32 v102, v102
	v_mul_f32_e32 v101, v101, v99
	v_mul_f32_e32 v94, v94, v100
	v_cndmask_b32_e32 v99, v99, v101, vcc
	v_cndmask_b32_e32 v100, v100, v94, vcc
	v_mul_f32_e32 v94, v95, v102
	v_mul_f32_e32 v88, v88, v134
	v_cndmask_b32_e32 v95, v102, v94, vcc
	v_cvt_pk_bf16_f32 v94, v98, v99
	v_mul_f32_e32 v98, 0xbfb8aa3b, v88
	v_exp_f32_e32 v98, v98
	v_cvt_pk_bf16_f32 v95, v100, v95
	v_mul_f32_e32 v89, v89, v134
	global_store_dwordx4 v[96:97], v[92:95], off nt
	v_mul_f32_e32 v90, v90, v134
	v_mul_f32_e32 v99, 0xbfb8aa3b, v89
	v_add_f32_e32 v92, 1.0, v98
	v_rcp_f32_e32 v92, v92
	v_mul_f32_e32 v94, 0xbfb8aa3b, v90
	v_exp_f32_e32 v99, v99
	v_exp_f32_e32 v94, v94
	v_mul_f32_e32 v88, v88, v92
	v_cndmask_b32_e32 v88, v92, v88, vcc
	v_add_f32_e32 v93, 1.0, v99
	v_add_f32_e32 v92, 1.0, v94
	v_mul_f32_e32 v91, v91, v134
	v_rcp_f32_e32 v93, v93
	v_rcp_f32_e32 v92, v92
	v_mul_f32_e32 v94, 0xbfb8aa3b, v91
	v_exp_f32_e32 v94, v94
	v_mul_f32_e32 v89, v89, v93
	v_mul_f32_e32 v90, v90, v92
	v_cndmask_b32_e32 v89, v93, v89, vcc
	v_cndmask_b32_e32 v90, v92, v90, vcc
	v_add_f32_e32 v92, 1.0, v94
	v_mul_f32_e32 v93, v84, v134
	v_rcp_f32_e32 v92, v92
	v_mul_f32_e32 v84, 0xbfb8aa3b, v93
	v_exp_f32_e32 v94, v84
	v_mul_f32_e32 v86, v86, v134
	v_mul_f32_e32 v84, v91, v92
	v_cndmask_b32_e32 v91, v92, v84, vcc
	v_cvt_pk_bf16_f32 v84, v88, v89
	v_add_f32_e32 v88, 1.0, v94
	v_mul_f32_e32 v89, v85, v134
	v_rcp_f32_e32 v88, v88
	v_mul_f32_e32 v85, 0xbfb8aa3b, v89
	v_exp_f32_e32 v92, v85
	v_cvt_pk_bf16_f32 v85, v90, v91
	v_mul_f32_e32 v90, v93, v88
	v_mul_f32_e32 v91, 0xbfb8aa3b, v86
	v_mul_f32_e32 v87, v87, v134
	v_cndmask_b32_e32 v88, v88, v90, vcc
	v_add_f32_e32 v90, 1.0, v92
	v_exp_f32_e32 v91, v91
	v_mul_f32_e32 v92, 0xbfb8aa3b, v87
	v_exp_f32_e32 v92, v92
	v_rcp_f32_e32 v90, v90
	v_add_f32_e32 v91, 1.0, v91
	v_rcp_f32_e32 v91, v91
	v_add_f32_e32 v92, 1.0, v92
	v_rcp_f32_e32 v92, v92
	v_mul_f32_e32 v89, v89, v90
	v_mul_f32_e32 v86, v86, v91
	v_cndmask_b32_e32 v89, v90, v89, vcc
	v_cndmask_b32_e32 v90, v91, v86, vcc
	v_mul_f32_e32 v86, v87, v92
	v_cndmask_b32_e32 v87, v92, v86, vcc
	v_cvt_pk_bf16_f32 v86, v88, v89
	v_cvt_pk_bf16_f32 v87, v90, v87
	global_store_dwordx4 v[96:97], v[84:87], off offset:256 nt
	v_mul_f32_e32 v88, v81, v135
	v_mul_f32_e32 v82, v82, v135
	v_mul_f32_e32 v86, v80, v135
	v_mul_f32_e32 v80, 0xbfb8aa3b, v86
	v_exp_f32_e32 v87, v80
	v_mul_f32_e32 v80, 0xbfb8aa3b, v88
	v_or_b32_e32 v84, 48, v148
	v_exp_f32_e32 v89, v80
	v_ashrrev_i32_e32 v85, 31, v84
	v_lshlrev_b64 v[84:85], 11, v[84:85]
	v_lshl_add_u64 v[80:81], v[120:121], 0, v[84:85]
	v_add_f32_e32 v84, 1.0, v87
	v_mul_f32_e32 v87, 0xbfb8aa3b, v82
	v_rcp_f32_e32 v84, v84
	v_add_f32_e32 v85, 1.0, v89
	v_exp_f32_e32 v87, v87
	v_rcp_f32_e32 v85, v85
	v_mul_f32_e32 v86, v86, v84
	v_mul_f32_e32 v83, v83, v135
	v_add_f32_e32 v87, 1.0, v87
	v_cndmask_b32_e32 v84, v84, v86, vcc
	v_mul_f32_e32 v86, v88, v85
	v_rcp_f32_e32 v87, v87
	v_mul_f32_e32 v88, 0xbfb8aa3b, v83
	v_exp_f32_e32 v88, v88
	v_cndmask_b32_e32 v85, v85, v86, vcc
	v_mul_f32_e32 v82, v82, v87
	v_cndmask_b32_e32 v82, v87, v82, vcc
	v_add_f32_e32 v86, 1.0, v88
	v_mul_f32_e32 v87, v76, v135
	v_rcp_f32_e32 v86, v86
	v_mul_f32_e32 v76, 0xbfb8aa3b, v87
	v_exp_f32_e32 v88, v76
	v_mul_f32_e32 v78, v78, v135
	v_mul_f32_e32 v76, v83, v86
	v_cndmask_b32_e32 v83, v86, v76, vcc
	v_cvt_pk_bf16_f32 v76, v84, v85
	v_add_f32_e32 v84, 1.0, v88
	v_rcp_f32_e32 v84, v84
	v_mul_f32_e32 v85, v77, v135
	v_mul_f32_e32 v77, 0xbfb8aa3b, v85
	v_exp_f32_e32 v86, v77
	v_cvt_pk_bf16_f32 v77, v82, v83
	v_mul_f32_e32 v82, v87, v84
	v_cndmask_b32_e32 v82, v84, v82, vcc
	v_mul_f32_e32 v84, 0xbfb8aa3b, v78
	v_mul_f32_e32 v79, v79, v135
	v_add_f32_e32 v83, 1.0, v86
	v_exp_f32_e32 v84, v84
	v_mul_f32_e32 v86, 0xbfb8aa3b, v79
	v_exp_f32_e32 v86, v86
	v_rcp_f32_e32 v83, v83
	v_add_f32_e32 v84, 1.0, v84
	v_rcp_f32_e32 v84, v84
	v_add_f32_e32 v86, 1.0, v86
	v_rcp_f32_e32 v86, v86
	v_mul_f32_e32 v85, v85, v83
	v_mul_f32_e32 v78, v78, v84
	v_cndmask_b32_e32 v83, v83, v85, vcc
	v_cndmask_b32_e32 v84, v84, v78, vcc
	v_mul_f32_e32 v78, v79, v86
	v_mul_f32_e32 v68, v68, v135
	v_cndmask_b32_e32 v79, v86, v78, vcc
	v_cvt_pk_bf16_f32 v78, v82, v83
	v_mul_f32_e32 v82, 0xbfb8aa3b, v68
	v_exp_f32_e32 v82, v82
	v_cvt_pk_bf16_f32 v79, v84, v79
	v_mul_f32_e32 v69, v69, v135
	global_store_dwordx4 v[80:81], v[76:79], off nt
	v_mul_f32_e32 v70, v70, v135
	v_mul_f32_e32 v83, 0xbfb8aa3b, v69
	v_add_f32_e32 v76, 1.0, v82
	v_rcp_f32_e32 v76, v76
	v_mul_f32_e32 v78, 0xbfb8aa3b, v70
	v_exp_f32_e32 v83, v83
	v_exp_f32_e32 v78, v78
	v_mul_f32_e32 v68, v68, v76
	v_cndmask_b32_e32 v68, v76, v68, vcc
	v_add_f32_e32 v77, 1.0, v83
	v_add_f32_e32 v76, 1.0, v78
	v_mul_f32_e32 v71, v71, v135
	v_rcp_f32_e32 v77, v77
	v_rcp_f32_e32 v76, v76
	v_mul_f32_e32 v78, 0xbfb8aa3b, v71
	v_exp_f32_e32 v78, v78
	v_mul_f32_e32 v69, v69, v77
	v_mul_f32_e32 v70, v70, v76
	v_cndmask_b32_e32 v69, v77, v69, vcc
	v_cndmask_b32_e32 v70, v76, v70, vcc
	v_add_f32_e32 v76, 1.0, v78
	v_mul_f32_e32 v77, v64, v135
	v_rcp_f32_e32 v76, v76
	v_mul_f32_e32 v64, 0xbfb8aa3b, v77
	v_exp_f32_e32 v78, v64
	v_mul_f32_e32 v66, v66, v135
	v_mul_f32_e32 v64, v71, v76
	v_cndmask_b32_e32 v71, v76, v64, vcc
	v_cvt_pk_bf16_f32 v64, v68, v69
	v_add_f32_e32 v68, 1.0, v78
	v_mul_f32_e32 v69, v65, v135
	v_rcp_f32_e32 v68, v68
	v_mul_f32_e32 v65, 0xbfb8aa3b, v69
	v_exp_f32_e32 v76, v65
	v_cvt_pk_bf16_f32 v65, v70, v71
	v_mul_f32_e32 v70, v77, v68
	v_mul_f32_e32 v71, 0xbfb8aa3b, v66
	v_mul_f32_e32 v67, v67, v135
	v_cndmask_b32_e32 v68, v68, v70, vcc
	v_add_f32_e32 v70, 1.0, v76
	v_exp_f32_e32 v71, v71
; DI u32x2 pk4(f32x4 v) { u32x2 r; r.x = pk2(v[0], v[1]); r.y = pk2(v[2], v[3]); return r; }
; DI float sigmoidf_(float v) { return __builtin_amdgcn_rcpf(1.f + fast_exp2(-1.4426950408889634f * v)); }
; template <int REG>
; DI void epi_inproj(const Params& p, f32x4 (&acc)[2][2][4][2], int pm, int pn, LAS unsigned char* shm) {
;     ...
;       for (int m = 0; m < 4; ++m) { asm volatile("" ::: "memory");
;         const int r = 128 * ai + 64 * wr + 16 * m + fr;
;         const float rs = rsr[ai][m];
; #pragma unroll
;         for (int bj = 0; bj < 2; ++bj) {
;           u32x2 h[2];
; #pragma unroll
;           for (int n = 0; n < 2; ++n) {
;             f32x4 v = acc[ai][bj][m][n] * rs, o;
; #pragma unroll
;             for (int j = 0; j < 4; ++j) { const float sg = sigmoidf_(v[j]); o[j] = silu ? v[j] * sg : sg; }
;             h[n] = pk4(o);
;           }
;           *(u32x4*)(dstb + (long)(T0 + r) * 1024 + cb + 128 * bj + 32 * wc + 8 * fq) = (u32x4){h[0].x, h[0].y, h[1].x, h[1].y};
;         }
	v_mul_f32_e32 v76, 0xbfb8aa3b, v67
	v_exp_f32_e32 v76, v76
	v_rcp_f32_e32 v70, v70
	v_add_f32_e32 v71, 1.0, v71
	v_rcp_f32_e32 v71, v71
	v_add_f32_e32 v76, 1.0, v76
	v_rcp_f32_e32 v76, v76
	v_mul_f32_e32 v69, v69, v70
	v_mul_f32_e32 v66, v66, v71
	v_cndmask_b32_e32 v69, v70, v69, vcc
	v_cndmask_b32_e32 v70, v71, v66, vcc
	v_mul_f32_e32 v66, v67, v76
	v_cndmask_b32_e32 v67, v76, v66, vcc
	v_cvt_pk_bf16_f32 v66, v68, v69
	v_cvt_pk_bf16_f32 v67, v70, v67
	global_store_dwordx4 v[80:81], v[64:67], off offset:256 nt
	v_mul_f32_e32 v68, v61, v72
	v_mul_f32_e32 v62, v62, v72
	v_mul_f32_e32 v66, v60, v72
	v_mul_f32_e32 v60, 0xbfb8aa3b, v66
	v_exp_f32_e32 v67, v60
	v_mul_f32_e32 v60, 0xbfb8aa3b, v68
	v_add_u32_e32 v64, 0x80, v148
	v_exp_f32_e32 v69, v60
	v_ashrrev_i32_e32 v65, 31, v64
	v_lshlrev_b64 v[64:65], 11, v[64:65]
	v_lshl_add_u64 v[60:61], v[120:121], 0, v[64:65]
	v_add_f32_e32 v64, 1.0, v67
	v_mul_f32_e32 v67, 0xbfb8aa3b, v62
	v_rcp_f32_e32 v64, v64
	v_add_f32_e32 v65, 1.0, v69
	v_exp_f32_e32 v67, v67
	v_rcp_f32_e32 v65, v65
	v_mul_f32_e32 v66, v66, v64
	v_mul_f32_e32 v63, v63, v72
	v_add_f32_e32 v67, 1.0, v67
	v_cndmask_b32_e32 v64, v64, v66, vcc
	v_mul_f32_e32 v66, v68, v65
	v_rcp_f32_e32 v67, v67
	v_mul_f32_e32 v68, 0xbfb8aa3b, v63
	v_exp_f32_e32 v68, v68
	v_cndmask_b32_e32 v65, v65, v66, vcc
	v_mul_f32_e32 v62, v62, v67
	v_cndmask_b32_e32 v62, v67, v62, vcc
	v_add_f32_e32 v66, 1.0, v68
	v_mul_f32_e32 v67, v56, v72
	v_rcp_f32_e32 v66, v66
	v_mul_f32_e32 v56, 0xbfb8aa3b, v67
	v_exp_f32_e32 v68, v56
	v_mul_f32_e32 v58, v58, v72
	v_mul_f32_e32 v56, v63, v66
	v_cndmask_b32_e32 v63, v66, v56, vcc
	v_cvt_pk_bf16_f32 v56, v64, v65
	v_add_f32_e32 v64, 1.0, v68
	v_rcp_f32_e32 v64, v64
	v_mul_f32_e32 v65, v57, v72
	v_mul_f32_e32 v57, 0xbfb8aa3b, v65
	v_exp_f32_e32 v66, v57
	v_cvt_pk_bf16_f32 v57, v62, v63
	v_mul_f32_e32 v62, v67, v64
	v_cndmask_b32_e32 v62, v64, v62, vcc
	v_mul_f32_e32 v64, 0xbfb8aa3b, v58
	v_mul_f32_e32 v59, v59, v72
	v_add_f32_e32 v63, 1.0, v66
	v_exp_f32_e32 v64, v64
	v_mul_f32_e32 v66, 0xbfb8aa3b, v59
	v_exp_f32_e32 v66, v66
	v_rcp_f32_e32 v63, v63
	v_add_f32_e32 v64, 1.0, v64
	v_rcp_f32_e32 v64, v64
	v_add_f32_e32 v66, 1.0, v66
	v_rcp_f32_e32 v66, v66
	v_mul_f32_e32 v65, v65, v63
	v_mul_f32_e32 v58, v58, v64
	v_cndmask_b32_e32 v63, v63, v65, vcc
	v_cndmask_b32_e32 v64, v64, v58, vcc
	v_mul_f32_e32 v58, v59, v66
	v_mul_f32_e32 v52, v52, v72
	v_cndmask_b32_e32 v59, v66, v58, vcc
	v_cvt_pk_bf16_f32 v58, v62, v63
	v_mul_f32_e32 v62, 0xbfb8aa3b, v52
	v_exp_f32_e32 v62, v62
	v_cvt_pk_bf16_f32 v59, v64, v59
	v_mul_f32_e32 v53, v53, v72
	global_store_dwordx4 v[60:61], v[56:59], off nt
	v_mul_f32_e32 v54, v54, v72
	v_mul_f32_e32 v63, 0xbfb8aa3b, v53
	v_add_f32_e32 v56, 1.0, v62
	v_rcp_f32_e32 v56, v56
	v_mul_f32_e32 v58, 0xbfb8aa3b, v54
	v_exp_f32_e32 v63, v63
	v_exp_f32_e32 v58, v58
	v_mul_f32_e32 v52, v52, v56
	v_cndmask_b32_e32 v52, v56, v52, vcc
	v_add_f32_e32 v57, 1.0, v63
	v_add_f32_e32 v56, 1.0, v58
	v_mul_f32_e32 v55, v55, v72
	v_rcp_f32_e32 v57, v57
	v_rcp_f32_e32 v56, v56
	v_mul_f32_e32 v58, 0xbfb8aa3b, v55
	v_exp_f32_e32 v58, v58
	v_mul_f32_e32 v53, v53, v57
	v_mul_f32_e32 v54, v54, v56
	v_cndmask_b32_e32 v53, v57, v53, vcc
	v_cndmask_b32_e32 v54, v56, v54, vcc
	v_add_f32_e32 v56, 1.0, v58
	v_mul_f32_e32 v57, v48, v72
	v_rcp_f32_e32 v56, v56
	v_mul_f32_e32 v48, 0xbfb8aa3b, v57
	v_exp_f32_e32 v58, v48
	v_mul_f32_e32 v50, v50, v72
	v_mul_f32_e32 v48, v55, v56
	v_cndmask_b32_e32 v55, v56, v48, vcc
	v_cvt_pk_bf16_f32 v48, v52, v53
	v_add_f32_e32 v52, 1.0, v58
	v_mul_f32_e32 v53, v49, v72
	v_rcp_f32_e32 v52, v52
	v_mul_f32_e32 v49, 0xbfb8aa3b, v53
	v_exp_f32_e32 v56, v49
	v_cvt_pk_bf16_f32 v49, v54, v55
	v_mul_f32_e32 v54, v57, v52
	v_mul_f32_e32 v55, 0xbfb8aa3b, v50
	v_mul_f32_e32 v51, v51, v72
	v_cndmask_b32_e32 v52, v52, v54, vcc
	v_add_f32_e32 v54, 1.0, v56
	v_exp_f32_e32 v55, v55
	v_mul_f32_e32 v56, 0xbfb8aa3b, v51
	v_exp_f32_e32 v56, v56
	v_rcp_f32_e32 v54, v54
	v_add_f32_e32 v55, 1.0, v55
	v_rcp_f32_e32 v55, v55
	v_add_f32_e32 v56, 1.0, v56
	v_rcp_f32_e32 v56, v56
	v_mul_f32_e32 v53, v53, v54
	v_mul_f32_e32 v50, v50, v55
	v_cndmask_b32_e32 v53, v54, v53, vcc
	v_cndmask_b32_e32 v54, v55, v50, vcc
	v_mul_f32_e32 v50, v51, v56
	v_cndmask_b32_e32 v51, v56, v50, vcc
	v_cvt_pk_bf16_f32 v50, v52, v53
	v_cvt_pk_bf16_f32 v51, v54, v51
	global_store_dwordx4 v[60:61], v[48:51], off offset:256 nt
	v_mul_f32_e32 v52, v45, v73
	v_mul_f32_e32 v46, v46, v73
	v_mul_f32_e32 v50, v44, v73
	v_mul_f32_e32 v44, 0xbfb8aa3b, v50
	v_exp_f32_e32 v51, v44
	v_mul_f32_e32 v44, 0xbfb8aa3b, v52
	v_add_u32_e32 v48, 0x90, v148
	v_exp_f32_e32 v53, v44
	v_ashrrev_i32_e32 v49, 31, v48
	v_lshlrev_b64 v[48:49], 11, v[48:49]
	v_lshl_add_u64 v[44:45], v[120:121], 0, v[48:49]
	v_add_f32_e32 v48, 1.0, v51
	v_mul_f32_e32 v51, 0xbfb8aa3b, v46
	v_rcp_f32_e32 v48, v48
	v_add_f32_e32 v49, 1.0, v53
	v_exp_f32_e32 v51, v51
	v_rcp_f32_e32 v49, v49
	v_mul_f32_e32 v50, v50, v48
	v_mul_f32_e32 v47, v47, v73
	v_add_f32_e32 v51, 1.0, v51
	v_cndmask_b32_e32 v48, v48, v50, vcc
	v_mul_f32_e32 v50, v52, v49
	v_rcp_f32_e32 v51, v51
	v_mul_f32_e32 v52, 0xbfb8aa3b, v47
	v_exp_f32_e32 v52, v52
	v_cndmask_b32_e32 v49, v49, v50, vcc
	v_mul_f32_e32 v46, v46, v51
	v_cndmask_b32_e32 v46, v51, v46, vcc
	v_add_f32_e32 v50, 1.0, v52
	v_mul_f32_e32 v51, v40, v73
	v_rcp_f32_e32 v50, v50
	v_mul_f32_e32 v40, 0xbfb8aa3b, v51
	v_exp_f32_e32 v52, v40
	v_mul_f32_e32 v42, v42, v73
	v_mul_f32_e32 v40, v47, v50
	v_cndmask_b32_e32 v47, v50, v40, vcc
	v_cvt_pk_bf16_f32 v40, v48, v49
	v_add_f32_e32 v48, 1.0, v52
	v_rcp_f32_e32 v48, v48
	v_mul_f32_e32 v49, v41, v73
	v_mul_f32_e32 v41, 0xbfb8aa3b, v49
; DI u32x2 pk4(f32x4 v) { u32x2 r; r.x = pk2(v[0], v[1]); r.y = pk2(v[2], v[3]); return r; }
; DI float sigmoidf_(float v) { return __builtin_amdgcn_rcpf(1.f + fast_exp2(-1.4426950408889634f * v)); }
; template <int REG>
; DI void epi_inproj(const Params& p, f32x4 (&acc)[2][2][4][2], int pm, int pn, LAS unsigned char* shm) {
;     ...
;       for (int m = 0; m < 4; ++m) { asm volatile("" ::: "memory");
;         const int r = 128 * ai + 64 * wr + 16 * m + fr;
;         const float rs = rsr[ai][m];
; #pragma unroll
;         for (int bj = 0; bj < 2; ++bj) {
;           u32x2 h[2];
; #pragma unroll
;           for (int n = 0; n < 2; ++n) {
;             f32x4 v = acc[ai][bj][m][n] * rs, o;
; #pragma unroll
;             for (int j = 0; j < 4; ++j) { const float sg = sigmoidf_(v[j]); o[j] = silu ? v[j] * sg : sg; }
;             h[n] = pk4(o);
;           }
;           *(u32x4*)(dstb + (long)(T0 + r) * 1024 + cb + 128 * bj + 32 * wc + 8 * fq) = (u32x4){h[0].x, h[0].y, h[1].x, h[1].y};
;         }
	v_exp_f32_e32 v50, v41
	v_cvt_pk_bf16_f32 v41, v46, v47
	v_mul_f32_e32 v46, v51, v48
	v_cndmask_b32_e32 v46, v48, v46, vcc
	v_mul_f32_e32 v48, 0xbfb8aa3b, v42
	v_mul_f32_e32 v43, v43, v73
	v_add_f32_e32 v47, 1.0, v50
	v_exp_f32_e32 v48, v48
	v_mul_f32_e32 v50, 0xbfb8aa3b, v43
	v_exp_f32_e32 v50, v50
	v_rcp_f32_e32 v47, v47
	v_add_f32_e32 v48, 1.0, v48
	v_rcp_f32_e32 v48, v48
	v_add_f32_e32 v50, 1.0, v50
	v_rcp_f32_e32 v50, v50
	v_mul_f32_e32 v49, v49, v47
	v_mul_f32_e32 v42, v42, v48
	v_cndmask_b32_e32 v47, v47, v49, vcc
	v_cndmask_b32_e32 v48, v48, v42, vcc
	v_mul_f32_e32 v42, v43, v50
	v_mul_f32_e32 v36, v36, v73
	v_cndmask_b32_e32 v43, v50, v42, vcc
	v_cvt_pk_bf16_f32 v42, v46, v47
	v_mul_f32_e32 v46, 0xbfb8aa3b, v36
	v_exp_f32_e32 v46, v46
	v_cvt_pk_bf16_f32 v43, v48, v43
	v_mul_f32_e32 v37, v37, v73
	global_store_dwordx4 v[44:45], v[40:43], off nt
	v_mul_f32_e32 v38, v38, v73
	v_mul_f32_e32 v47, 0xbfb8aa3b, v37
	v_add_f32_e32 v40, 1.0, v46
	v_rcp_f32_e32 v40, v40
	v_mul_f32_e32 v42, 0xbfb8aa3b, v38
	v_exp_f32_e32 v47, v47
	v_exp_f32_e32 v42, v42
	v_mul_f32_e32 v36, v36, v40
	v_cndmask_b32_e32 v36, v40, v36, vcc
	v_add_f32_e32 v41, 1.0, v47
	v_add_f32_e32 v40, 1.0, v42
	v_mul_f32_e32 v39, v39, v73
	v_rcp_f32_e32 v41, v41
	v_rcp_f32_e32 v40, v40
	v_mul_f32_e32 v42, 0xbfb8aa3b, v39
	v_exp_f32_e32 v42, v42
	v_mul_f32_e32 v37, v37, v41
	v_mul_f32_e32 v38, v38, v40
	v_cndmask_b32_e32 v37, v41, v37, vcc
	v_cndmask_b32_e32 v38, v40, v38, vcc
	v_add_f32_e32 v40, 1.0, v42
	v_mul_f32_e32 v41, v32, v73
	v_rcp_f32_e32 v40, v40
	v_mul_f32_e32 v32, 0xbfb8aa3b, v41
	v_exp_f32_e32 v42, v32
	v_mul_f32_e32 v34, v34, v73
	v_mul_f32_e32 v32, v39, v40
	v_cndmask_b32_e32 v39, v40, v32, vcc
	v_cvt_pk_bf16_f32 v32, v36, v37
	v_add_f32_e32 v36, 1.0, v42
	v_mul_f32_e32 v37, v33, v73
	v_rcp_f32_e32 v36, v36
	v_mul_f32_e32 v33, 0xbfb8aa3b, v37
	v_exp_f32_e32 v40, v33
	v_cvt_pk_bf16_f32 v33, v38, v39
	v_mul_f32_e32 v38, v41, v36
	v_mul_f32_e32 v39, 0xbfb8aa3b, v34
	v_mul_f32_e32 v35, v35, v73
	v_cndmask_b32_e32 v36, v36, v38, vcc
	v_add_f32_e32 v38, 1.0, v40
	v_exp_f32_e32 v39, v39
	v_mul_f32_e32 v40, 0xbfb8aa3b, v35
	v_exp_f32_e32 v40, v40
	v_rcp_f32_e32 v38, v38
	v_add_f32_e32 v39, 1.0, v39
	v_rcp_f32_e32 v39, v39
	v_add_f32_e32 v40, 1.0, v40
	v_rcp_f32_e32 v40, v40
	v_mul_f32_e32 v37, v37, v38
	v_mul_f32_e32 v34, v34, v39
	v_cndmask_b32_e32 v37, v38, v37, vcc
	v_cndmask_b32_e32 v38, v39, v34, vcc
	v_mul_f32_e32 v34, v35, v40
	v_cndmask_b32_e32 v35, v40, v34, vcc
	v_cvt_pk_bf16_f32 v34, v36, v37
	v_cvt_pk_bf16_f32 v35, v38, v35
	global_store_dwordx4 v[44:45], v[32:35], off offset:256 nt
	v_mul_f32_e32 v36, v29, v74
	v_mul_f32_e32 v30, v30, v74
	v_mul_f32_e32 v34, v28, v74
	v_mul_f32_e32 v28, 0xbfb8aa3b, v34
	v_exp_f32_e32 v35, v28
	v_mul_f32_e32 v28, 0xbfb8aa3b, v36
	v_add_u32_e32 v32, 0xa0, v148
	v_exp_f32_e32 v37, v28
	v_ashrrev_i32_e32 v33, 31, v32
	v_lshlrev_b64 v[32:33], 11, v[32:33]
	v_lshl_add_u64 v[28:29], v[120:121], 0, v[32:33]
	v_add_f32_e32 v32, 1.0, v35
	v_mul_f32_e32 v35, 0xbfb8aa3b, v30
	v_rcp_f32_e32 v32, v32
	v_add_f32_e32 v33, 1.0, v37
	v_exp_f32_e32 v35, v35
	v_rcp_f32_e32 v33, v33
	v_mul_f32_e32 v34, v34, v32
	v_mul_f32_e32 v31, v31, v74
	v_add_f32_e32 v35, 1.0, v35
	v_cndmask_b32_e32 v32, v32, v34, vcc
	v_mul_f32_e32 v34, v36, v33
	v_rcp_f32_e32 v35, v35
	v_mul_f32_e32 v36, 0xbfb8aa3b, v31
	v_exp_f32_e32 v36, v36
	v_cndmask_b32_e32 v33, v33, v34, vcc
	v_mul_f32_e32 v30, v30, v35
	v_cndmask_b32_e32 v30, v35, v30, vcc
	v_add_f32_e32 v34, 1.0, v36
	v_mul_f32_e32 v35, v24, v74
	v_rcp_f32_e32 v34, v34
	v_mul_f32_e32 v24, 0xbfb8aa3b, v35
	v_exp_f32_e32 v36, v24
	v_mul_f32_e32 v26, v26, v74
	v_mul_f32_e32 v24, v31, v34
	v_cndmask_b32_e32 v31, v34, v24, vcc
	v_cvt_pk_bf16_f32 v24, v32, v33
	v_add_f32_e32 v32, 1.0, v36
	v_rcp_f32_e32 v32, v32
	v_mul_f32_e32 v33, v25, v74
	v_mul_f32_e32 v25, 0xbfb8aa3b, v33
	v_exp_f32_e32 v34, v25
	v_cvt_pk_bf16_f32 v25, v30, v31
	v_mul_f32_e32 v30, v35, v32
	v_cndmask_b32_e32 v30, v32, v30, vcc
	v_mul_f32_e32 v32, 0xbfb8aa3b, v26
	v_mul_f32_e32 v27, v27, v74
	v_add_f32_e32 v31, 1.0, v34
	v_exp_f32_e32 v32, v32
	v_mul_f32_e32 v34, 0xbfb8aa3b, v27
	v_exp_f32_e32 v34, v34
	v_rcp_f32_e32 v31, v31
	v_add_f32_e32 v32, 1.0, v32
	v_rcp_f32_e32 v32, v32
	v_add_f32_e32 v34, 1.0, v34
	v_rcp_f32_e32 v34, v34
	v_mul_f32_e32 v33, v33, v31
	v_mul_f32_e32 v26, v26, v32
	v_cndmask_b32_e32 v31, v31, v33, vcc
	v_cndmask_b32_e32 v32, v32, v26, vcc
	v_mul_f32_e32 v26, v27, v34
	v_mul_f32_e32 v20, v20, v74
	v_cndmask_b32_e32 v27, v34, v26, vcc
	v_cvt_pk_bf16_f32 v26, v30, v31
	v_mul_f32_e32 v30, 0xbfb8aa3b, v20
	v_exp_f32_e32 v30, v30
	v_cvt_pk_bf16_f32 v27, v32, v27
	v_mul_f32_e32 v21, v21, v74
	global_store_dwordx4 v[28:29], v[24:27], off nt
	v_mul_f32_e32 v22, v22, v74
	v_mul_f32_e32 v31, 0xbfb8aa3b, v21
	v_add_f32_e32 v24, 1.0, v30
	v_rcp_f32_e32 v24, v24
	v_mul_f32_e32 v26, 0xbfb8aa3b, v22
	v_exp_f32_e32 v31, v31
	v_exp_f32_e32 v26, v26
	v_mul_f32_e32 v20, v20, v24
	v_cndmask_b32_e32 v20, v24, v20, vcc
	v_add_f32_e32 v25, 1.0, v31
	v_add_f32_e32 v24, 1.0, v26
	v_mul_f32_e32 v23, v23, v74
	v_rcp_f32_e32 v25, v25
	v_rcp_f32_e32 v24, v24
	v_mul_f32_e32 v26, 0xbfb8aa3b, v23
	v_exp_f32_e32 v26, v26
; DI u32x2 pk4(f32x4 v) { u32x2 r; r.x = pk2(v[0], v[1]); r.y = pk2(v[2], v[3]); return r; }
; DI float sigmoidf_(float v) { return __builtin_amdgcn_rcpf(1.f + fast_exp2(-1.4426950408889634f * v)); }
; template <int REG>
; DI void epi_inproj(const Params& p, f32x4 (&acc)[2][2][4][2], int pm, int pn, LAS unsigned char* shm) {
;     ...
;       for (int m = 0; m < 4; ++m) { asm volatile("" ::: "memory");
;         const int r = 128 * ai + 64 * wr + 16 * m + fr;
;         const float rs = rsr[ai][m];
; #pragma unroll
;         for (int bj = 0; bj < 2; ++bj) {
;           u32x2 h[2];
; #pragma unroll
;           for (int n = 0; n < 2; ++n) {
;             f32x4 v = acc[ai][bj][m][n] * rs, o;
; #pragma unroll
;             for (int j = 0; j < 4; ++j) { const float sg = sigmoidf_(v[j]); o[j] = silu ? v[j] * sg : sg; }
;             h[n] = pk4(o);
;           }
;           *(u32x4*)(dstb + (long)(T0 + r) * 1024 + cb + 128 * bj + 32 * wc + 8 * fq) = (u32x4){h[0].x, h[0].y, h[1].x, h[1].y};
;         }
	v_mul_f32_e32 v21, v21, v25
	v_mul_f32_e32 v22, v22, v24
	v_cndmask_b32_e32 v21, v25, v21, vcc
	v_cndmask_b32_e32 v22, v24, v22, vcc
	v_add_f32_e32 v24, 1.0, v26
	v_mul_f32_e32 v25, v16, v74
	v_rcp_f32_e32 v24, v24
	v_mul_f32_e32 v16, 0xbfb8aa3b, v25
	v_exp_f32_e32 v26, v16
	v_mul_f32_e32 v18, v18, v74
	v_mul_f32_e32 v16, v23, v24
	v_cndmask_b32_e32 v23, v24, v16, vcc
	v_cvt_pk_bf16_f32 v16, v20, v21
	v_add_f32_e32 v20, 1.0, v26
	v_mul_f32_e32 v21, v17, v74
	v_rcp_f32_e32 v20, v20
	v_mul_f32_e32 v17, 0xbfb8aa3b, v21
	v_exp_f32_e32 v24, v17
	v_cvt_pk_bf16_f32 v17, v22, v23
	v_mul_f32_e32 v22, v25, v20
	v_mul_f32_e32 v23, 0xbfb8aa3b, v18
	v_mul_f32_e32 v19, v19, v74
	v_cndmask_b32_e32 v20, v20, v22, vcc
	v_add_f32_e32 v22, 1.0, v24
	v_exp_f32_e32 v23, v23
	v_mul_f32_e32 v24, 0xbfb8aa3b, v19
	v_exp_f32_e32 v24, v24
	v_rcp_f32_e32 v22, v22
	v_add_f32_e32 v23, 1.0, v23
	v_rcp_f32_e32 v23, v23
	v_add_f32_e32 v24, 1.0, v24
	v_rcp_f32_e32 v24, v24
	v_mul_f32_e32 v21, v21, v22
	v_mul_f32_e32 v18, v18, v23
	v_cndmask_b32_e32 v21, v22, v21, vcc
	v_cndmask_b32_e32 v22, v23, v18, vcc
	v_mul_f32_e32 v18, v19, v24
	v_cndmask_b32_e32 v19, v24, v18, vcc
	v_cvt_pk_bf16_f32 v18, v20, v21
	v_cvt_pk_bf16_f32 v19, v22, v19
	global_store_dwordx4 v[28:29], v[16:19], off offset:256 nt
	v_mul_f32_e32 v20, v13, v75
	v_mul_f32_e32 v14, v14, v75
	v_mul_f32_e32 v18, v12, v75
	v_mul_f32_e32 v12, 0xbfb8aa3b, v18
	v_exp_f32_e32 v19, v12
	v_mul_f32_e32 v12, 0xbfb8aa3b, v20
	v_add_u32_e32 v16, 0xb0, v148
	v_exp_f32_e32 v21, v12
	v_ashrrev_i32_e32 v17, 31, v16
	v_lshlrev_b64 v[16:17], 11, v[16:17]
	v_lshl_add_u64 v[12:13], v[120:121], 0, v[16:17]
	v_add_f32_e32 v16, 1.0, v19
	v_mul_f32_e32 v19, 0xbfb8aa3b, v14
	v_rcp_f32_e32 v16, v16
	v_add_f32_e32 v17, 1.0, v21
	v_exp_f32_e32 v19, v19
	v_rcp_f32_e32 v17, v17
	v_mul_f32_e32 v18, v18, v16
	v_mul_f32_e32 v15, v15, v75
	v_add_f32_e32 v19, 1.0, v19
	v_cndmask_b32_e32 v16, v16, v18, vcc
	v_mul_f32_e32 v18, v20, v17
	v_rcp_f32_e32 v19, v19
	v_mul_f32_e32 v20, 0xbfb8aa3b, v15
	v_exp_f32_e32 v20, v20
	v_cndmask_b32_e32 v17, v17, v18, vcc
	v_mul_f32_e32 v14, v14, v19
	v_cndmask_b32_e32 v14, v19, v14, vcc
	v_add_f32_e32 v18, 1.0, v20
	v_mul_f32_e32 v19, v8, v75
	v_rcp_f32_e32 v18, v18
	v_mul_f32_e32 v8, 0xbfb8aa3b, v19
	v_exp_f32_e32 v20, v8
	v_mul_f32_e32 v10, v10, v75
	v_mul_f32_e32 v8, v15, v18
	v_cndmask_b32_e32 v15, v18, v8, vcc
	v_cvt_pk_bf16_f32 v8, v16, v17
	v_add_f32_e32 v16, 1.0, v20
	v_rcp_f32_e32 v16, v16
	v_mul_f32_e32 v17, v9, v75
	v_mul_f32_e32 v9, 0xbfb8aa3b, v17
	v_exp_f32_e32 v18, v9
	v_cvt_pk_bf16_f32 v9, v14, v15
	v_mul_f32_e32 v14, v19, v16
	v_cndmask_b32_e32 v14, v16, v14, vcc
	v_mul_f32_e32 v16, 0xbfb8aa3b, v10
	v_mul_f32_e32 v11, v11, v75
	v_add_f32_e32 v15, 1.0, v18
	v_exp_f32_e32 v16, v16
	v_mul_f32_e32 v18, 0xbfb8aa3b, v11
	v_exp_f32_e32 v18, v18
	v_rcp_f32_e32 v15, v15
	v_add_f32_e32 v16, 1.0, v16
	v_rcp_f32_e32 v16, v16
	v_add_f32_e32 v18, 1.0, v18
	v_rcp_f32_e32 v18, v18
	v_mul_f32_e32 v17, v17, v15
	v_mul_f32_e32 v10, v10, v16
	v_cndmask_b32_e32 v15, v15, v17, vcc
	v_cndmask_b32_e32 v16, v16, v10, vcc
	v_mul_f32_e32 v10, v11, v18
	v_mul_f32_e32 v4, v4, v75
	v_cndmask_b32_e32 v11, v18, v10, vcc
	v_cvt_pk_bf16_f32 v10, v14, v15
	v_mul_f32_e32 v14, 0xbfb8aa3b, v4
	v_exp_f32_e32 v14, v14
	v_cvt_pk_bf16_f32 v11, v16, v11
	v_mul_f32_e32 v5, v5, v75
	global_store_dwordx4 v[12:13], v[8:11], off nt
	v_mul_f32_e32 v6, v6, v75
	v_mul_f32_e32 v15, 0xbfb8aa3b, v5
	v_add_f32_e32 v8, 1.0, v14
	v_rcp_f32_e32 v8, v8
	v_mul_f32_e32 v10, 0xbfb8aa3b, v6
	v_exp_f32_e32 v15, v15
	v_exp_f32_e32 v10, v10
	v_mul_f32_e32 v4, v4, v8
	v_cndmask_b32_e32 v4, v8, v4, vcc
	v_add_f32_e32 v9, 1.0, v15
	v_add_f32_e32 v8, 1.0, v10
	v_mul_f32_e32 v7, v7, v75
	v_rcp_f32_e32 v9, v9
	v_rcp_f32_e32 v8, v8
	v_mul_f32_e32 v10, 0xbfb8aa3b, v7
	v_exp_f32_e32 v10, v10
	v_mul_f32_e32 v5, v5, v9
	v_mul_f32_e32 v6, v6, v8
	v_cndmask_b32_e32 v5, v9, v5, vcc
	v_cndmask_b32_e32 v6, v8, v6, vcc
	v_add_f32_e32 v8, 1.0, v10
	v_mul_f32_e32 v9, v0, v75
	v_rcp_f32_e32 v8, v8
	v_mul_f32_e32 v0, 0xbfb8aa3b, v9
	v_exp_f32_e32 v10, v0
	v_mul_f32_e32 v2, v2, v75
	v_mul_f32_e32 v0, v7, v8
	v_cndmask_b32_e32 v7, v8, v0, vcc
	v_cvt_pk_bf16_f32 v0, v4, v5
	v_add_f32_e32 v4, 1.0, v10
	v_mul_f32_e32 v5, v1, v75
	v_rcp_f32_e32 v4, v4
	v_mul_f32_e32 v1, 0xbfb8aa3b, v5
	v_exp_f32_e32 v8, v1
	v_cvt_pk_bf16_f32 v1, v6, v7
	v_mul_f32_e32 v6, v9, v4
	v_mul_f32_e32 v7, 0xbfb8aa3b, v2
	v_mul_f32_e32 v3, v3, v75
	v_cndmask_b32_e32 v4, v4, v6, vcc
	v_add_f32_e32 v6, 1.0, v8
	v_exp_f32_e32 v7, v7
	v_mul_f32_e32 v8, 0xbfb8aa3b, v3
	v_exp_f32_e32 v8, v8
	v_rcp_f32_e32 v6, v6
	v_add_f32_e32 v7, 1.0, v7
	v_rcp_f32_e32 v7, v7
	v_add_f32_e32 v8, 1.0, v8
	v_rcp_f32_e32 v8, v8
	v_mul_f32_e32 v5, v5, v6
	v_mul_f32_e32 v2, v2, v7
	v_cndmask_b32_e32 v5, v6, v5, vcc
	v_cndmask_b32_e32 v6, v7, v2, vcc
	v_mul_f32_e32 v2, v3, v8
	v_cndmask_b32_e32 v3, v8, v2, vcc
	v_cvt_pk_bf16_f32 v2, v4, v5
	v_cvt_pk_bf16_f32 v3, v6, v3
	s_andn2_b64 vcc, exec, s[40:41]
	s_mov_b64 s[40:41], -1
	global_store_dwordx4 v[12:13], v[0:3], off offset:256 nt
	s_cbranch_vccnz .LBB0_192
	s_andn2_b64 vcc, exec, s[12:13]
	s_cbranch_vccnz .LBB0_191
	s_barrier
	s_branch .LBB0_191

; DI u32x2 pk4(f32x4 v) { u32x2 r; r.x = pk2(v[0], v[1]); r.y = pk2(v[2], v[3]); return r; }
; template <int REG>
; DI void epi_inproj(const Params& p, f32x4 (&acc)[2][2][4][2], int pm, int pn, LAS unsigned char* shm) {
;     ...
;     for (int bj = 0; bj < 2; ++bj) {
;       const int cB = 128 * bj + 32 * wc + 8 * fq;
; #pragma unroll
;       for (int ai = 0; ai < 2; ++ai)
; #pragma unroll
;         for (int m = 0; m < 4; ++m) { asm volatile("" ::: "memory");
;           const int rA = 128 * ai + 64 * wr + 16 * m + fr;
;           bf16_t* dst;
;           if (isr) { const int tl = cB & 127;
;             dst = (bf16_t*)(ws + OFF_VRT) + ((long)((b * 4 + (pn - 4)) * 64 + 2 * blk + (cB >> 7))) * 32768 + (((rA >> 4) * 4 + (tl >> 5)) * 64 + ((tl >> 3) & 3) * 16 + (rA & 15)) * 8; }
;           else dst = (bf16_t*)(ws + OFF_MVT) + ((long)(((b * 8 + (pn - 16) * 4 + (rA >> 6)) * 32 + blk) * 64 + (rA & 63))) * 256 + cB;
;           const u32x2 h0 = pk4(acc[ai][bj][m][0] * rs4[bj][0]), h1 = pk4(acc[ai][bj][m][1] * rs4[bj][1]);
;           *(u32x4*)dst = (u32x4){h0.x, h0.y, h1.x, h1.y};
;         }
.LBB0_259:
	s_waitcnt vmcnt(0)
	v_pk_mul_f32 v[134:135], v[134:135], v[142:143]
	v_pk_mul_f32 v[132:133], v[132:133], v[140:141]
	v_pk_mul_f32 v[130:131], v[130:131], v[138:139]
	v_pk_mul_f32 v[128:129], v[128:129], v[136:137]
	v_cvt_pk_bf16_f32 v132, v132, v133
	v_cvt_pk_bf16_f32 v133, v134, v135
	v_cvt_pk_bf16_f32 v134, v128, v129
	v_cvt_pk_bf16_f32 v135, v130, v131
	global_store_dwordx4 v[154:155], v[132:135], off nt
	v_cndmask_b32_e64 v128, 0, 1, s[58:59]
	v_cmp_ne_u32_e64 s[4:5], 1, v128
	s_andn2_b64 vcc, exec, s[58:59]
	s_mov_b64 s[58:59], -1
	s_cbranch_vccnz .LBB0_261
	v_or3_b32 v128, v171, v148, 16
	v_ashrrev_i32_e32 v129, 31, v128
	v_lshlrev_b64 v[128:129], 9, v[128:129]
	v_lshl_add_u64 v[128:129], v[152:153], 0, v[128:129]
	s_mov_b64 s[58:59], 0

; DI u32x2 pk4(f32x4 v) { u32x2 r; r.x = pk2(v[0], v[1]); r.y = pk2(v[2], v[3]); return r; }
; template <int REG>
; DI void epi_inproj(const Params& p, f32x4 (&acc)[2][2][4][2], int pm, int pn, LAS unsigned char* shm) {
;     ...
;         for (int m = 0; m < 4; ++m) { asm volatile("" ::: "memory");
;           const int rA = 128 * ai + 64 * wr + 16 * m + fr;
;           bf16_t* dst;
;           if (isr) { const int tl = cB & 127;
;             dst = (bf16_t*)(ws + OFF_VRT) + ((long)((b * 4 + (pn - 4)) * 64 + 2 * blk + (cB >> 7))) * 32768 + (((rA >> 4) * 4 + (tl >> 5)) * 64 + ((tl >> 3) & 3) * 16 + (rA & 15)) * 8; }
;           else dst = (bf16_t*)(ws + OFF_MVT) + ((long)(((b * 8 + (pn - 16) * 4 + (rA >> 6)) * 32 + blk) * 64 + (rA & 63))) * 256 + cB;
;           const u32x2 h0 = pk4(acc[ai][bj][m][0] * rs4[bj][0]), h1 = pk4(acc[ai][bj][m][1] * rs4[bj][1]);
;           *(u32x4*)dst = (u32x4){h0.x, h0.y, h1.x, h1.y};
;         }
.LBB0_263:
	v_pk_mul_f32 v[126:127], v[126:127], v[142:143]
	v_pk_mul_f32 v[124:125], v[124:125], v[140:141]
	v_pk_mul_f32 v[122:123], v[122:123], v[138:139]
	v_pk_mul_f32 v[120:121], v[120:121], v[136:137]
	v_cvt_pk_bf16_f32 v124, v124, v125
	v_cvt_pk_bf16_f32 v125, v126, v127
	v_cvt_pk_bf16_f32 v126, v120, v121
	v_cvt_pk_bf16_f32 v127, v122, v123
	global_store_dwordx4 v[128:129], v[124:127], off nt
	s_and_b64 vcc, exec, s[4:5]
	s_mov_b64 s[58:59], -1
	s_cbranch_vccnz .LBB0_265
	v_or3_b32 v120, v171, v148, 32
	v_ashrrev_i32_e32 v121, 31, v120
	v_lshlrev_b64 v[120:121], 9, v[120:121]
	v_lshl_add_u64 v[120:121], v[152:153], 0, v[120:121]
	s_mov_b64 s[58:59], 0

; DI u32x2 pk4(f32x4 v) { u32x2 r; r.x = pk2(v[0], v[1]); r.y = pk2(v[2], v[3]); return r; }
; template <int REG>
; DI void epi_inproj(const Params& p, f32x4 (&acc)[2][2][4][2], int pm, int pn, LAS unsigned char* shm) {
;     ...
;         for (int m = 0; m < 4; ++m) { asm volatile("" ::: "memory");
;           const int rA = 128 * ai + 64 * wr + 16 * m + fr;
;           bf16_t* dst;
;           if (isr) { const int tl = cB & 127;
;             dst = (bf16_t*)(ws + OFF_VRT) + ((long)((b * 4 + (pn - 4)) * 64 + 2 * blk + (cB >> 7))) * 32768 + (((rA >> 4) * 4 + (tl >> 5)) * 64 + ((tl >> 3) & 3) * 16 + (rA & 15)) * 8; }
;           else dst = (bf16_t*)(ws + OFF_MVT) + ((long)(((b * 8 + (pn - 16) * 4 + (rA >> 6)) * 32 + blk) * 64 + (rA & 63))) * 256 + cB;
;           const u32x2 h0 = pk4(acc[ai][bj][m][0] * rs4[bj][0]), h1 = pk4(acc[ai][bj][m][1] * rs4[bj][1]);
;           *(u32x4*)dst = (u32x4){h0.x, h0.y, h1.x, h1.y};
;         }
.LBB0_267:
	v_pk_mul_f32 v[118:119], v[118:119], v[142:143]
	v_pk_mul_f32 v[116:117], v[116:117], v[140:141]
	v_pk_mul_f32 v[114:115], v[114:115], v[138:139]
	v_pk_mul_f32 v[112:113], v[112:113], v[136:137]
	v_cvt_pk_bf16_f32 v116, v116, v117
	v_cvt_pk_bf16_f32 v117, v118, v119
	v_cvt_pk_bf16_f32 v118, v112, v113
	v_cvt_pk_bf16_f32 v119, v114, v115
	global_store_dwordx4 v[120:121], v[116:119], off nt
	s_and_b64 vcc, exec, s[4:5]
	s_mov_b64 s[58:59], -1
	s_cbranch_vccnz .LBB0_269
	v_or3_b32 v112, v171, v148, 48
	v_ashrrev_i32_e32 v113, 31, v112
	v_lshlrev_b64 v[112:113], 9, v[112:113]
	v_lshl_add_u64 v[112:113], v[152:153], 0, v[112:113]
	s_mov_b64 s[58:59], 0

; DI u32x2 pk4(f32x4 v) { u32x2 r; r.x = pk2(v[0], v[1]); r.y = pk2(v[2], v[3]); return r; }
; template <int REG>
; DI void epi_inproj(const Params& p, f32x4 (&acc)[2][2][4][2], int pm, int pn, LAS unsigned char* shm) {
;     ...
;         for (int m = 0; m < 4; ++m) { asm volatile("" ::: "memory");
;           const int rA = 128 * ai + 64 * wr + 16 * m + fr;
;           bf16_t* dst;
;           if (isr) { const int tl = cB & 127;
;             dst = (bf16_t*)(ws + OFF_VRT) + ((long)((b * 4 + (pn - 4)) * 64 + 2 * blk + (cB >> 7))) * 32768 + (((rA >> 4) * 4 + (tl >> 5)) * 64 + ((tl >> 3) & 3) * 16 + (rA & 15)) * 8; }
;           else dst = (bf16_t*)(ws + OFF_MVT) + ((long)(((b * 8 + (pn - 16) * 4 + (rA >> 6)) * 32 + blk) * 64 + (rA & 63))) * 256 + cB;
;           const u32x2 h0 = pk4(acc[ai][bj][m][0] * rs4[bj][0]), h1 = pk4(acc[ai][bj][m][1] * rs4[bj][1]);
;           *(u32x4*)dst = (u32x4){h0.x, h0.y, h1.x, h1.y};
;         }
.LBB0_271:
	v_pk_mul_f32 v[110:111], v[110:111], v[142:143]
	v_pk_mul_f32 v[108:109], v[108:109], v[140:141]
	v_pk_mul_f32 v[106:107], v[106:107], v[138:139]
	v_pk_mul_f32 v[104:105], v[104:105], v[136:137]
	v_cvt_pk_bf16_f32 v108, v108, v109
	v_cvt_pk_bf16_f32 v109, v110, v111
	v_cvt_pk_bf16_f32 v110, v104, v105
	v_cvt_pk_bf16_f32 v111, v106, v107
	global_store_dwordx4 v[112:113], v[108:111], off nt
	v_add_u32_e32 v106, 0x80, v172
	v_lshrrev_b32_e32 v104, 6, v106
	v_add_u32_e32 v104, s60, v104
	v_lshl_or_b32 v107, v104, 11, s61
	s_and_b64 vcc, exec, s[4:5]
	s_mov_b64 s[58:59], -1
	s_cbranch_vccnz .LBB0_273
	v_or_b32_e32 v104, v107, v171
	v_ashrrev_i32_e32 v105, 31, v104
	v_lshlrev_b64 v[104:105], 9, v[104:105]
	v_lshl_add_u64 v[104:105], v[152:153], 0, v[104:105]
	s_mov_b64 s[58:59], 0

; DI u32x2 pk4(f32x4 v) { u32x2 r; r.x = pk2(v[0], v[1]); r.y = pk2(v[2], v[3]); return r; }
; template <int REG>
; DI void epi_inproj(const Params& p, f32x4 (&acc)[2][2][4][2], int pm, int pn, LAS unsigned char* shm) {
;     ...
;         for (int m = 0; m < 4; ++m) { asm volatile("" ::: "memory");
;           const int rA = 128 * ai + 64 * wr + 16 * m + fr;
;           bf16_t* dst;
;           if (isr) { const int tl = cB & 127;
;             dst = (bf16_t*)(ws + OFF_VRT) + ((long)((b * 4 + (pn - 4)) * 64 + 2 * blk + (cB >> 7))) * 32768 + (((rA >> 4) * 4 + (tl >> 5)) * 64 + ((tl >> 3) & 3) * 16 + (rA & 15)) * 8; }
;           else dst = (bf16_t*)(ws + OFF_MVT) + ((long)(((b * 8 + (pn - 16) * 4 + (rA >> 6)) * 32 + blk) * 64 + (rA & 63))) * 256 + cB;
;           const u32x2 h0 = pk4(acc[ai][bj][m][0] * rs4[bj][0]), h1 = pk4(acc[ai][bj][m][1] * rs4[bj][1]);
;           *(u32x4*)dst = (u32x4){h0.x, h0.y, h1.x, h1.y};
;         }
.LBB0_275:
	v_pk_mul_f32 v[94:95], v[94:95], v[142:143]
	v_pk_mul_f32 v[92:93], v[92:93], v[140:141]
	v_pk_mul_f32 v[90:91], v[90:91], v[138:139]
	v_pk_mul_f32 v[88:89], v[88:89], v[136:137]
	v_cvt_pk_bf16_f32 v92, v92, v93
	v_cvt_pk_bf16_f32 v93, v94, v95
	v_cvt_pk_bf16_f32 v94, v88, v89
	v_cvt_pk_bf16_f32 v95, v90, v91
	global_store_dwordx4 v[104:105], v[92:95], off nt
	s_and_b64 vcc, exec, s[4:5]
	s_mov_b64 s[58:59], -1
	s_cbranch_vccnz .LBB0_277
	v_or3_b32 v88, v171, v107, 16
	v_ashrrev_i32_e32 v89, 31, v88
	v_lshlrev_b64 v[88:89], 9, v[88:89]
	v_lshl_add_u64 v[88:89], v[152:153], 0, v[88:89]
	s_mov_b64 s[58:59], 0

; DI u32x2 pk4(f32x4 v) { u32x2 r; r.x = pk2(v[0], v[1]); r.y = pk2(v[2], v[3]); return r; }
; template <int REG>
; DI void epi_inproj(const Params& p, f32x4 (&acc)[2][2][4][2], int pm, int pn, LAS unsigned char* shm) {
;     ...
;         for (int m = 0; m < 4; ++m) { asm volatile("" ::: "memory");
;           const int rA = 128 * ai + 64 * wr + 16 * m + fr;
;           bf16_t* dst;
;           if (isr) { const int tl = cB & 127;
;             dst = (bf16_t*)(ws + OFF_VRT) + ((long)((b * 4 + (pn - 4)) * 64 + 2 * blk + (cB >> 7))) * 32768 + (((rA >> 4) * 4 + (tl >> 5)) * 64 + ((tl >> 3) & 3) * 16 + (rA & 15)) * 8; }
;           else dst = (bf16_t*)(ws + OFF_MVT) + ((long)(((b * 8 + (pn - 16) * 4 + (rA >> 6)) * 32 + blk) * 64 + (rA & 63))) * 256 + cB;
;           const u32x2 h0 = pk4(acc[ai][bj][m][0] * rs4[bj][0]), h1 = pk4(acc[ai][bj][m][1] * rs4[bj][1]);
;           *(u32x4*)dst = (u32x4){h0.x, h0.y, h1.x, h1.y};
;         }
.LBB0_279:
	v_pk_mul_f32 v[86:87], v[86:87], v[142:143]
	v_pk_mul_f32 v[84:85], v[84:85], v[140:141]
	v_pk_mul_f32 v[82:83], v[82:83], v[138:139]
	v_pk_mul_f32 v[80:81], v[80:81], v[136:137]
	v_cvt_pk_bf16_f32 v84, v84, v85
	v_cvt_pk_bf16_f32 v85, v86, v87
	v_cvt_pk_bf16_f32 v86, v80, v81
	v_cvt_pk_bf16_f32 v87, v82, v83
	global_store_dwordx4 v[88:89], v[84:87], off nt
	s_and_b64 vcc, exec, s[4:5]
	s_mov_b64 s[58:59], -1
	s_cbranch_vccnz .LBB0_281
	v_or3_b32 v80, v171, v107, 32
	v_ashrrev_i32_e32 v81, 31, v80
	v_lshlrev_b64 v[80:81], 9, v[80:81]
	v_lshl_add_u64 v[80:81], v[152:153], 0, v[80:81]
	s_mov_b64 s[58:59], 0

; DI u32x2 pk4(f32x4 v) { u32x2 r; r.x = pk2(v[0], v[1]); r.y = pk2(v[2], v[3]); return r; }
; template <int REG>
; DI void epi_inproj(const Params& p, f32x4 (&acc)[2][2][4][2], int pm, int pn, LAS unsigned char* shm) {
;     ...
;         for (int m = 0; m < 4; ++m) { asm volatile("" ::: "memory");
;           const int rA = 128 * ai + 64 * wr + 16 * m + fr;
;           bf16_t* dst;
;           if (isr) { const int tl = cB & 127;
;             dst = (bf16_t*)(ws + OFF_VRT) + ((long)((b * 4 + (pn - 4)) * 64 + 2 * blk + (cB >> 7))) * 32768 + (((rA >> 4) * 4 + (tl >> 5)) * 64 + ((tl >> 3) & 3) * 16 + (rA & 15)) * 8; }
;           else dst = (bf16_t*)(ws + OFF_MVT) + ((long)(((b * 8 + (pn - 16) * 4 + (rA >> 6)) * 32 + blk) * 64 + (rA & 63))) * 256 + cB;
;           const u32x2 h0 = pk4(acc[ai][bj][m][0] * rs4[bj][0]), h1 = pk4(acc[ai][bj][m][1] * rs4[bj][1]);
;           *(u32x4*)dst = (u32x4){h0.x, h0.y, h1.x, h1.y};
;         }
.LBB0_283:
	v_pk_mul_f32 v[78:79], v[78:79], v[142:143]
	v_pk_mul_f32 v[76:77], v[76:77], v[140:141]
	v_pk_mul_f32 v[74:75], v[74:75], v[138:139]
	v_pk_mul_f32 v[72:73], v[72:73], v[136:137]
	v_cvt_pk_bf16_f32 v76, v76, v77
	v_cvt_pk_bf16_f32 v77, v78, v79
	v_cvt_pk_bf16_f32 v78, v72, v73
	v_cvt_pk_bf16_f32 v79, v74, v75
	global_store_dwordx4 v[80:81], v[76:79], off nt
	s_and_b64 vcc, exec, s[4:5]
	s_mov_b64 s[58:59], -1
	s_cbranch_vccnz .LBB0_285
	v_or3_b32 v72, v171, v107, 48
	v_ashrrev_i32_e32 v73, 31, v72
	v_lshlrev_b64 v[72:73], 9, v[72:73]
	v_lshl_add_u64 v[72:73], v[152:153], 0, v[72:73]
	s_mov_b64 s[58:59], 0

; DI u32x2 pk4(f32x4 v) { u32x2 r; r.x = pk2(v[0], v[1]); r.y = pk2(v[2], v[3]); return r; }
; template <int REG>
; DI void epi_inproj(const Params& p, f32x4 (&acc)[2][2][4][2], int pm, int pn, LAS unsigned char* shm) {
;     ...
;     for (int bj = 0; bj < 2; ++bj) {
;       const int cB = 128 * bj + 32 * wc + 8 * fq;
; #pragma unroll
;       for (int ai = 0; ai < 2; ++ai)
; #pragma unroll
;         for (int m = 0; m < 4; ++m) { asm volatile("" ::: "memory");
;           const int rA = 128 * ai + 64 * wr + 16 * m + fr;
;           bf16_t* dst;
;           if (isr) { const int tl = cB & 127;
;             dst = (bf16_t*)(ws + OFF_VRT) + ((long)((b * 4 + (pn - 4)) * 64 + 2 * blk + (cB >> 7))) * 32768 + (((rA >> 4) * 4 + (tl >> 5)) * 64 + ((tl >> 3) & 3) * 16 + (rA & 15)) * 8; }
;           else dst = (bf16_t*)(ws + OFF_MVT) + ((long)(((b * 8 + (pn - 16) * 4 + (rA >> 6)) * 32 + blk) * 64 + (rA & 63))) * 256 + cB;
;           const u32x2 h0 = pk4(acc[ai][bj][m][0] * rs4[bj][0]), h1 = pk4(acc[ai][bj][m][1] * rs4[bj][1]);
;           *(u32x4*)dst = (u32x4){h0.x, h0.y, h1.x, h1.y};
;         }
.LBB0_287:
	v_pk_mul_f32 v[70:71], v[70:71], v[142:143]
	v_pk_mul_f32 v[68:69], v[68:69], v[140:141]
	v_pk_mul_f32 v[62:63], v[62:63], v[138:139]
	v_pk_mul_f32 v[60:61], v[60:61], v[136:137]
	v_cvt_pk_bf16_f32 v68, v68, v69
	v_cvt_pk_bf16_f32 v69, v70, v71
	v_cvt_pk_bf16_f32 v70, v60, v61
	v_cvt_pk_bf16_f32 v71, v62, v63
	s_or_b32 s54, s54, 1
	global_store_dwordx4 v[72:73], v[68:71], off nt
	s_ashr_i32 s55, s54, 31
	s_lshl_b64 s[54:55], s[54:55], 16
	s_add_u32 s54, s82, s54
	s_addc_u32 s55, s83, s55
	s_and_b64 vcc, exec, s[4:5]
	s_mov_b64 s[56:57], -1
	s_cbranch_vccnz .LBB0_289
	v_or_b32_e32 v60, v148, v171
	v_ashrrev_i32_e32 v61, 31, v60
	v_lshlrev_b64 v[60:61], 9, v[60:61]
	v_lshl_add_u64 v[60:61], v[152:153], 0, v[60:61]
	v_lshl_add_u64 v[60:61], v[60:61], 0, s[100:101]
	s_mov_b64 s[56:57], 0

; DI u32x2 pk4(f32x4 v) { u32x2 r; r.x = pk2(v[0], v[1]); r.y = pk2(v[2], v[3]); return r; }
; template <int REG>
; DI void epi_inproj(const Params& p, f32x4 (&acc)[2][2][4][2], int pm, int pn, LAS unsigned char* shm) {
;     ...
;         for (int m = 0; m < 4; ++m) { asm volatile("" ::: "memory");
;           const int rA = 128 * ai + 64 * wr + 16 * m + fr;
;           bf16_t* dst;
;           if (isr) { const int tl = cB & 127;
;             dst = (bf16_t*)(ws + OFF_VRT) + ((long)((b * 4 + (pn - 4)) * 64 + 2 * blk + (cB >> 7))) * 32768 + (((rA >> 4) * 4 + (tl >> 5)) * 64 + ((tl >> 3) & 3) * 16 + (rA & 15)) * 8; }
;           else dst = (bf16_t*)(ws + OFF_MVT) + ((long)(((b * 8 + (pn - 16) * 4 + (rA >> 6)) * 32 + blk) * 64 + (rA & 63))) * 256 + cB;
;           const u32x2 h0 = pk4(acc[ai][bj][m][0] * rs4[bj][0]), h1 = pk4(acc[ai][bj][m][1] * rs4[bj][1]);
;           *(u32x4*)dst = (u32x4){h0.x, h0.y, h1.x, h1.y};
;         }
.LBB0_291:
	v_pk_mul_f32 v[66:67], v[66:67], v[102:103]
	v_pk_mul_f32 v[62:63], v[64:65], v[100:101]
	v_pk_mul_f32 v[58:59], v[58:59], v[98:99]
	v_pk_mul_f32 v[56:57], v[56:57], v[96:97]
	v_cvt_pk_bf16_f32 v62, v62, v63
	v_cvt_pk_bf16_f32 v63, v66, v67
	v_cvt_pk_bf16_f32 v64, v56, v57
	v_cvt_pk_bf16_f32 v65, v58, v59
	global_store_dwordx4 v[60:61], v[62:65], off nt
	s_and_b64 vcc, exec, s[4:5]
	s_mov_b64 s[56:57], -1
	s_cbranch_vccnz .LBB0_293
	v_or3_b32 v56, v171, v148, 16
	v_ashrrev_i32_e32 v57, 31, v56
	v_lshlrev_b64 v[56:57], 9, v[56:57]
	v_lshl_add_u64 v[56:57], v[152:153], 0, v[56:57]
	v_lshl_add_u64 v[56:57], v[56:57], 0, s[100:101]
	s_mov_b64 s[56:57], 0

; DI u32x2 pk4(f32x4 v) { u32x2 r; r.x = pk2(v[0], v[1]); r.y = pk2(v[2], v[3]); return r; }
; template <int REG>
; DI void epi_inproj(const Params& p, f32x4 (&acc)[2][2][4][2], int pm, int pn, LAS unsigned char* shm) {
;     ...
;         for (int m = 0; m < 4; ++m) { asm volatile("" ::: "memory");
;           const int rA = 128 * ai + 64 * wr + 16 * m + fr;
;           bf16_t* dst;
;           if (isr) { const int tl = cB & 127;
;             dst = (bf16_t*)(ws + OFF_VRT) + ((long)((b * 4 + (pn - 4)) * 64 + 2 * blk + (cB >> 7))) * 32768 + (((rA >> 4) * 4 + (tl >> 5)) * 64 + ((tl >> 3) & 3) * 16 + (rA & 15)) * 8; }
;           else dst = (bf16_t*)(ws + OFF_MVT) + ((long)(((b * 8 + (pn - 16) * 4 + (rA >> 6)) * 32 + blk) * 64 + (rA & 63))) * 256 + cB;
;           const u32x2 h0 = pk4(acc[ai][bj][m][0] * rs4[bj][0]), h1 = pk4(acc[ai][bj][m][1] * rs4[bj][1]);
;           *(u32x4*)dst = (u32x4){h0.x, h0.y, h1.x, h1.y};
;         }
.LBB0_295:
	v_pk_mul_f32 v[54:55], v[54:55], v[102:103]
	v_pk_mul_f32 v[52:53], v[52:53], v[100:101]
	v_pk_mul_f32 v[50:51], v[50:51], v[98:99]
	v_pk_mul_f32 v[48:49], v[48:49], v[96:97]
	v_cvt_pk_bf16_f32 v52, v52, v53
	v_cvt_pk_bf16_f32 v53, v54, v55
	v_cvt_pk_bf16_f32 v54, v48, v49
	v_cvt_pk_bf16_f32 v55, v50, v51
	global_store_dwordx4 v[56:57], v[52:55], off nt
	s_and_b64 vcc, exec, s[4:5]
	s_mov_b64 s[56:57], -1
	s_cbranch_vccnz .LBB0_297
	v_or3_b32 v48, v171, v148, 32
	v_ashrrev_i32_e32 v49, 31, v48
	v_lshlrev_b64 v[48:49], 9, v[48:49]
	v_lshl_add_u64 v[48:49], v[152:153], 0, v[48:49]
	v_lshl_add_u64 v[48:49], v[48:49], 0, s[100:101]
	s_mov_b64 s[56:57], 0

; DI u32x2 pk4(f32x4 v) { u32x2 r; r.x = pk2(v[0], v[1]); r.y = pk2(v[2], v[3]); return r; }
; template <int REG>
; DI void epi_inproj(const Params& p, f32x4 (&acc)[2][2][4][2], int pm, int pn, LAS unsigned char* shm) {
;     ...
;         for (int m = 0; m < 4; ++m) { asm volatile("" ::: "memory");
;           const int rA = 128 * ai + 64 * wr + 16 * m + fr;
;           bf16_t* dst;
;           if (isr) { const int tl = cB & 127;
;             dst = (bf16_t*)(ws + OFF_VRT) + ((long)((b * 4 + (pn - 4)) * 64 + 2 * blk + (cB >> 7))) * 32768 + (((rA >> 4) * 4 + (tl >> 5)) * 64 + ((tl >> 3) & 3) * 16 + (rA & 15)) * 8; }
;           else dst = (bf16_t*)(ws + OFF_MVT) + ((long)(((b * 8 + (pn - 16) * 4 + (rA >> 6)) * 32 + blk) * 64 + (rA & 63))) * 256 + cB;
;           const u32x2 h0 = pk4(acc[ai][bj][m][0] * rs4[bj][0]), h1 = pk4(acc[ai][bj][m][1] * rs4[bj][1]);
;           *(u32x4*)dst = (u32x4){h0.x, h0.y, h1.x, h1.y};
;         }
.LBB0_299:
	v_pk_mul_f32 v[46:47], v[46:47], v[102:103]
	v_pk_mul_f32 v[44:45], v[44:45], v[100:101]
	v_pk_mul_f32 v[42:43], v[42:43], v[98:99]
	v_pk_mul_f32 v[40:41], v[40:41], v[96:97]
	v_cvt_pk_bf16_f32 v44, v44, v45
	v_cvt_pk_bf16_f32 v45, v46, v47
	v_cvt_pk_bf16_f32 v46, v40, v41
	v_cvt_pk_bf16_f32 v47, v42, v43
	global_store_dwordx4 v[48:49], v[44:47], off nt
	s_and_b64 vcc, exec, s[4:5]
	s_mov_b64 s[56:57], -1
	s_cbranch_vccnz .LBB0_301
	v_or3_b32 v40, v171, v148, 48
	v_ashrrev_i32_e32 v41, 31, v40
	v_lshlrev_b64 v[40:41], 9, v[40:41]
	v_lshl_add_u64 v[40:41], v[152:153], 0, v[40:41]
	v_lshl_add_u64 v[40:41], v[40:41], 0, s[100:101]
	s_mov_b64 s[56:57], 0

; DI u32x2 pk4(f32x4 v) { u32x2 r; r.x = pk2(v[0], v[1]); r.y = pk2(v[2], v[3]); return r; }
; template <int REG>
; DI void epi_inproj(const Params& p, f32x4 (&acc)[2][2][4][2], int pm, int pn, LAS unsigned char* shm) {
;     ...
;         for (int m = 0; m < 4; ++m) { asm volatile("" ::: "memory");
;           const int rA = 128 * ai + 64 * wr + 16 * m + fr;
;           bf16_t* dst;
;           if (isr) { const int tl = cB & 127;
;             dst = (bf16_t*)(ws + OFF_VRT) + ((long)((b * 4 + (pn - 4)) * 64 + 2 * blk + (cB >> 7))) * 32768 + (((rA >> 4) * 4 + (tl >> 5)) * 64 + ((tl >> 3) & 3) * 16 + (rA & 15)) * 8; }
;           else dst = (bf16_t*)(ws + OFF_MVT) + ((long)(((b * 8 + (pn - 16) * 4 + (rA >> 6)) * 32 + blk) * 64 + (rA & 63))) * 256 + cB;
;           const u32x2 h0 = pk4(acc[ai][bj][m][0] * rs4[bj][0]), h1 = pk4(acc[ai][bj][m][1] * rs4[bj][1]);
;           *(u32x4*)dst = (u32x4){h0.x, h0.y, h1.x, h1.y};
;         }
.LBB0_303:
	v_pk_mul_f32 v[38:39], v[38:39], v[102:103]
	v_pk_mul_f32 v[36:37], v[36:37], v[100:101]
	v_pk_mul_f32 v[34:35], v[34:35], v[98:99]
	v_pk_mul_f32 v[32:33], v[32:33], v[96:97]
	v_cvt_pk_bf16_f32 v36, v36, v37
	v_cvt_pk_bf16_f32 v37, v38, v39
	v_cvt_pk_bf16_f32 v38, v32, v33
	v_cvt_pk_bf16_f32 v39, v34, v35
	global_store_dwordx4 v[40:41], v[36:39], off nt
	s_and_b64 vcc, exec, s[4:5]
	s_mov_b64 s[56:57], -1
	s_cbranch_vccnz .LBB0_305
	v_or_b32_e32 v32, v107, v171
	v_ashrrev_i32_e32 v33, 31, v32
	v_lshlrev_b64 v[32:33], 9, v[32:33]
	v_lshl_add_u64 v[32:33], v[152:153], 0, v[32:33]
	v_lshl_add_u64 v[32:33], v[32:33], 0, s[100:101]
	s_mov_b64 s[56:57], 0

; DI u32x2 pk4(f32x4 v) { u32x2 r; r.x = pk2(v[0], v[1]); r.y = pk2(v[2], v[3]); return r; }
; template <int REG>
; DI void epi_inproj(const Params& p, f32x4 (&acc)[2][2][4][2], int pm, int pn, LAS unsigned char* shm) {
;     ...
;         for (int m = 0; m < 4; ++m) { asm volatile("" ::: "memory");
;           const int rA = 128 * ai + 64 * wr + 16 * m + fr;
;           bf16_t* dst;
;           if (isr) { const int tl = cB & 127;
;             dst = (bf16_t*)(ws + OFF_VRT) + ((long)((b * 4 + (pn - 4)) * 64 + 2 * blk + (cB >> 7))) * 32768 + (((rA >> 4) * 4 + (tl >> 5)) * 64 + ((tl >> 3) & 3) * 16 + (rA & 15)) * 8; }
;           else dst = (bf16_t*)(ws + OFF_MVT) + ((long)(((b * 8 + (pn - 16) * 4 + (rA >> 6)) * 32 + blk) * 64 + (rA & 63))) * 256 + cB;
;           const u32x2 h0 = pk4(acc[ai][bj][m][0] * rs4[bj][0]), h1 = pk4(acc[ai][bj][m][1] * rs4[bj][1]);
;           *(u32x4*)dst = (u32x4){h0.x, h0.y, h1.x, h1.y};
;         }
.LBB0_307:
	v_pk_mul_f32 v[30:31], v[30:31], v[102:103]
	v_pk_mul_f32 v[28:29], v[28:29], v[100:101]
	v_pk_mul_f32 v[26:27], v[26:27], v[98:99]
	v_pk_mul_f32 v[24:25], v[24:25], v[96:97]
	v_cvt_pk_bf16_f32 v28, v28, v29
	v_cvt_pk_bf16_f32 v29, v30, v31
	v_cvt_pk_bf16_f32 v30, v24, v25
	v_cvt_pk_bf16_f32 v31, v26, v27
	global_store_dwordx4 v[32:33], v[28:31], off nt
	s_and_b64 vcc, exec, s[4:5]
	s_mov_b64 s[56:57], -1
	s_cbranch_vccnz .LBB0_309
	v_or3_b32 v24, v171, v107, 16
	v_ashrrev_i32_e32 v25, 31, v24
	v_lshlrev_b64 v[24:25], 9, v[24:25]
	v_lshl_add_u64 v[24:25], v[152:153], 0, v[24:25]
	v_lshl_add_u64 v[24:25], v[24:25], 0, s[100:101]
	s_mov_b64 s[56:57], 0

; DI u32x2 pk4(f32x4 v) { u32x2 r; r.x = pk2(v[0], v[1]); r.y = pk2(v[2], v[3]); return r; }
; template <int REG>
; DI void epi_inproj(const Params& p, f32x4 (&acc)[2][2][4][2], int pm, int pn, LAS unsigned char* shm) {
;     ...
;         for (int m = 0; m < 4; ++m) { asm volatile("" ::: "memory");
;           const int rA = 128 * ai + 64 * wr + 16 * m + fr;
;           bf16_t* dst;
;           if (isr) { const int tl = cB & 127;
;             dst = (bf16_t*)(ws + OFF_VRT) + ((long)((b * 4 + (pn - 4)) * 64 + 2 * blk + (cB >> 7))) * 32768 + (((rA >> 4) * 4 + (tl >> 5)) * 64 + ((tl >> 3) & 3) * 16 + (rA & 15)) * 8; }
;           else dst = (bf16_t*)(ws + OFF_MVT) + ((long)(((b * 8 + (pn - 16) * 4 + (rA >> 6)) * 32 + blk) * 64 + (rA & 63))) * 256 + cB;
;           const u32x2 h0 = pk4(acc[ai][bj][m][0] * rs4[bj][0]), h1 = pk4(acc[ai][bj][m][1] * rs4[bj][1]);
;           *(u32x4*)dst = (u32x4){h0.x, h0.y, h1.x, h1.y};
;         }
.LBB0_311:
	v_pk_mul_f32 v[22:23], v[22:23], v[102:103]
	v_pk_mul_f32 v[20:21], v[20:21], v[100:101]
	v_pk_mul_f32 v[18:19], v[18:19], v[98:99]
	v_pk_mul_f32 v[16:17], v[16:17], v[96:97]
	v_cvt_pk_bf16_f32 v20, v20, v21
	v_cvt_pk_bf16_f32 v21, v22, v23
	v_cvt_pk_bf16_f32 v22, v16, v17
	v_cvt_pk_bf16_f32 v23, v18, v19
	global_store_dwordx4 v[24:25], v[20:23], off nt
	s_and_b64 vcc, exec, s[4:5]
	s_mov_b64 s[56:57], -1
	s_cbranch_vccnz .LBB0_313
	v_or3_b32 v16, v171, v107, 32
	v_ashrrev_i32_e32 v17, 31, v16
	v_lshlrev_b64 v[16:17], 9, v[16:17]
	v_lshl_add_u64 v[16:17], v[152:153], 0, v[16:17]
	v_lshl_add_u64 v[16:17], v[16:17], 0, s[100:101]
	s_mov_b64 s[56:57], 0

; DI u32x2 pk4(f32x4 v) { u32x2 r; r.x = pk2(v[0], v[1]); r.y = pk2(v[2], v[3]); return r; }
; template <int REG>
; DI void epi_inproj(const Params& p, f32x4 (&acc)[2][2][4][2], int pm, int pn, LAS unsigned char* shm) {
;     ...
;         for (int m = 0; m < 4; ++m) { asm volatile("" ::: "memory");
;           const int rA = 128 * ai + 64 * wr + 16 * m + fr;
;           bf16_t* dst;
;           if (isr) { const int tl = cB & 127;
;             dst = (bf16_t*)(ws + OFF_VRT) + ((long)((b * 4 + (pn - 4)) * 64 + 2 * blk + (cB >> 7))) * 32768 + (((rA >> 4) * 4 + (tl >> 5)) * 64 + ((tl >> 3) & 3) * 16 + (rA & 15)) * 8; }
;           else dst = (bf16_t*)(ws + OFF_MVT) + ((long)(((b * 8 + (pn - 16) * 4 + (rA >> 6)) * 32 + blk) * 64 + (rA & 63))) * 256 + cB;
;           const u32x2 h0 = pk4(acc[ai][bj][m][0] * rs4[bj][0]), h1 = pk4(acc[ai][bj][m][1] * rs4[bj][1]);
;           *(u32x4*)dst = (u32x4){h0.x, h0.y, h1.x, h1.y};
;         }
.LBB0_315:
	v_pk_mul_f32 v[14:15], v[14:15], v[102:103]
	v_pk_mul_f32 v[12:13], v[12:13], v[100:101]
	v_pk_mul_f32 v[10:11], v[10:11], v[98:99]
	v_pk_mul_f32 v[8:9], v[8:9], v[96:97]
	v_cvt_pk_bf16_f32 v12, v12, v13
	v_cvt_pk_bf16_f32 v13, v14, v15
	v_cvt_pk_bf16_f32 v14, v8, v9
	v_cvt_pk_bf16_f32 v15, v10, v11
	global_store_dwordx4 v[16:17], v[12:15], off nt
	s_and_b64 vcc, exec, s[4:5]
	s_mov_b64 s[4:5], -1
	s_cbranch_vccnz .LBB0_317
	v_or3_b32 v8, v171, v107, 48
	v_ashrrev_i32_e32 v9, 31, v8
	v_lshlrev_b64 v[8:9], 9, v[8:9]
	v_lshl_add_u64 v[8:9], v[152:153], 0, v[8:9]
	v_lshl_add_u64 v[8:9], v[8:9], 0, s[100:101]
	s_mov_b64 s[4:5], 0

; DI u32x2 pk4(f32x4 v) { u32x2 r; r.x = pk2(v[0], v[1]); r.y = pk2(v[2], v[3]); return r; }
; template <int REG>
; DI void epi_inproj(const Params& p, f32x4 (&acc)[2][2][4][2], int pm, int pn, LAS unsigned char* shm) {
;     ...
;         for (int m = 0; m < 4; ++m) { asm volatile("" ::: "memory");
;           const int rA = 128 * ai + 64 * wr + 16 * m + fr;
;           bf16_t* dst;
;           if (isr) { const int tl = cB & 127;
;             dst = (bf16_t*)(ws + OFF_VRT) + ((long)((b * 4 + (pn - 4)) * 64 + 2 * blk + (cB >> 7))) * 32768 + (((rA >> 4) * 4 + (tl >> 5)) * 64 + ((tl >> 3) & 3) * 16 + (rA & 15)) * 8; }
;           else dst = (bf16_t*)(ws + OFF_MVT) + ((long)(((b * 8 + (pn - 16) * 4 + (rA >> 6)) * 32 + blk) * 64 + (rA & 63))) * 256 + cB;
;           const u32x2 h0 = pk4(acc[ai][bj][m][0] * rs4[bj][0]), h1 = pk4(acc[ai][bj][m][1] * rs4[bj][1]);
;           *(u32x4*)dst = (u32x4){h0.x, h0.y, h1.x, h1.y};
;         }
.LBB0_319:
	v_pk_mul_f32 v[6:7], v[6:7], v[102:103]
	v_pk_mul_f32 v[4:5], v[4:5], v[100:101]
	v_pk_mul_f32 v[2:3], v[2:3], v[98:99]
	v_pk_mul_f32 v[0:1], v[0:1], v[96:97]
	v_cvt_pk_bf16_f32 v4, v4, v5
	v_cvt_pk_bf16_f32 v5, v6, v7
	v_cvt_pk_bf16_f32 v6, v0, v1
	v_cvt_pk_bf16_f32 v7, v2, v3
	s_andn2_b64 vcc, exec, s[52:53]
	s_mov_b64 s[4:5], -1
	global_store_dwordx4 v[8:9], v[4:7], off nt
	s_cbranch_vccnz .LBB0_240
	s_andn2_b64 vcc, exec, s[12:13]
	s_cbranch_vccnz .LBB0_239
	s_barrier
	s_branch .LBB0_239

; #define LAS __attribute__((address_space(3)))
; template <int REG>
; DI void epi_inproj(const Params& p, f32x4 (&acc)[2][2][4][2], int pm, int pn, LAS unsigned char* shm) {
;     ...
; #pragma unroll
;     for (int ai = 0; ai < 2; ++ai)
; #pragma unroll
;       for (int m = 0; m < 4; ++m) { asm volatile("" ::: "memory");
;         const int r = 128 * ai + 64 * wr + 16 * m + fr, t = t0 + r;
;         const float rs = rsr[ai][m];
;         const f32x4 cs = *(const f32x4*)(cosT + t * 64 + 16 * wc + 4 * fq), sn = *(const f32x4*)(sinT + t * 64 + 16 * wc + 4 * fq);
; #pragma unroll
;         for (int bj = 0; bj < 2; ++bj) {
;           const int h = 2 * (pn & 1) + bj;
;           const float sc = fast_exp2((isk ? -1.f : 1.f) * (float)(t & 127) * lg2gamma(h)) * rs;
;           const f32x4 x1 = acc[ai][bj][m][0] * sc, x2 = acc[ai][bj][m][1] * sc;
;           const f32x4 y1 = x1 * cs - x2 * sn, y2 = x2 * cs + x1 * sn;
;           const int d = 16 * wc + 4 * fq;
;           const int tl2 = t & 127, r32 = tl2 & 31;
;           const int frag = isk ? (((tl2 >> 5) * 2 + ((r32 >> 2) & 1)) * 4 + (d >> 5)) : ((tl2 >> 4) * 4 + (d >> 5));
;           const int frl = isk ? ((r32 >> 3) * 4 + (r32 & 3)) : (tl2 & 15);
;           bf16_t* dst = dstb + ((long)((b * 4 + h) * 64 + (t >> 7))) * 16384 + (frag * 64 + ((d >> 3) & 3) * 16 + frl) * 8 + (d & 7);
;           const u32x2 o1 = pk4(y1), o2 = pk4(y2);
;           *(u32x2*)dst = o1; *(u32x2*)(dst + 2 * 512) = o2;
;           if (isk) {
;             LAS unsigned char* tb = shm + 135168 + wid * 1024;
;             LAS bf16_t* w1 = (LAS bf16_t*)(tb + (4 * fq) * 32 + fr * 2);
;             w1[0] = (bf16_t)(o1.x & 0xffff); w1[16] = (bf16_t)(o1.x >> 16); w1[32] = (bf16_t)(o1.y & 0xffff); w1[48] = (bf16_t)(o1.y >> 16);
;             LAS bf16_t* w2 = w1 + 16 * 16;
;             w2[0] = (bf16_t)(o2.x & 0xffff); w2[16] = (bf16_t)(o2.x >> 16); w2[32] = (bf16_t)(o2.y & 0xffff); w2[48] = (bf16_t)(o2.y >> 16);
;             asm volatile("s_waitcnt lgkmcnt(0)" ::: "memory");
;             const int dl = lane >> 1, th = lane & 1;
;             const u32x4 kv = *(const LAS u32x4*)(tb + dl * 32 + th * 16);
;             asm volatile("" ::: "memory");
;             const int dd = dl < 16 ? 16 * wc + dl : 48 + 16 * wc + dl;
;             const int tb0 = t0 + 128 * ai + 64 * wr + 16 * m + 8 * th, tl = tb0 & 127;
.LBB0_365:
	v_mov_b32_e32 v156, v194
	s_lshl_b32 s6, s8, 8
	v_ashrrev_i32_e32 v169, 6, v156
	v_lshlrev_b32_e32 v170, 4, v169
	v_and_b32_e32 v177, 48, v170
	v_lshrrev_b32_e32 v171, 2, v156
	s_ashr_i32 s7, s6, 31
	v_lshlrev_b32_e32 v148, 2, v177
	v_and_b32_e32 v178, 12, v171
	v_ashrrev_i32_e32 v157, 8, v156
	s_lshl_b64 s[56:57], s[6:7], 2
	v_lshl_add_u64 v[136:137], s[16:17], 0, v[148:149]
	v_lshlrev_b32_e32 v138, 2, v178
	v_mov_b32_e32 v139, v149
	v_and_b32_e32 v168, 15, v156
	s_add_u32 s56, s78, s56
	v_lshlrev_b32_e32 v176, 6, v157
	v_lshl_add_u64 v[152:153], v[136:137], 0, v[138:139]
	v_lshl_add_u64 v[136:137], s[20:21], 0, v[148:149]
	s_addc_u32 s57, s79, s57
	v_lshlrev_b32_e32 v64, 3, v168
	s_and_b32 s59, s6, 0x1f00
	v_lshl_add_u64 v[154:155], v[136:137], 0, v[138:139]
	v_or_b32_e32 v136, v176, v168
	v_lshl_or_b32 v64, v157, 7, v64
	v_add_u32_e32 v148, s59, v136
	v_ashrrev_i32_e32 v65, 31, v64
	v_lshlrev_b32_e32 v136, 6, v148
	v_lshl_add_u64 v[132:133], v[64:65], 2, s[56:57]
	v_ashrrev_i32_e32 v137, 31, v136
	global_load_dwordx4 v[64:67], v[132:133], off offset:16
	s_nop 0
	global_load_dwordx4 v[132:135], v[132:133], off
	v_lshlrev_b64 v[140:141], 2, v[136:137]
	v_lshl_add_u64 v[136:137], v[154:155], 0, v[140:141]
	global_load_dwordx4 v[136:139], v[136:137], off
	v_lshl_add_u64 v[140:141], v[152:153], 0, v[140:141]
	global_load_dwordx4 v[140:143], v[140:141], off
	s_cmp_gt_i32 s0, 1
	s_cselect_b64 s[6:7], -1, 0
	s_and_b64 s[56:57], s[6:7], exec
	s_cselect_b32 s1, s88, 0x2300000
	s_add_u32 s56, s26, s1
	s_addc_u32 s57, s27, 0
	s_lshl_b32 s1, s0, 1
	s_lshr_b32 s8, s8, 3
	s_and_b32 s1, s1, 2
	s_and_b32 s8, s8, 0x3fffffc
	s_cmp_eq_u32 s1, 0
	v_bitop3_b32 v172, v176, s90, v168 bitop3:0xc8
	s_cselect_b64 vcc, -1, 0
	s_or_b32 s1, s1, s8
	v_cvt_f32_ubyte0_e32 v172, v172
	s_lshl_b32 s58, s1, 6
	v_bfe_u32 v174, v170, 5, 1
	v_bfe_u32 v179, v156, 1, 5
	v_cndmask_b32_e64 v186, v172, -v172, s[6:7]
	s_cmp_lt_i32 s0, 2
	v_or_b32_e32 v172, v170, v178
	v_and_b32_e32 v173, 3, v156
	v_and_or_b32 v175, v156, 4, v174
	v_lshl_add_u32 v170, v169, 10, s89
	v_lshlrev_b32_e32 v169, 5, v178
	v_lshrrev_b32_e32 v178, 1, v156
	v_and_b32_e32 v184, 1, v156
	v_or_b32_e32 v156, v177, v179
	v_add3_u32 v177, v179, v177, 48
	v_cmp_gt_u32_e64 s[0:1], 16, v179
	v_lshlrev_b32_e32 v172, 1, v172
	v_and_b32_e32 v172, 48, v172
	v_cndmask_b32_e64 v156, v177, v156, s[0:1]
	v_lshrrev_b32_e32 v177, 2, v156
	v_and_b32_e32 v181, 15, v156
	v_and_or_b32 v156, v178, 4, v173
	v_and_b32_e32 v183, 64, v176
	v_and_b32_e32 v182, 60, v177
	v_cndmask_b32_e64 v156, v168, v156, s[6:7]
	v_ashrrev_i32_e32 v187, 7, v148
	v_lshlrev_b32_e32 v148, 4, v157
	v_cndmask_b32_e32 v177, v163, v164, vcc
	v_or_b32_e32 v196, v172, v156
	v_and_b32_e32 v178, 16, v148
	v_lshrrev_b32_e32 v148, 5, v183
	v_mul_f32_e32 v156, v177, v186
	v_and_b32_e32 v195, 4, v171
	v_lshlrev_b32_e32 v171, 1, v168
	v_or_b32_e32 v148, v182, v148
	v_exp_f32_e32 v188, v156
	v_add3_u32 v169, v170, v169, v171
	v_lshlrev_b32_e32 v171, 4, v184
	v_lshlrev_b32_e32 v148, 6, v148
	v_or3_b32 v185, v148, v171, v181
	v_lshlrev_b32_e32 v148, 4, v185
	v_lshl_add_u64 v[156:157], s[46:47], 0, v[148:149]
	v_lshl_add_u32 v170, v179, 5, v170
	v_add_u32_e32 v179, s59, v176
	v_ashrrev_i32_e32 v180, 7, v179
	s_waitcnt vmcnt(0)
	v_mul_f32_e32 v148, v132, v188
	v_pk_mul_f32 v[126:127], v[126:127], v[148:149] op_sel_hi:[1,0]
	v_pk_mul_f32 v[124:125], v[124:125], v[148:149] op_sel_hi:[1,0]
	v_pk_mul_f32 v[128:129], v[128:129], v[148:149] op_sel_hi:[1,0]
	v_pk_mul_f32 v[130:131], v[130:131], v[148:149] op_sel_hi:[1,0]
	v_pk_mul_f32 v[188:189], v[136:137], v[124:125]
	v_pk_mul_f32 v[190:191], v[138:139], v[126:127]
	v_pk_fma_f32 v[188:189], v[140:141], v[128:129], v[188:189] neg_lo:[0,0,1] neg_hi:[0,0,1]
	v_pk_fma_f32 v[190:191], v[142:143], v[130:131], v[190:191] neg_lo:[0,0,1] neg_hi:[0,0,1]
	v_pk_mul_f32 v[128:129], v[136:137], v[128:129]
	v_pk_mul_f32 v[130:131], v[138:139], v[130:131]
	s_nop 0
	v_pk_fma_f32 v[192:193], v[142:143], v[126:127], v[130:131]
	v_pk_fma_f32 v[126:127], v[140:141], v[124:125], v[128:129]
	v_cndmask_b32_e64 v124, v174, v175, s[6:7]
	v_or_b32_e32 v128, v124, v178
	v_add_u32_e32 v124, s58, v187
	v_ashrrev_i32_e32 v125, 31, v124
	v_lshlrev_b64 v[124:125], 15, v[124:125]
	v_lshlrev_b32_e32 v130, 3, v196
	v_lshl_add_u64 v[124:125], s[56:57], 0, v[124:125]
	v_lshl_or_b32 v148, v128, 9, v130
	v_lshl_add_u64 v[128:129], v[148:149], 1, v[124:125]
	v_lshlrev_b32_e32 v124, 1, v195
	v_mov_b32_e32 v125, v149
	v_lshl_add_u64 v[196:197], v[128:129], 0, v[124:125]
	v_cvt_pk_bf16_f32 v128, v188, v189
	v_cvt_pk_bf16_f32 v129, v190, v191
	v_cvt_pk_bf16_f32 v126, v126, v127
	v_cvt_pk_bf16_f32 v127, v192, v193
	global_store_dwordx2 v[196:197], v[128:129], off
	global_store_dwordx2 v[196:197], v[126:127], off offset:2048
	s_cbranch_scc1 .LBB0_367
	ds_write_b16 v169, v128
	ds_write_b16_d16_hi v169, v128 offset:32
	ds_write_b16 v169, v129 offset:64
	ds_write_b16_d16_hi v169, v129 offset:96
	ds_write_b16 v169, v126 offset:512
	ds_write_b16_d16_hi v169, v126 offset:544
	ds_write_b16 v169, v127 offset:576
	ds_write_b16_d16_hi v169, v127 offset:608
	s_waitcnt lgkmcnt(0)
	v_add_u32_e32 v126, v170, v171
	ds_read_b128 v[126:129], v126
	v_add_u32_e32 v188, s58, v180
	v_ashrrev_i32_e32 v189, 31, v188
	v_lshlrev_b64 v[188:189], 15, v[188:189]
	v_lshl_add_u64 v[188:189], v[156:157], 0, v[188:189]
	s_waitcnt lgkmcnt(0)
	global_store_dwordx4 v[188:189], v[126:129], off nt
; #define LAS __attribute__((address_space(3)))
; template <int REG>
; DI void epi_inproj(const Params& p, f32x4 (&acc)[2][2][4][2], int pm, int pn, LAS unsigned char* shm) {
;     ...
; #pragma unroll
;     for (int ai = 0; ai < 2; ++ai)
; #pragma unroll
;       for (int m = 0; m < 4; ++m) { asm volatile("" ::: "memory");
;         const int r = 128 * ai + 64 * wr + 16 * m + fr, t = t0 + r;
;         const float rs = rsr[ai][m];
;         const f32x4 cs = *(const f32x4*)(cosT + t * 64 + 16 * wc + 4 * fq), sn = *(const f32x4*)(sinT + t * 64 + 16 * wc + 4 * fq);
; #pragma unroll
;         for (int bj = 0; bj < 2; ++bj) {
;           const int h = 2 * (pn & 1) + bj;
;           const float sc = fast_exp2((isk ? -1.f : 1.f) * (float)(t & 127) * lg2gamma(h)) * rs;
;           const f32x4 x1 = acc[ai][bj][m][0] * sc, x2 = acc[ai][bj][m][1] * sc;
;           const f32x4 y1 = x1 * cs - x2 * sn, y2 = x2 * cs + x1 * sn;
;           const int d = 16 * wc + 4 * fq;
;           const int tl2 = t & 127, r32 = tl2 & 31;
;           const int frag = isk ? (((tl2 >> 5) * 2 + ((r32 >> 2) & 1)) * 4 + (d >> 5)) : ((tl2 >> 4) * 4 + (d >> 5));
;           const int frl = isk ? ((r32 >> 3) * 4 + (r32 & 3)) : (tl2 & 15);
;           bf16_t* dst = dstb + ((long)((b * 4 + h) * 64 + (t >> 7))) * 16384 + (frag * 64 + ((d >> 3) & 3) * 16 + frl) * 8 + (d & 7);
;           const u32x2 o1 = pk4(y1), o2 = pk4(y2);
;           *(u32x2*)dst = o1; *(u32x2*)(dst + 2 * 512) = o2;
;           if (isk) {
;             LAS unsigned char* tb = shm + 135168 + wid * 1024;
;             LAS bf16_t* w1 = (LAS bf16_t*)(tb + (4 * fq) * 32 + fr * 2);
;             w1[0] = (bf16_t)(o1.x & 0xffff); w1[16] = (bf16_t)(o1.x >> 16); w1[32] = (bf16_t)(o1.y & 0xffff); w1[48] = (bf16_t)(o1.y >> 16);
;             LAS bf16_t* w2 = w1 + 16 * 16;
;             w2[0] = (bf16_t)(o2.x & 0xffff); w2[16] = (bf16_t)(o2.x >> 16); w2[32] = (bf16_t)(o2.y & 0xffff); w2[48] = (bf16_t)(o2.y >> 16);
;             asm volatile("s_waitcnt lgkmcnt(0)" ::: "memory");
;             const int dl = lane >> 1, th = lane & 1;
;             const u32x4 kv = *(const LAS u32x4*)(tb + dl * 32 + th * 16);
;             asm volatile("" ::: "memory");
;             const int dd = dl < 16 ? 16 * wc + dl : 48 + 16 * wc + dl;
;             const int tb0 = t0 + 128 * ai + 64 * wr + 16 * m + 8 * th, tl = tb0 & 127;
.LBB0_367:
	s_nop 1
	v_cndmask_b32_e32 v126, v165, v166, vcc
	v_mul_f32_e32 v127, v126, v186
	v_exp_f32_e32 v127, v127
	s_or_b32 s0, s58, 64
	s_andn2_b64 vcc, exec, s[6:7]
	v_mul_f32_e32 v128, v132, v127
	v_pk_mul_f32 v[118:119], v[118:119], v[128:129] op_sel_hi:[1,0]
	v_pk_mul_f32 v[122:123], v[122:123], v[128:129] op_sel_hi:[1,0]
	v_pk_mul_f32 v[188:189], v[138:139], v[118:119]
	v_pk_mul_f32 v[118:119], v[142:143], v[118:119]
	v_pk_fma_f32 v[188:189], v[142:143], v[122:123], v[188:189] neg_lo:[0,0,1] neg_hi:[0,0,1]
	v_pk_fma_f32 v[122:123], v[138:139], v[122:123], v[118:119]
	v_add_u32_e32 v118, s0, v187
	v_pk_mul_f32 v[116:117], v[116:117], v[128:129] op_sel_hi:[1,0]
	v_ashrrev_i32_e32 v119, 31, v118
	v_pk_mul_f32 v[120:121], v[120:121], v[128:129] op_sel_hi:[1,0]
	v_pk_mul_f32 v[128:129], v[136:137], v[116:117]
	v_pk_mul_f32 v[116:117], v[140:141], v[116:117]
	v_lshlrev_b64 v[118:119], 15, v[118:119]
	v_pk_fma_f32 v[116:117], v[136:137], v[120:121], v[116:117]
	v_lshl_add_u64 v[118:119], s[56:57], 0, v[118:119]
	v_pk_fma_f32 v[128:129], v[140:141], v[120:121], v[128:129] neg_lo:[0,0,1] neg_hi:[0,0,1]
	v_lshl_add_u64 v[118:119], v[148:149], 1, v[118:119]
	v_cvt_pk_bf16_f32 v116, v116, v117
	v_cvt_pk_bf16_f32 v117, v122, v123
	v_cndmask_b32_e64 v122, 0, 1, s[6:7]
	v_lshl_add_u64 v[120:121], v[118:119], 0, v[124:125]
	v_cvt_pk_bf16_f32 v118, v128, v129
	v_cvt_pk_bf16_f32 v119, v188, v189
	v_cmp_ne_u32_e64 s[8:9], 1, v122
	global_store_dwordx2 v[120:121], v[118:119], off
	global_store_dwordx2 v[120:121], v[116:117], off offset:2048
	s_cbranch_vccnz .LBB0_369
	ds_write_b16 v169, v118
	ds_write_b16_d16_hi v169, v118 offset:32
	ds_write_b16 v169, v119 offset:64
	ds_write_b16_d16_hi v169, v119 offset:96
	ds_write_b16 v169, v116 offset:512
	ds_write_b16_d16_hi v169, v116 offset:544
	ds_write_b16 v169, v117 offset:576
	ds_write_b16_d16_hi v169, v117 offset:608
	s_waitcnt lgkmcnt(0)
	v_add_u32_e32 v116, v170, v171
	ds_read_b128 v[116:119], v116
	v_add_u32_e32 v120, s0, v180
	v_ashrrev_i32_e32 v121, 31, v120
	v_lshlrev_b64 v[120:121], 15, v[120:121]
	v_lshl_add_u64 v[120:121], v[156:157], 0, v[120:121]
	s_waitcnt lgkmcnt(0)
	global_store_dwordx4 v[120:121], v[116:119], off nt
.LBB0_369:
	v_or_b32_e32 v127, 16, v176
	v_or_b32_e32 v128, v127, v168
	v_add_u32_e32 v129, s59, v128
	v_lshlrev_b32_e32 v116, 6, v129
	v_ashrrev_i32_e32 v117, 31, v116
	v_lshlrev_b64 v[116:117], 2, v[116:117]
	v_lshl_add_u64 v[118:119], v[154:155], 0, v[116:117]
	global_load_dwordx4 v[120:123], v[118:119], off
	v_lshl_add_u64 v[116:117], v[152:153], 0, v[116:117]
	global_load_dwordx4 v[116:119], v[116:117], off
	v_bitop3_b32 v131, v127, s91, v168 bitop3:0xc8
	v_cvt_f32_ubyte0_e32 v131, v131
	v_lshrrev_b32_e32 v132, 1, v128
	v_cndmask_b32_e64 v128, v131, -v131, s[6:7]
	v_and_or_b32 v131, v132, 12, v173
	v_mul_f32_e32 v132, v177, v128
	v_exp_f32_e32 v132, v132
	v_lshrrev_b32_e32 v127, 2, v127
	v_and_or_b32 v136, v127, 20, v174
	v_and_or_b32 v137, v127, 16, v175
	v_ashrrev_i32_e32 v127, 7, v129
	v_cndmask_b32_e64 v129, v136, v137, s[6:7]
	v_cndmask_b32_e64 v131, v168, v131, s[6:7]
	v_add_u32_e32 v136, s58, v127
	v_lshlrev_b32_e32 v129, 9, v129
	v_or_b32_e32 v131, v131, v172
	v_ashrrev_i32_e32 v137, 31, v136
	v_mul_f32_e32 v132, v133, v132
	v_lshlrev_b64 v[136:137], 15, v[136:137]
	v_lshl_or_b32 v129, v131, 3, v129
	v_pk_mul_f32 v[114:115], v[114:115], v[132:133] op_sel_hi:[1,0]
	v_pk_mul_f32 v[112:113], v[112:113], v[132:133] op_sel_hi:[1,0]
	v_pk_mul_f32 v[110:111], v[110:111], v[132:133] op_sel_hi:[1,0]
	v_pk_mul_f32 v[108:109], v[108:109], v[132:133] op_sel_hi:[1,0]
	v_lshl_add_u64 v[136:137], s[56:57], 0, v[136:137]
	v_lshlrev_b32_e32 v148, 1, v129
	v_mov_b32_e32 v125, v149
	v_lshl_add_u64 v[136:137], v[136:137], 0, v[148:149]
	s_and_b64 vcc, exec, s[8:9]
	v_lshl_add_u64 v[136:137], v[136:137], 0, v[124:125]
	s_waitcnt vmcnt(1)
	v_pk_mul_f32 v[138:139], v[110:111], v[122:123]
	v_pk_mul_f32 v[140:141], v[108:109], v[120:121]
	v_pk_mul_f32 v[142:143], v[114:115], v[122:123]
	v_pk_mul_f32 v[186:187], v[112:113], v[120:121]
	s_waitcnt vmcnt(0)
	v_pk_fma_f32 v[114:115], v[114:115], v[118:119], v[138:139] neg_lo:[0,0,1] neg_hi:[0,0,1]
	v_pk_fma_f32 v[112:113], v[112:113], v[116:117], v[140:141] neg_lo:[0,0,1] neg_hi:[0,0,1]
	v_pk_fma_f32 v[138:139], v[110:111], v[118:119], v[142:143]
	v_pk_fma_f32 v[108:109], v[108:109], v[116:117], v[186:187]
	v_cvt_pk_bf16_f32 v110, v112, v113
	v_cvt_pk_bf16_f32 v111, v114, v115
	v_cvt_pk_bf16_f32 v108, v108, v109
	v_cvt_pk_bf16_f32 v109, v138, v139
	global_store_dwordx2 v[136:137], v[110:111], off
	global_store_dwordx2 v[136:137], v[108:109], off offset:2048
	s_cbranch_vccnz .LBB0_371
	ds_write_b16 v169, v110
	ds_write_b16_d16_hi v169, v110 offset:32
	ds_write_b16 v169, v111 offset:64
	ds_write_b16_d16_hi v169, v111 offset:96
	ds_write_b16 v169, v108 offset:512
	ds_write_b16_d16_hi v169, v108 offset:544
	ds_write_b16 v169, v109 offset:576
	ds_write_b16_d16_hi v169, v109 offset:608
	s_waitcnt lgkmcnt(0)
	v_add_u32_e32 v108, v170, v171
	ds_read_b128 v[108:111], v108
	v_add_u32_e32 v112, s58, v180
	v_ashrrev_i32_e32 v113, 31, v112
	v_lshlrev_b64 v[112:113], 15, v[112:113]
	v_lshl_add_u64 v[112:113], v[156:157], 0, v[112:113]
	s_waitcnt lgkmcnt(0)
	global_store_dwordx4 v[112:113], v[108:111], off offset:512 nt
; #define LAS __attribute__((address_space(3)))
; template <int REG>
; DI void epi_inproj(const Params& p, f32x4 (&acc)[2][2][4][2], int pm, int pn, LAS unsigned char* shm) {
;     ...
; #pragma unroll
;     for (int ai = 0; ai < 2; ++ai)
; #pragma unroll
;       for (int m = 0; m < 4; ++m) { asm volatile("" ::: "memory");
;         const int r = 128 * ai + 64 * wr + 16 * m + fr, t = t0 + r;
;         const float rs = rsr[ai][m];
;         const f32x4 cs = *(const f32x4*)(cosT + t * 64 + 16 * wc + 4 * fq), sn = *(const f32x4*)(sinT + t * 64 + 16 * wc + 4 * fq);
; #pragma unroll
;         for (int bj = 0; bj < 2; ++bj) {
;           const int h = 2 * (pn & 1) + bj;
;           const float sc = fast_exp2((isk ? -1.f : 1.f) * (float)(t & 127) * lg2gamma(h)) * rs;
;           const f32x4 x1 = acc[ai][bj][m][0] * sc, x2 = acc[ai][bj][m][1] * sc;
;           const f32x4 y1 = x1 * cs - x2 * sn, y2 = x2 * cs + x1 * sn;
;           const int d = 16 * wc + 4 * fq;
;           const int tl2 = t & 127, r32 = tl2 & 31;
;           const int frag = isk ? (((tl2 >> 5) * 2 + ((r32 >> 2) & 1)) * 4 + (d >> 5)) : ((tl2 >> 4) * 4 + (d >> 5));
;           const int frl = isk ? ((r32 >> 3) * 4 + (r32 & 3)) : (tl2 & 15);
;           bf16_t* dst = dstb + ((long)((b * 4 + h) * 64 + (t >> 7))) * 16384 + (frag * 64 + ((d >> 3) & 3) * 16 + frl) * 8 + (d & 7);
;           const u32x2 o1 = pk4(y1), o2 = pk4(y2);
;           *(u32x2*)dst = o1; *(u32x2*)(dst + 2 * 512) = o2;
;           if (isk) {
;             LAS unsigned char* tb = shm + 135168 + wid * 1024;
;             LAS bf16_t* w1 = (LAS bf16_t*)(tb + (4 * fq) * 32 + fr * 2);
;             w1[0] = (bf16_t)(o1.x & 0xffff); w1[16] = (bf16_t)(o1.x >> 16); w1[32] = (bf16_t)(o1.y & 0xffff); w1[48] = (bf16_t)(o1.y >> 16);
;             LAS bf16_t* w2 = w1 + 16 * 16;
;             w2[0] = (bf16_t)(o2.x & 0xffff); w2[16] = (bf16_t)(o2.x >> 16); w2[32] = (bf16_t)(o2.y & 0xffff); w2[48] = (bf16_t)(o2.y >> 16);
;             asm volatile("s_waitcnt lgkmcnt(0)" ::: "memory");
;             const int dl = lane >> 1, th = lane & 1;
;             const u32x4 kv = *(const LAS u32x4*)(tb + dl * 32 + th * 16);
;             asm volatile("" ::: "memory");
;             const int dd = dl < 16 ? 16 * wc + dl : 48 + 16 * wc + dl;
;             const int tb0 = t0 + 128 * ai + 64 * wr + 16 * m + 8 * th, tl = tb0 & 127;
.LBB0_371:
	s_nop 1
	v_mul_f32_e32 v108, v126, v128
	v_exp_f32_e32 v108, v108
	s_and_b64 vcc, exec, s[8:9]
	v_mul_f32_e32 v108, v133, v108
	v_pk_mul_f32 v[102:103], v[102:103], v[108:109] op_sel_hi:[1,0]
	v_pk_mul_f32 v[106:107], v[106:107], v[108:109] op_sel_hi:[1,0]
	v_pk_mul_f32 v[104:105], v[104:105], v[108:109] op_sel_hi:[1,0]
	v_pk_mul_f32 v[100:101], v[100:101], v[108:109] op_sel_hi:[1,0]
	v_pk_mul_f32 v[108:109], v[102:103], v[122:123]
	v_pk_mul_f32 v[110:111], v[100:101], v[120:121]
	v_pk_fma_f32 v[108:109], v[106:107], v[118:119], v[108:109] neg_lo:[0,0,1] neg_hi:[0,0,1]
	v_pk_mul_f32 v[106:107], v[106:107], v[122:123]
	v_pk_fma_f32 v[110:111], v[104:105], v[116:117], v[110:111] neg_lo:[0,0,1] neg_hi:[0,0,1]
	v_pk_fma_f32 v[106:107], v[102:103], v[118:119], v[106:107]
	v_add_u32_e32 v102, s0, v127
	v_ashrrev_i32_e32 v103, 31, v102
	v_lshlrev_b64 v[102:103], 15, v[102:103]
	v_pk_mul_f32 v[104:105], v[104:105], v[120:121]
	v_lshl_add_u64 v[102:103], s[56:57], 0, v[102:103]
	v_pk_fma_f32 v[100:101], v[100:101], v[116:117], v[104:105]
	v_lshl_add_u64 v[102:103], v[102:103], 0, v[148:149]
	v_lshl_add_u64 v[104:105], v[102:103], 0, v[124:125]
	v_cvt_pk_bf16_f32 v102, v110, v111
	v_cvt_pk_bf16_f32 v103, v108, v109
	v_cvt_pk_bf16_f32 v100, v100, v101
	v_cvt_pk_bf16_f32 v101, v106, v107
	v_mov_b32_e32 v110, v174
	global_store_dwordx2 v[104:105], v[102:103], off
	global_store_dwordx2 v[104:105], v[100:101], off offset:2048
	s_cbranch_vccnz .LBB0_373
	ds_write_b16 v169, v102
	ds_write_b16_d16_hi v169, v102 offset:32
	ds_write_b16 v169, v103 offset:64
	ds_write_b16_d16_hi v169, v103 offset:96
	ds_write_b16 v169, v100 offset:512
	ds_write_b16_d16_hi v169, v100 offset:544
	ds_write_b16 v169, v101 offset:576
	ds_write_b16_d16_hi v169, v101 offset:608
	s_waitcnt lgkmcnt(0)
	v_add_u32_e32 v100, v170, v171
	ds_read_b128 v[100:103], v100
	v_add_u32_e32 v104, s0, v180
	v_ashrrev_i32_e32 v105, 31, v104
	v_lshlrev_b64 v[104:105], 15, v[104:105]
	v_lshl_add_u64 v[104:105], v[156:157], 0, v[104:105]
	v_mov_b32_e32 v110, v175
	s_waitcnt lgkmcnt(0)
	global_store_dwordx4 v[104:105], v[100:103], off offset:512 nt
.LBB0_373:
	v_or_b32_e32 v108, 32, v176
	s_nop 0
	v_or_b32_e32 v100, v108, v168
	v_add_u32_e32 v112, s59, v100
	v_lshlrev_b32_e32 v100, 6, v112
	v_ashrrev_i32_e32 v101, 31, v100
	v_lshlrev_b64 v[100:101], 2, v[100:101]
	v_lshl_add_u64 v[102:103], v[154:155], 0, v[100:101]
	global_load_dwordx4 v[104:107], v[102:103], off
	v_lshl_add_u64 v[100:101], v[152:153], 0, v[100:101]
	global_load_dwordx4 v[100:103], v[100:101], off
	v_bitop3_b32 v111, v108, s92, v168 bitop3:0xc8
	v_cvt_f32_ubyte0_e32 v111, v111
	v_cndmask_b32_e64 v111, v111, -v111, s[6:7]
	v_mul_f32_e32 v114, v177, v111
	v_exp_f32_e32 v114, v114
	v_lshrrev_b32_e32 v113, 2, v108
	v_lshlrev_b32_e32 v109, 3, v185
	v_and_or_b32 v113, v113, 24, v110
	v_ashrrev_i32_e32 v110, 7, v112
	v_lshl_or_b32 v148, v109, 1, v167
	v_lshl_or_b32 v113, v113, 9, v130
	v_add_u32_e32 v112, s58, v110
	v_lshl_add_u64 v[108:109], s[46:47], 0, v[148:149]
	v_lshlrev_b32_e32 v148, 1, v113
	v_ashrrev_i32_e32 v113, 31, v112
	v_mul_f32_e32 v114, v134, v114
	v_lshlrev_b64 v[112:113], 15, v[112:113]
	v_pk_mul_f32 v[98:99], v[98:99], v[114:115] op_sel_hi:[1,0]
	v_pk_mul_f32 v[96:97], v[96:97], v[114:115] op_sel_hi:[1,0]
	v_pk_mul_f32 v[94:95], v[94:95], v[114:115] op_sel_hi:[1,0]
	v_pk_mul_f32 v[92:93], v[92:93], v[114:115] op_sel_hi:[1,0]
	v_lshl_add_u64 v[112:113], s[56:57], 0, v[112:113]
	v_mov_b32_e32 v125, v149
	v_lshl_add_u64 v[112:113], v[112:113], 0, v[148:149]
	s_and_b64 vcc, exec, s[8:9]
	v_lshl_add_u64 v[112:113], v[112:113], 0, v[124:125]
	s_waitcnt vmcnt(1)
	v_pk_mul_f32 v[114:115], v[94:95], v[106:107]
	v_pk_mul_f32 v[116:117], v[92:93], v[104:105]
	v_pk_mul_f32 v[118:119], v[98:99], v[106:107]
	v_pk_mul_f32 v[120:121], v[96:97], v[104:105]
	s_waitcnt vmcnt(0)
	v_pk_fma_f32 v[98:99], v[98:99], v[102:103], v[114:115] neg_lo:[0,0,1] neg_hi:[0,0,1]
	v_pk_fma_f32 v[96:97], v[96:97], v[100:101], v[116:117] neg_lo:[0,0,1] neg_hi:[0,0,1]
	v_pk_fma_f32 v[114:115], v[94:95], v[102:103], v[118:119]
	v_pk_fma_f32 v[92:93], v[92:93], v[100:101], v[120:121]
	v_cvt_pk_bf16_f32 v94, v96, v97
	v_cvt_pk_bf16_f32 v95, v98, v99
	v_cvt_pk_bf16_f32 v92, v92, v93
	v_cvt_pk_bf16_f32 v93, v114, v115
	global_store_dwordx2 v[112:113], v[94:95], off
	global_store_dwordx2 v[112:113], v[92:93], off offset:2048
	s_cbranch_vccnz .LBB0_375
	ds_write_b16 v169, v94
	ds_write_b16_d16_hi v169, v94 offset:32
	ds_write_b16 v169, v95 offset:64
	ds_write_b16_d16_hi v169, v95 offset:96
	ds_write_b16 v169, v92 offset:512
	ds_write_b16_d16_hi v169, v92 offset:544
	ds_write_b16 v169, v93 offset:576
	ds_write_b16_d16_hi v169, v93 offset:608
	s_waitcnt lgkmcnt(0)
	v_add_u32_e32 v92, v170, v171
	ds_read_b128 v[92:95], v92
	v_add_u32_e32 v96, s58, v180
	v_ashrrev_i32_e32 v97, 31, v96
	v_lshlrev_b64 v[96:97], 15, v[96:97]
	v_lshl_add_u64 v[96:97], v[108:109], 0, v[96:97]
	s_waitcnt lgkmcnt(0)
	global_store_dwordx4 v[96:97], v[92:95], off nt
; #define LAS __attribute__((address_space(3)))
; template <int REG>
; DI void epi_inproj(const Params& p, f32x4 (&acc)[2][2][4][2], int pm, int pn, LAS unsigned char* shm) {
;     ...
; #pragma unroll
;     for (int ai = 0; ai < 2; ++ai)
; #pragma unroll
;       for (int m = 0; m < 4; ++m) { asm volatile("" ::: "memory");
;         const int r = 128 * ai + 64 * wr + 16 * m + fr, t = t0 + r;
;         const float rs = rsr[ai][m];
;         const f32x4 cs = *(const f32x4*)(cosT + t * 64 + 16 * wc + 4 * fq), sn = *(const f32x4*)(sinT + t * 64 + 16 * wc + 4 * fq);
; #pragma unroll
;         for (int bj = 0; bj < 2; ++bj) {
;           const int h = 2 * (pn & 1) + bj;
;           const float sc = fast_exp2((isk ? -1.f : 1.f) * (float)(t & 127) * lg2gamma(h)) * rs;
;           const f32x4 x1 = acc[ai][bj][m][0] * sc, x2 = acc[ai][bj][m][1] * sc;
;           const f32x4 y1 = x1 * cs - x2 * sn, y2 = x2 * cs + x1 * sn;
;           const int d = 16 * wc + 4 * fq;
;           const int tl2 = t & 127, r32 = tl2 & 31;
;           const int frag = isk ? (((tl2 >> 5) * 2 + ((r32 >> 2) & 1)) * 4 + (d >> 5)) : ((tl2 >> 4) * 4 + (d >> 5));
;           const int frl = isk ? ((r32 >> 3) * 4 + (r32 & 3)) : (tl2 & 15);
;           bf16_t* dst = dstb + ((long)((b * 4 + h) * 64 + (t >> 7))) * 16384 + (frag * 64 + ((d >> 3) & 3) * 16 + frl) * 8 + (d & 7);
;           const u32x2 o1 = pk4(y1), o2 = pk4(y2);
;           *(u32x2*)dst = o1; *(u32x2*)(dst + 2 * 512) = o2;
;           if (isk) {
;             LAS unsigned char* tb = shm + 135168 + wid * 1024;
;             LAS bf16_t* w1 = (LAS bf16_t*)(tb + (4 * fq) * 32 + fr * 2);
;             w1[0] = (bf16_t)(o1.x & 0xffff); w1[16] = (bf16_t)(o1.x >> 16); w1[32] = (bf16_t)(o1.y & 0xffff); w1[48] = (bf16_t)(o1.y >> 16);
;             LAS bf16_t* w2 = w1 + 16 * 16;
;             w2[0] = (bf16_t)(o2.x & 0xffff); w2[16] = (bf16_t)(o2.x >> 16); w2[32] = (bf16_t)(o2.y & 0xffff); w2[48] = (bf16_t)(o2.y >> 16);
;             asm volatile("s_waitcnt lgkmcnt(0)" ::: "memory");
;             const int dl = lane >> 1, th = lane & 1;
;             const u32x4 kv = *(const LAS u32x4*)(tb + dl * 32 + th * 16);
;             asm volatile("" ::: "memory");
;             const int dd = dl < 16 ? 16 * wc + dl : 48 + 16 * wc + dl;
;             const int tb0 = t0 + 128 * ai + 64 * wr + 16 * m + 8 * th, tl = tb0 & 127;
.LBB0_375:
	s_nop 1
	v_mul_f32_e32 v92, v126, v111
	v_exp_f32_e32 v92, v92
	s_and_b64 vcc, exec, s[8:9]
	v_mul_f32_e32 v92, v134, v92
	v_pk_mul_f32 v[86:87], v[86:87], v[92:93] op_sel_hi:[1,0]
	v_pk_mul_f32 v[90:91], v[90:91], v[92:93] op_sel_hi:[1,0]
	v_pk_mul_f32 v[88:89], v[88:89], v[92:93] op_sel_hi:[1,0]
	v_pk_mul_f32 v[84:85], v[84:85], v[92:93] op_sel_hi:[1,0]
	v_pk_mul_f32 v[92:93], v[86:87], v[106:107]
	v_pk_mul_f32 v[94:95], v[84:85], v[104:105]
	v_pk_fma_f32 v[92:93], v[90:91], v[102:103], v[92:93] neg_lo:[0,0,1] neg_hi:[0,0,1]
	v_pk_mul_f32 v[90:91], v[90:91], v[106:107]
	v_pk_fma_f32 v[94:95], v[88:89], v[100:101], v[94:95] neg_lo:[0,0,1] neg_hi:[0,0,1]
	v_pk_fma_f32 v[90:91], v[86:87], v[102:103], v[90:91]
	v_add_u32_e32 v86, s0, v110
	v_ashrrev_i32_e32 v87, 31, v86
	v_lshlrev_b64 v[86:87], 15, v[86:87]
	v_pk_mul_f32 v[88:89], v[88:89], v[104:105]
	v_lshl_add_u64 v[86:87], s[56:57], 0, v[86:87]
	v_pk_fma_f32 v[84:85], v[84:85], v[100:101], v[88:89]
	v_lshl_add_u64 v[86:87], v[86:87], 0, v[148:149]
	v_lshl_add_u64 v[88:89], v[86:87], 0, v[124:125]
	v_cvt_pk_bf16_f32 v86, v94, v95
	v_cvt_pk_bf16_f32 v87, v92, v93
	v_cvt_pk_bf16_f32 v84, v84, v85
	v_cvt_pk_bf16_f32 v85, v90, v91
	global_store_dwordx2 v[88:89], v[86:87], off
	global_store_dwordx2 v[88:89], v[84:85], off offset:2048
	s_cbranch_vccnz .LBB0_377
	ds_write_b16 v169, v86
	ds_write_b16_d16_hi v169, v86 offset:32
	ds_write_b16 v169, v87 offset:64
	ds_write_b16_d16_hi v169, v87 offset:96
	ds_write_b16 v169, v84 offset:512
	ds_write_b16_d16_hi v169, v84 offset:544
	ds_write_b16 v169, v85 offset:576
	ds_write_b16_d16_hi v169, v85 offset:608
	s_waitcnt lgkmcnt(0)
	v_add_u32_e32 v84, v170, v171
	ds_read_b128 v[84:87], v84
	v_add_u32_e32 v88, s0, v180
	v_ashrrev_i32_e32 v89, 31, v88
	v_lshlrev_b64 v[88:89], 15, v[88:89]
	v_lshl_add_u64 v[88:89], v[108:109], 0, v[88:89]
	s_waitcnt lgkmcnt(0)
	global_store_dwordx4 v[88:89], v[84:87], off nt
.LBB0_377:
	v_or_b32_e32 v92, 48, v176
	v_or_b32_e32 v93, v92, v168
	v_add_u32_e32 v94, s59, v93
	v_lshlrev_b32_e32 v84, 6, v94
	v_ashrrev_i32_e32 v85, 31, v84
	v_lshlrev_b64 v[84:85], 2, v[84:85]
	v_lshl_add_u64 v[86:87], v[154:155], 0, v[84:85]
	global_load_dwordx4 v[88:91], v[86:87], off
	v_lshl_add_u64 v[84:85], v[152:153], 0, v[84:85]
	global_load_dwordx4 v[84:87], v[84:85], off
	v_lshlrev_b32_e32 v95, 3, v184
	v_bitop3_b32 v96, v92, s93, v168 bitop3:0xc8
	v_or3_b32 v95, v183, v95, 48
	v_cvt_f32_ubyte0_e32 v96, v96
	v_lshrrev_b32_e32 v98, 5, v95
	v_lshlrev_b32_e32 v99, 1, v95
	v_cndmask_b32_e64 v95, v96, -v96, s[6:7]
	v_or_b32_e32 v96, v182, v98
	v_and_b32_e32 v98, 48, v99
	v_lshlrev_b32_e32 v96, 6, v96
	v_mul_f32_e32 v99, v177, v95
	v_lshrrev_b32_e32 v92, 2, v92
	v_lshrrev_b32_e32 v93, 1, v93
	v_or3_b32 v96, v96, v98, v181
	v_exp_f32_e32 v98, v99
	v_and_or_b32 v97, v92, 28, v174
	v_and_or_b32 v92, v92, 24, v175
	v_and_or_b32 v93, v93, 12, v173
	v_ashrrev_i32_e32 v94, 7, v94
	v_cndmask_b32_e64 v97, v97, v92, s[6:7]
	v_cndmask_b32_e64 v93, v168, v93, s[6:7]
	v_add_u32_e32 v92, s58, v94
	v_lshlrev_b32_e32 v100, 9, v97
	v_or_b32_e32 v101, v93, v172
	v_ashrrev_i32_e32 v93, 31, v92
	v_lshl_or_b32 v99, v101, 3, v100
	v_mul_f32_e32 v98, v135, v98
	v_lshlrev_b32_e32 v148, 4, v96
	v_lshlrev_b64 v[96:97], 15, v[92:93]
	v_pk_mul_f32 v[82:83], v[82:83], v[98:99] op_sel_hi:[1,0]
	v_pk_mul_f32 v[80:81], v[80:81], v[98:99] op_sel_hi:[1,0]
	v_pk_mul_f32 v[78:79], v[78:79], v[98:99] op_sel_hi:[1,0]
	v_pk_mul_f32 v[76:77], v[76:77], v[98:99] op_sel_hi:[1,0]
	v_lshl_add_u64 v[92:93], s[46:47], 0, v[148:149]
	v_lshl_add_u64 v[96:97], s[56:57], 0, v[96:97]
	v_lshlrev_b32_e32 v148, 1, v99
	v_mov_b32_e32 v125, v149
	v_lshl_add_u64 v[96:97], v[96:97], 0, v[148:149]
	s_and_b64 vcc, exec, s[8:9]
	v_lshl_add_u64 v[96:97], v[96:97], 0, v[124:125]
	s_waitcnt vmcnt(1)
	v_pk_mul_f32 v[98:99], v[78:79], v[90:91]
	v_pk_mul_f32 v[100:101], v[76:77], v[88:89]
	v_pk_mul_f32 v[102:103], v[82:83], v[90:91]
	v_pk_mul_f32 v[104:105], v[80:81], v[88:89]
	s_waitcnt vmcnt(0)
	v_pk_fma_f32 v[82:83], v[82:83], v[86:87], v[98:99] neg_lo:[0,0,1] neg_hi:[0,0,1]
	v_pk_fma_f32 v[80:81], v[80:81], v[84:85], v[100:101] neg_lo:[0,0,1] neg_hi:[0,0,1]
	v_pk_fma_f32 v[98:99], v[78:79], v[86:87], v[102:103]
	v_pk_fma_f32 v[76:77], v[76:77], v[84:85], v[104:105]
	v_cvt_pk_bf16_f32 v78, v80, v81
	v_cvt_pk_bf16_f32 v79, v82, v83
	v_cvt_pk_bf16_f32 v76, v76, v77
	v_cvt_pk_bf16_f32 v77, v98, v99
	global_store_dwordx2 v[96:97], v[78:79], off
	global_store_dwordx2 v[96:97], v[76:77], off offset:2048
	s_cbranch_vccnz .LBB0_379
	ds_write_b16 v169, v78
	ds_write_b16_d16_hi v169, v78 offset:32
	ds_write_b16 v169, v79 offset:64
	ds_write_b16_d16_hi v169, v79 offset:96
	ds_write_b16 v169, v76 offset:512
	ds_write_b16_d16_hi v169, v76 offset:544
	ds_write_b16 v169, v77 offset:576
	ds_write_b16_d16_hi v169, v77 offset:608
	s_waitcnt lgkmcnt(0)
	v_add_u32_e32 v76, v170, v171
	ds_read_b128 v[76:79], v76
	v_add_u32_e32 v80, s58, v180
	v_ashrrev_i32_e32 v81, 31, v80
	v_lshlrev_b64 v[80:81], 15, v[80:81]
	v_lshl_add_u64 v[80:81], v[92:93], 0, v[80:81]
	s_waitcnt lgkmcnt(0)
	global_store_dwordx4 v[80:81], v[76:79], off nt
; #define LAS __attribute__((address_space(3)))
; template <int REG>
; DI void epi_inproj(const Params& p, f32x4 (&acc)[2][2][4][2], int pm, int pn, LAS unsigned char* shm) {
;     ...
; #pragma unroll
;     for (int ai = 0; ai < 2; ++ai)
; #pragma unroll
;       for (int m = 0; m < 4; ++m) { asm volatile("" ::: "memory");
;         const int r = 128 * ai + 64 * wr + 16 * m + fr, t = t0 + r;
;         const float rs = rsr[ai][m];
;         const f32x4 cs = *(const f32x4*)(cosT + t * 64 + 16 * wc + 4 * fq), sn = *(const f32x4*)(sinT + t * 64 + 16 * wc + 4 * fq);
; #pragma unroll
;         for (int bj = 0; bj < 2; ++bj) {
;           const int h = 2 * (pn & 1) + bj;
;           const float sc = fast_exp2((isk ? -1.f : 1.f) * (float)(t & 127) * lg2gamma(h)) * rs;
;           const f32x4 x1 = acc[ai][bj][m][0] * sc, x2 = acc[ai][bj][m][1] * sc;
;           const f32x4 y1 = x1 * cs - x2 * sn, y2 = x2 * cs + x1 * sn;
;           const int d = 16 * wc + 4 * fq;
;           const int tl2 = t & 127, r32 = tl2 & 31;
;           const int frag = isk ? (((tl2 >> 5) * 2 + ((r32 >> 2) & 1)) * 4 + (d >> 5)) : ((tl2 >> 4) * 4 + (d >> 5));
;           const int frl = isk ? ((r32 >> 3) * 4 + (r32 & 3)) : (tl2 & 15);
;           bf16_t* dst = dstb + ((long)((b * 4 + h) * 64 + (t >> 7))) * 16384 + (frag * 64 + ((d >> 3) & 3) * 16 + frl) * 8 + (d & 7);
;           const u32x2 o1 = pk4(y1), o2 = pk4(y2);
;           *(u32x2*)dst = o1; *(u32x2*)(dst + 2 * 512) = o2;
;           if (isk) {
;             LAS unsigned char* tb = shm + 135168 + wid * 1024;
;             LAS bf16_t* w1 = (LAS bf16_t*)(tb + (4 * fq) * 32 + fr * 2);
;             w1[0] = (bf16_t)(o1.x & 0xffff); w1[16] = (bf16_t)(o1.x >> 16); w1[32] = (bf16_t)(o1.y & 0xffff); w1[48] = (bf16_t)(o1.y >> 16);
;             LAS bf16_t* w2 = w1 + 16 * 16;
;             w2[0] = (bf16_t)(o2.x & 0xffff); w2[16] = (bf16_t)(o2.x >> 16); w2[32] = (bf16_t)(o2.y & 0xffff); w2[48] = (bf16_t)(o2.y >> 16);
;             asm volatile("s_waitcnt lgkmcnt(0)" ::: "memory");
;             const int dl = lane >> 1, th = lane & 1;
;             const u32x4 kv = *(const LAS u32x4*)(tb + dl * 32 + th * 16);
;             asm volatile("" ::: "memory");
;             const int dd = dl < 16 ? 16 * wc + dl : 48 + 16 * wc + dl;
;             const int tb0 = t0 + 128 * ai + 64 * wr + 16 * m + 8 * th, tl = tb0 & 127;
.LBB0_379:
	s_nop 1
	v_mul_f32_e32 v76, v126, v95
	v_exp_f32_e32 v76, v76
	s_and_b64 vcc, exec, s[8:9]
	v_mul_f32_e32 v76, v135, v76
	v_pk_mul_f32 v[70:71], v[70:71], v[76:77] op_sel_hi:[1,0]
	v_pk_mul_f32 v[74:75], v[74:75], v[76:77] op_sel_hi:[1,0]
	v_pk_mul_f32 v[72:73], v[72:73], v[76:77] op_sel_hi:[1,0]
	v_pk_mul_f32 v[68:69], v[68:69], v[76:77] op_sel_hi:[1,0]
	v_pk_mul_f32 v[76:77], v[70:71], v[90:91]
	v_pk_mul_f32 v[78:79], v[68:69], v[88:89]
	v_pk_fma_f32 v[76:77], v[74:75], v[86:87], v[76:77] neg_lo:[0,0,1] neg_hi:[0,0,1]
	v_pk_mul_f32 v[74:75], v[74:75], v[90:91]
	v_pk_fma_f32 v[78:79], v[72:73], v[84:85], v[78:79] neg_lo:[0,0,1] neg_hi:[0,0,1]
	v_pk_fma_f32 v[74:75], v[70:71], v[86:87], v[74:75]
	v_add_u32_e32 v70, s0, v94
	v_ashrrev_i32_e32 v71, 31, v70
	v_lshlrev_b64 v[70:71], 15, v[70:71]
	v_pk_mul_f32 v[72:73], v[72:73], v[88:89]
	v_lshl_add_u64 v[70:71], s[56:57], 0, v[70:71]
	v_pk_fma_f32 v[68:69], v[68:69], v[84:85], v[72:73]
	v_lshl_add_u64 v[70:71], v[70:71], 0, v[148:149]
	v_lshl_add_u64 v[72:73], v[70:71], 0, v[124:125]
	v_cvt_pk_bf16_f32 v70, v78, v79
	v_cvt_pk_bf16_f32 v71, v76, v77
	v_cvt_pk_bf16_f32 v68, v68, v69
	v_cvt_pk_bf16_f32 v69, v74, v75
	v_mov_b32_e32 v76, v174
	global_store_dwordx2 v[72:73], v[70:71], off
	global_store_dwordx2 v[72:73], v[68:69], off offset:2048
	s_cbranch_vccnz .LBB0_381
	ds_write_b16 v169, v70
	ds_write_b16_d16_hi v169, v70 offset:32
	ds_write_b16 v169, v71 offset:64
	ds_write_b16_d16_hi v169, v71 offset:96
	ds_write_b16 v169, v68 offset:512
	ds_write_b16_d16_hi v169, v68 offset:544
	ds_write_b16 v169, v69 offset:576
	ds_write_b16_d16_hi v169, v69 offset:608
	s_waitcnt lgkmcnt(0)
	v_add_u32_e32 v68, v170, v171
	ds_read_b128 v[68:71], v68
	v_add_u32_e32 v72, s0, v180
	v_ashrrev_i32_e32 v73, 31, v72
	v_lshlrev_b64 v[72:73], 15, v[72:73]
	v_lshl_add_u64 v[72:73], v[92:93], 0, v[72:73]
	v_mov_b32_e32 v76, v175
	s_waitcnt lgkmcnt(0)
	global_store_dwordx4 v[72:73], v[68:71], off nt
.LBB0_381:
	v_add3_u32 v77, v176, v168, s94
	v_add_u32_e32 v78, s59, v77
	v_lshlrev_b32_e32 v68, 6, v78
	v_ashrrev_i32_e32 v69, 31, v68
	v_lshlrev_b64 v[68:69], 2, v[68:69]
	v_lshl_add_u64 v[70:71], v[154:155], 0, v[68:69]
	global_load_dwordx4 v[72:75], v[70:71], off
	v_lshl_add_u64 v[68:69], v[152:153], 0, v[68:69]
	global_load_dwordx4 v[68:71], v[68:69], off
	v_add_u32_e32 v79, 0x80, v179
	v_add_u32_e32 v80, v76, v178
	v_and_b32_e32 v77, 0x4f, v77
	v_ashrrev_i32_e32 v76, 7, v79
	v_lshl_or_b32 v79, v80, 9, v130
	v_cvt_f32_ubyte0_e32 v80, v77
	v_ashrrev_i32_e32 v77, 7, v78
	v_cndmask_b32_e64 v78, v80, -v80, s[6:7]
	v_lshlrev_b32_e32 v148, 1, v79
	v_mul_f32_e32 v79, v177, v78
	v_exp_f32_e32 v79, v79
	v_add_u32_e32 v80, s58, v77
	v_ashrrev_i32_e32 v81, 31, v80
	v_lshlrev_b64 v[80:81], 15, v[80:81]
	v_mul_f32_e32 v82, v64, v79
	v_pk_mul_f32 v[60:61], v[60:61], v[82:83] op_sel_hi:[1,0]
	v_pk_mul_f32 v[62:63], v[62:63], v[82:83] op_sel_hi:[1,0]
	v_pk_mul_f32 v[56:57], v[56:57], v[82:83] op_sel_hi:[1,0]
	v_pk_mul_f32 v[58:59], v[58:59], v[82:83] op_sel_hi:[1,0]
	v_lshl_add_u64 v[80:81], s[56:57], 0, v[80:81]
	v_mov_b32_e32 v125, v149
	v_lshl_add_u64 v[80:81], v[80:81], 0, v[148:149]
	s_and_b64 vcc, exec, s[8:9]
	v_lshl_add_u64 v[80:81], v[80:81], 0, v[124:125]
	s_waitcnt vmcnt(1)
	v_pk_mul_f32 v[82:83], v[58:59], v[74:75]
	v_pk_mul_f32 v[84:85], v[56:57], v[72:73]
	v_pk_mul_f32 v[86:87], v[62:63], v[74:75]
	v_pk_mul_f32 v[88:89], v[60:61], v[72:73]
	s_waitcnt vmcnt(0)
	v_pk_fma_f32 v[62:63], v[62:63], v[70:71], v[82:83] neg_lo:[0,0,1] neg_hi:[0,0,1]
	v_pk_fma_f32 v[60:61], v[60:61], v[68:69], v[84:85] neg_lo:[0,0,1] neg_hi:[0,0,1]
	v_pk_fma_f32 v[82:83], v[58:59], v[70:71], v[86:87]
	v_pk_fma_f32 v[56:57], v[56:57], v[68:69], v[88:89]
	v_cvt_pk_bf16_f32 v58, v60, v61
	v_cvt_pk_bf16_f32 v59, v62, v63
	v_cvt_pk_bf16_f32 v56, v56, v57
	v_cvt_pk_bf16_f32 v57, v82, v83
	global_store_dwordx2 v[80:81], v[58:59], off
	global_store_dwordx2 v[80:81], v[56:57], off offset:2048
	s_cbranch_vccnz .LBB0_383
	ds_write_b16 v169, v58
	ds_write_b16_d16_hi v169, v58 offset:32
	ds_write_b16 v169, v59 offset:64
	ds_write_b16_d16_hi v169, v59 offset:96
	ds_write_b16 v169, v56 offset:512
	ds_write_b16_d16_hi v169, v56 offset:544
	ds_write_b16 v169, v57 offset:576
	ds_write_b16_d16_hi v169, v57 offset:608
	s_waitcnt lgkmcnt(0)
	v_add_u32_e32 v56, v170, v171
	ds_read_b128 v[56:59], v56
	v_add_u32_e32 v60, s58, v76
	v_ashrrev_i32_e32 v61, 31, v60
	v_lshlrev_b64 v[60:61], 15, v[60:61]
	v_lshl_add_u64 v[60:61], v[156:157], 0, v[60:61]
	s_waitcnt lgkmcnt(0)
	global_store_dwordx4 v[60:61], v[56:59], off nt
.LBB0_383:
	s_nop 1
	v_mul_f32_e32 v56, v126, v78
	v_exp_f32_e32 v56, v56
	s_and_b64 vcc, exec, s[8:9]
	v_mul_f32_e32 v56, v64, v56
	v_pk_mul_f32 v[50:51], v[50:51], v[56:57] op_sel_hi:[1,0]
	v_pk_mul_f32 v[54:55], v[54:55], v[56:57] op_sel_hi:[1,0]
	v_pk_mul_f32 v[52:53], v[52:53], v[56:57] op_sel_hi:[1,0]
	v_pk_mul_f32 v[48:49], v[48:49], v[56:57] op_sel_hi:[1,0]
	v_pk_mul_f32 v[56:57], v[50:51], v[74:75]
	v_pk_mul_f32 v[58:59], v[48:49], v[72:73]
	v_pk_fma_f32 v[56:57], v[54:55], v[70:71], v[56:57] neg_lo:[0,0,1] neg_hi:[0,0,1]
	v_pk_mul_f32 v[54:55], v[54:55], v[74:75]
	v_pk_fma_f32 v[58:59], v[52:53], v[68:69], v[58:59] neg_lo:[0,0,1] neg_hi:[0,0,1]
	v_pk_fma_f32 v[54:55], v[50:51], v[70:71], v[54:55]
	v_add_u32_e32 v50, s0, v77
	v_ashrrev_i32_e32 v51, 31, v50
	v_lshlrev_b64 v[50:51], 15, v[50:51]
	v_pk_mul_f32 v[52:53], v[52:53], v[72:73]
	v_lshl_add_u64 v[50:51], s[56:57], 0, v[50:51]
	v_pk_fma_f32 v[48:49], v[48:49], v[68:69], v[52:53]
	v_lshl_add_u64 v[50:51], v[50:51], 0, v[148:149]
	v_lshl_add_u64 v[52:53], v[50:51], 0, v[124:125]
	v_cvt_pk_bf16_f32 v50, v58, v59
	v_cvt_pk_bf16_f32 v51, v56, v57
	v_cvt_pk_bf16_f32 v48, v48, v49
	v_cvt_pk_bf16_f32 v49, v54, v55
	global_store_dwordx2 v[52:53], v[50:51], off
	global_store_dwordx2 v[52:53], v[48:49], off offset:2048
	s_cbranch_vccnz .LBB0_385
	ds_write_b16 v169, v50
	ds_write_b16_d16_hi v169, v50 offset:32
	ds_write_b16 v169, v51 offset:64
	ds_write_b16_d16_hi v169, v51 offset:96
	ds_write_b16 v169, v48 offset:512
	ds_write_b16_d16_hi v169, v48 offset:544
	ds_write_b16 v169, v49 offset:576
	ds_write_b16_d16_hi v169, v49 offset:608
	s_waitcnt lgkmcnt(0)
	v_add_u32_e32 v48, v170, v171
	ds_read_b128 v[48:51], v48
	v_add_u32_e32 v52, s0, v76
	v_ashrrev_i32_e32 v53, 31, v52
	v_lshlrev_b64 v[52:53], 15, v[52:53]
	v_lshl_add_u64 v[52:53], v[156:157], 0, v[52:53]
	s_waitcnt lgkmcnt(0)
	global_store_dwordx4 v[52:53], v[48:51], off nt
; template <int REG>
; DI void epi_inproj(const Params& p, f32x4 (&acc)[2][2][4][2], int pm, int pn, LAS unsigned char* shm) {
;     ...
;       for (int m = 0; m < 4; ++m) { asm volatile("" ::: "memory");
;         const int r = 128 * ai + 64 * wr + 16 * m + fr, t = t0 + r;
;         const float rs = rsr[ai][m];
;         const f32x4 cs = *(const f32x4*)(cosT + t * 64 + 16 * wc + 4 * fq), sn = *(const f32x4*)(sinT + t * 64 + 16 * wc + 4 * fq);
; #pragma unroll
;         for (int bj = 0; bj < 2; ++bj) {
;           const int h = 2 * (pn & 1) + bj;
;           const float sc = fast_exp2((isk ? -1.f : 1.f) * (float)(t & 127) * lg2gamma(h)) * rs;
;           const f32x4 x1 = acc[ai][bj][m][0] * sc, x2 = acc[ai][bj][m][1] * sc;
;           const f32x4 y1 = x1 * cs - x2 * sn, y2 = x2 * cs + x1 * sn;
;           const int d = 16 * wc + 4 * fq;
;           const int tl2 = t & 127, r32 = tl2 & 31;
;           const int frag = isk ? (((tl2 >> 5) * 2 + ((r32 >> 2) & 1)) * 4 + (d >> 5)) : ((tl2 >> 4) * 4 + (d >> 5));
;           const int frl = isk ? ((r32 >> 3) * 4 + (r32 & 3)) : (tl2 & 15);
;           bf16_t* dst = dstb + ((long)((b * 4 + h) * 64 + (t >> 7))) * 16384 + (frag * 64 + ((d >> 3) & 3) * 16 + frl) * 8 + (d & 7);
;           const u32x2 o1 = pk4(y1), o2 = pk4(y2);
;           *(u32x2*)dst = o1; *(u32x2*)(dst + 2 * 512) = o2;
;           if (isk) {
;             LAS unsigned char* tb = shm + 135168 + wid * 1024;
;             LAS bf16_t* w1 = (LAS bf16_t*)(tb + (4 * fq) * 32 + fr * 2);
;             w1[0] = (bf16_t)(o1.x & 0xffff); w1[16] = (bf16_t)(o1.x >> 16); w1[32] = (bf16_t)(o1.y & 0xffff); w1[48] = (bf16_t)(o1.y >> 16);
;             LAS bf16_t* w2 = w1 + 16 * 16;
;             w2[0] = (bf16_t)(o2.x & 0xffff); w2[16] = (bf16_t)(o2.x >> 16); w2[32] = (bf16_t)(o2.y & 0xffff); w2[48] = (bf16_t)(o2.y >> 16);
;             asm volatile("s_waitcnt lgkmcnt(0)" ::: "memory");
;             const int dl = lane >> 1, th = lane & 1;
;             const u32x4 kv = *(const LAS u32x4*)(tb + dl * 32 + th * 16);
;             asm volatile("" ::: "memory");
;             const int dd = dl < 16 ? 16 * wc + dl : 48 + 16 * wc + dl;
;             const int tb0 = t0 + 128 * ai + 64 * wr + 16 * m + 8 * th, tl = tb0 & 127;
;             *(u32x4*)(krt + ((long)((b * 4 + h) * 64 + (tb0 >> 7))) * 16384 + (((dd >> 4) * 4 + (tl >> 5)) * 64 + ((tl >> 3) & 3) * 16 + (dd & 15)) * 8) = kv;
.LBB0_385:
	v_add_u32_e32 v56, 0x90, v176
	v_or_b32_e32 v57, v56, v168
	v_add_u32_e32 v58, s59, v57
	v_lshlrev_b32_e32 v48, 6, v58
	v_ashrrev_i32_e32 v49, 31, v48
	v_lshlrev_b64 v[48:49], 2, v[48:49]
	v_lshl_add_u64 v[50:51], v[154:155], 0, v[48:49]
	global_load_dwordx4 v[52:55], v[50:51], off
	v_lshl_add_u64 v[48:49], v[152:153], 0, v[48:49]
	global_load_dwordx4 v[48:51], v[48:49], off
	v_bitop3_b32 v59, v56, s91, v168 bitop3:0xc8
	v_lshrrev_b32_e32 v56, 2, v56
	v_cvt_f32_ubyte0_e32 v59, v59
	v_lshrrev_b32_e32 v60, 1, v57
	v_and_or_b32 v61, v56, 20, v174
	v_and_or_b32 v62, v56, 16, v175
	v_cndmask_b32_e64 v57, v59, -v59, s[6:7]
	v_and_or_b32 v59, v60, 12, v173
	v_cndmask_b32_e64 v60, v61, v62, s[6:7]
	v_mul_f32_e32 v61, v177, v57
	v_exp_f32_e32 v61, v61
	v_cndmask_b32_e64 v59, v168, v59, s[6:7]
	v_ashrrev_i32_e32 v56, 7, v58
	v_lshlrev_b32_e32 v60, 9, v60
	v_or_b32_e32 v62, v59, v172
	v_add_u32_e32 v58, s58, v56
	v_lshl_or_b32 v60, v62, 3, v60
	v_ashrrev_i32_e32 v59, 31, v58
	v_lshlrev_b32_e32 v148, 1, v60
	v_mul_f32_e32 v60, v65, v61
	v_lshlrev_b64 v[58:59], 15, v[58:59]
	v_pk_mul_f32 v[46:47], v[46:47], v[60:61] op_sel_hi:[1,0]
	v_pk_mul_f32 v[44:45], v[44:45], v[60:61] op_sel_hi:[1,0]
	v_pk_mul_f32 v[42:43], v[42:43], v[60:61] op_sel_hi:[1,0]
	v_pk_mul_f32 v[40:41], v[40:41], v[60:61] op_sel_hi:[1,0]
	v_lshl_add_u64 v[58:59], s[56:57], 0, v[58:59]
	v_mov_b32_e32 v125, v149
	v_lshl_add_u64 v[58:59], v[58:59], 0, v[148:149]
	s_and_b64 vcc, exec, s[8:9]
	v_lshl_add_u64 v[58:59], v[58:59], 0, v[124:125]
	s_waitcnt vmcnt(1)
	v_pk_mul_f32 v[60:61], v[42:43], v[54:55]
	v_pk_mul_f32 v[62:63], v[40:41], v[52:53]
	v_pk_mul_f32 v[68:69], v[46:47], v[54:55]
	v_pk_mul_f32 v[70:71], v[44:45], v[52:53]
	s_waitcnt vmcnt(0)
	v_pk_fma_f32 v[46:47], v[46:47], v[50:51], v[60:61] neg_lo:[0,0,1] neg_hi:[0,0,1]
	v_pk_fma_f32 v[44:45], v[44:45], v[48:49], v[62:63] neg_lo:[0,0,1] neg_hi:[0,0,1]
	v_pk_fma_f32 v[60:61], v[42:43], v[50:51], v[68:69]
	v_pk_fma_f32 v[40:41], v[40:41], v[48:49], v[70:71]
	v_cvt_pk_bf16_f32 v42, v44, v45
	v_cvt_pk_bf16_f32 v43, v46, v47
	v_cvt_pk_bf16_f32 v40, v40, v41
	v_cvt_pk_bf16_f32 v41, v60, v61
	global_store_dwordx2 v[58:59], v[42:43], off
	global_store_dwordx2 v[58:59], v[40:41], off offset:2048
	s_cbranch_vccnz .LBB0_387
	ds_write_b16 v169, v42
	ds_write_b16_d16_hi v169, v42 offset:32
	ds_write_b16 v169, v43 offset:64
	ds_write_b16_d16_hi v169, v43 offset:96
	ds_write_b16 v169, v40 offset:512
	ds_write_b16_d16_hi v169, v40 offset:544
	ds_write_b16 v169, v41 offset:576
	ds_write_b16_d16_hi v169, v41 offset:608
	s_waitcnt lgkmcnt(0)
	v_add_u32_e32 v40, v170, v171
	ds_read_b128 v[40:43], v40
	v_add_u32_e32 v44, s58, v76
	v_ashrrev_i32_e32 v45, 31, v44
	v_lshlrev_b64 v[44:45], 15, v[44:45]
	v_lshl_add_u64 v[44:45], v[156:157], 0, v[44:45]
	s_waitcnt lgkmcnt(0)
	global_store_dwordx4 v[44:45], v[40:43], off offset:512 nt
.LBB0_387:
	s_nop 1
	v_mul_f32_e32 v40, v126, v57
	v_exp_f32_e32 v40, v40
	s_and_b64 vcc, exec, s[8:9]
	v_mul_f32_e32 v40, v65, v40
	v_pk_mul_f32 v[34:35], v[34:35], v[40:41] op_sel_hi:[1,0]
	v_pk_mul_f32 v[38:39], v[38:39], v[40:41] op_sel_hi:[1,0]
	v_pk_mul_f32 v[36:37], v[36:37], v[40:41] op_sel_hi:[1,0]
	v_pk_mul_f32 v[32:33], v[32:33], v[40:41] op_sel_hi:[1,0]
	v_pk_mul_f32 v[40:41], v[34:35], v[54:55]
	v_pk_mul_f32 v[42:43], v[32:33], v[52:53]
	v_pk_fma_f32 v[40:41], v[38:39], v[50:51], v[40:41] neg_lo:[0,0,1] neg_hi:[0,0,1]
	v_pk_mul_f32 v[38:39], v[38:39], v[54:55]
	v_pk_fma_f32 v[42:43], v[36:37], v[48:49], v[42:43] neg_lo:[0,0,1] neg_hi:[0,0,1]
	v_pk_fma_f32 v[38:39], v[34:35], v[50:51], v[38:39]
	v_add_u32_e32 v34, s0, v56
	v_ashrrev_i32_e32 v35, 31, v34
	v_lshlrev_b64 v[34:35], 15, v[34:35]
	v_pk_mul_f32 v[36:37], v[36:37], v[52:53]
	v_lshl_add_u64 v[34:35], s[56:57], 0, v[34:35]
	v_pk_fma_f32 v[32:33], v[32:33], v[48:49], v[36:37]
	v_lshl_add_u64 v[34:35], v[34:35], 0, v[148:149]
	v_lshl_add_u64 v[36:37], v[34:35], 0, v[124:125]
	v_cvt_pk_bf16_f32 v34, v42, v43
	v_cvt_pk_bf16_f32 v35, v40, v41
	v_cvt_pk_bf16_f32 v32, v32, v33
	v_cvt_pk_bf16_f32 v33, v38, v39
	v_mov_b32_e32 v40, v174
	global_store_dwordx2 v[36:37], v[34:35], off
	global_store_dwordx2 v[36:37], v[32:33], off offset:2048
	s_cbranch_vccnz .LBB0_389
	ds_write_b16 v169, v34
	ds_write_b16_d16_hi v169, v34 offset:32
	ds_write_b16 v169, v35 offset:64
	ds_write_b16_d16_hi v169, v35 offset:96
	ds_write_b16 v169, v32 offset:512
	ds_write_b16_d16_hi v169, v32 offset:544
	ds_write_b16 v169, v33 offset:576
	ds_write_b16_d16_hi v169, v33 offset:608
	s_waitcnt lgkmcnt(0)
	v_add_u32_e32 v32, v170, v171
	ds_read_b128 v[32:35], v32
	v_add_u32_e32 v36, s0, v76
	v_ashrrev_i32_e32 v37, 31, v36
	v_lshlrev_b64 v[36:37], 15, v[36:37]
	v_lshl_add_u64 v[36:37], v[156:157], 0, v[36:37]
	v_mov_b32_e32 v40, v175
	s_waitcnt lgkmcnt(0)
	global_store_dwordx4 v[36:37], v[32:35], off offset:512 nt
; template <int REG>
; DI void epi_inproj(const Params& p, f32x4 (&acc)[2][2][4][2], int pm, int pn, LAS unsigned char* shm) {
;     ...
;       for (int m = 0; m < 4; ++m) { asm volatile("" ::: "memory");
;         const int r = 128 * ai + 64 * wr + 16 * m + fr, t = t0 + r;
;         const float rs = rsr[ai][m];
;         const f32x4 cs = *(const f32x4*)(cosT + t * 64 + 16 * wc + 4 * fq), sn = *(const f32x4*)(sinT + t * 64 + 16 * wc + 4 * fq);
; #pragma unroll
;         for (int bj = 0; bj < 2; ++bj) {
;           const int h = 2 * (pn & 1) + bj;
;           const float sc = fast_exp2((isk ? -1.f : 1.f) * (float)(t & 127) * lg2gamma(h)) * rs;
;           const f32x4 x1 = acc[ai][bj][m][0] * sc, x2 = acc[ai][bj][m][1] * sc;
;           const f32x4 y1 = x1 * cs - x2 * sn, y2 = x2 * cs + x1 * sn;
;           const int d = 16 * wc + 4 * fq;
;           const int tl2 = t & 127, r32 = tl2 & 31;
;           const int frag = isk ? (((tl2 >> 5) * 2 + ((r32 >> 2) & 1)) * 4 + (d >> 5)) : ((tl2 >> 4) * 4 + (d >> 5));
;           const int frl = isk ? ((r32 >> 3) * 4 + (r32 & 3)) : (tl2 & 15);
;           bf16_t* dst = dstb + ((long)((b * 4 + h) * 64 + (t >> 7))) * 16384 + (frag * 64 + ((d >> 3) & 3) * 16 + frl) * 8 + (d & 7);
;           const u32x2 o1 = pk4(y1), o2 = pk4(y2);
;           *(u32x2*)dst = o1; *(u32x2*)(dst + 2 * 512) = o2;
;           if (isk) {
;             LAS unsigned char* tb = shm + 135168 + wid * 1024;
;             LAS bf16_t* w1 = (LAS bf16_t*)(tb + (4 * fq) * 32 + fr * 2);
;             w1[0] = (bf16_t)(o1.x & 0xffff); w1[16] = (bf16_t)(o1.x >> 16); w1[32] = (bf16_t)(o1.y & 0xffff); w1[48] = (bf16_t)(o1.y >> 16);
;             LAS bf16_t* w2 = w1 + 16 * 16;
;             w2[0] = (bf16_t)(o2.x & 0xffff); w2[16] = (bf16_t)(o2.x >> 16); w2[32] = (bf16_t)(o2.y & 0xffff); w2[48] = (bf16_t)(o2.y >> 16);
;             asm volatile("s_waitcnt lgkmcnt(0)" ::: "memory");
;             const int dl = lane >> 1, th = lane & 1;
;             const u32x4 kv = *(const LAS u32x4*)(tb + dl * 32 + th * 16);
;             asm volatile("" ::: "memory");
;             const int dd = dl < 16 ? 16 * wc + dl : 48 + 16 * wc + dl;
;             const int tb0 = t0 + 128 * ai + 64 * wr + 16 * m + 8 * th, tl = tb0 & 127;
;             *(u32x4*)(krt + ((long)((b * 4 + h) * 64 + (tb0 >> 7))) * 16384 + (((dd >> 4) * 4 + (tl >> 5)) * 64 + ((tl >> 3) & 3) * 16 + (dd & 15)) * 8) = kv;
.LBB0_389:
	v_add_u32_e32 v41, 0xa0, v176
	s_nop 0
	v_or_b32_e32 v32, v41, v168
	v_add_u32_e32 v42, s59, v32
	v_lshlrev_b32_e32 v32, 6, v42
	v_ashrrev_i32_e32 v33, 31, v32
	v_lshlrev_b64 v[32:33], 2, v[32:33]
	v_lshl_add_u64 v[34:35], v[154:155], 0, v[32:33]
	global_load_dwordx4 v[36:39], v[34:35], off
	v_lshl_add_u64 v[32:33], v[152:153], 0, v[32:33]
	global_load_dwordx4 v[32:35], v[32:33], off
	v_bitop3_b32 v43, v41, s92, v168 bitop3:0xc8
	v_lshrrev_b32_e32 v41, 2, v41
	v_cvt_f32_ubyte0_e32 v43, v43
	v_and_or_b32 v44, v41, 24, v40
	v_cndmask_b32_e64 v41, v43, -v43, s[6:7]
	v_lshl_or_b32 v43, v44, 9, v130
	v_mul_f32_e32 v44, v177, v41
	v_exp_f32_e32 v44, v44
	v_ashrrev_i32_e32 v40, 7, v42
	v_add_u32_e32 v42, s58, v40
	v_lshlrev_b32_e32 v148, 1, v43
	v_ashrrev_i32_e32 v43, 31, v42
	v_mul_f32_e32 v44, v66, v44
	v_lshlrev_b64 v[42:43], 15, v[42:43]
	v_pk_mul_f32 v[30:31], v[30:31], v[44:45] op_sel_hi:[1,0]
	v_pk_mul_f32 v[28:29], v[28:29], v[44:45] op_sel_hi:[1,0]
	v_pk_mul_f32 v[26:27], v[26:27], v[44:45] op_sel_hi:[1,0]
	v_pk_mul_f32 v[24:25], v[24:25], v[44:45] op_sel_hi:[1,0]
	v_lshl_add_u64 v[42:43], s[56:57], 0, v[42:43]
	v_mov_b32_e32 v125, v149
	v_lshl_add_u64 v[42:43], v[42:43], 0, v[148:149]
	s_and_b64 vcc, exec, s[8:9]
	v_lshl_add_u64 v[42:43], v[42:43], 0, v[124:125]
	s_waitcnt vmcnt(1)
	v_pk_mul_f32 v[44:45], v[26:27], v[38:39]
	v_pk_mul_f32 v[46:47], v[24:25], v[36:37]
	v_pk_mul_f32 v[48:49], v[30:31], v[38:39]
	v_pk_mul_f32 v[50:51], v[28:29], v[36:37]
	s_waitcnt vmcnt(0)
	v_pk_fma_f32 v[30:31], v[30:31], v[34:35], v[44:45] neg_lo:[0,0,1] neg_hi:[0,0,1]
	v_pk_fma_f32 v[28:29], v[28:29], v[32:33], v[46:47] neg_lo:[0,0,1] neg_hi:[0,0,1]
	v_pk_fma_f32 v[44:45], v[26:27], v[34:35], v[48:49]
	v_pk_fma_f32 v[24:25], v[24:25], v[32:33], v[50:51]
	v_cvt_pk_bf16_f32 v26, v28, v29
	v_cvt_pk_bf16_f32 v27, v30, v31
	v_cvt_pk_bf16_f32 v24, v24, v25
	v_cvt_pk_bf16_f32 v25, v44, v45
	global_store_dwordx2 v[42:43], v[26:27], off
	global_store_dwordx2 v[42:43], v[24:25], off offset:2048
	s_cbranch_vccnz .LBB0_391
	ds_write_b16 v169, v26
	ds_write_b16_d16_hi v169, v26 offset:32
	ds_write_b16 v169, v27 offset:64
	ds_write_b16_d16_hi v169, v27 offset:96
	ds_write_b16 v169, v24 offset:512
	ds_write_b16_d16_hi v169, v24 offset:544
	ds_write_b16 v169, v25 offset:576
	ds_write_b16_d16_hi v169, v25 offset:608
	s_waitcnt lgkmcnt(0)
	v_add_u32_e32 v24, v170, v171
	ds_read_b128 v[24:27], v24
	v_add_u32_e32 v28, s58, v76
	v_ashrrev_i32_e32 v29, 31, v28
	v_lshlrev_b64 v[28:29], 15, v[28:29]
	v_lshl_add_u64 v[28:29], v[108:109], 0, v[28:29]
	s_waitcnt lgkmcnt(0)
	global_store_dwordx4 v[28:29], v[24:27], off nt
.LBB0_391:
	s_nop 1
	v_mul_f32_e32 v24, v126, v41
	v_exp_f32_e32 v24, v24
	s_and_b64 vcc, exec, s[8:9]
	v_mul_f32_e32 v24, v66, v24
	v_pk_mul_f32 v[18:19], v[18:19], v[24:25] op_sel_hi:[1,0]
	v_pk_mul_f32 v[22:23], v[22:23], v[24:25] op_sel_hi:[1,0]
	v_pk_mul_f32 v[20:21], v[20:21], v[24:25] op_sel_hi:[1,0]
	v_pk_mul_f32 v[16:17], v[16:17], v[24:25] op_sel_hi:[1,0]
	v_pk_mul_f32 v[24:25], v[18:19], v[38:39]
	v_pk_mul_f32 v[26:27], v[16:17], v[36:37]
	v_pk_fma_f32 v[24:25], v[22:23], v[34:35], v[24:25] neg_lo:[0,0,1] neg_hi:[0,0,1]
	v_pk_mul_f32 v[22:23], v[22:23], v[38:39]
	v_pk_fma_f32 v[26:27], v[20:21], v[32:33], v[26:27] neg_lo:[0,0,1] neg_hi:[0,0,1]
	v_pk_fma_f32 v[22:23], v[18:19], v[34:35], v[22:23]
	v_add_u32_e32 v18, s0, v40
	v_ashrrev_i32_e32 v19, 31, v18
	v_lshlrev_b64 v[18:19], 15, v[18:19]
	v_pk_mul_f32 v[20:21], v[20:21], v[36:37]
	v_lshl_add_u64 v[18:19], s[56:57], 0, v[18:19]
	v_pk_fma_f32 v[16:17], v[16:17], v[32:33], v[20:21]
	v_lshl_add_u64 v[18:19], v[18:19], 0, v[148:149]
	v_lshl_add_u64 v[20:21], v[18:19], 0, v[124:125]
	v_cvt_pk_bf16_f32 v18, v26, v27
	v_cvt_pk_bf16_f32 v19, v24, v25
	v_cvt_pk_bf16_f32 v16, v16, v17
	v_cvt_pk_bf16_f32 v17, v22, v23
	global_store_dwordx2 v[20:21], v[18:19], off
	global_store_dwordx2 v[20:21], v[16:17], off offset:2048
	s_cbranch_vccnz .LBB0_393
	ds_write_b16 v169, v18
	ds_write_b16_d16_hi v169, v18 offset:32
	ds_write_b16 v169, v19 offset:64
	ds_write_b16_d16_hi v169, v19 offset:96
	ds_write_b16 v169, v16 offset:512
	ds_write_b16_d16_hi v169, v16 offset:544
	ds_write_b16 v169, v17 offset:576
	ds_write_b16_d16_hi v169, v17 offset:608
	s_waitcnt lgkmcnt(0)
	v_add_u32_e32 v16, v170, v171
	ds_read_b128 v[16:19], v16
	v_add_u32_e32 v20, s0, v76
	v_ashrrev_i32_e32 v21, 31, v20
	v_lshlrev_b64 v[20:21], 15, v[20:21]
	v_lshl_add_u64 v[20:21], v[108:109], 0, v[20:21]
	s_waitcnt lgkmcnt(0)
	global_store_dwordx4 v[20:21], v[16:19], off nt
; template <int REG>
; DI void epi_inproj(const Params& p, f32x4 (&acc)[2][2][4][2], int pm, int pn, LAS unsigned char* shm) {
;     ...
;       for (int m = 0; m < 4; ++m) { asm volatile("" ::: "memory");
;         const int r = 128 * ai + 64 * wr + 16 * m + fr, t = t0 + r;
;         const float rs = rsr[ai][m];
;         const f32x4 cs = *(const f32x4*)(cosT + t * 64 + 16 * wc + 4 * fq), sn = *(const f32x4*)(sinT + t * 64 + 16 * wc + 4 * fq);
; #pragma unroll
;         for (int bj = 0; bj < 2; ++bj) {
;           const int h = 2 * (pn & 1) + bj;
;           const float sc = fast_exp2((isk ? -1.f : 1.f) * (float)(t & 127) * lg2gamma(h)) * rs;
;           const f32x4 x1 = acc[ai][bj][m][0] * sc, x2 = acc[ai][bj][m][1] * sc;
;           const f32x4 y1 = x1 * cs - x2 * sn, y2 = x2 * cs + x1 * sn;
;           const int d = 16 * wc + 4 * fq;
;           const int tl2 = t & 127, r32 = tl2 & 31;
;           const int frag = isk ? (((tl2 >> 5) * 2 + ((r32 >> 2) & 1)) * 4 + (d >> 5)) : ((tl2 >> 4) * 4 + (d >> 5));
;           const int frl = isk ? ((r32 >> 3) * 4 + (r32 & 3)) : (tl2 & 15);
;           bf16_t* dst = dstb + ((long)((b * 4 + h) * 64 + (t >> 7))) * 16384 + (frag * 64 + ((d >> 3) & 3) * 16 + frl) * 8 + (d & 7);
;           const u32x2 o1 = pk4(y1), o2 = pk4(y2);
;           *(u32x2*)dst = o1; *(u32x2*)(dst + 2 * 512) = o2;
;           if (isk) {
;             LAS unsigned char* tb = shm + 135168 + wid * 1024;
;             LAS bf16_t* w1 = (LAS bf16_t*)(tb + (4 * fq) * 32 + fr * 2);
;             w1[0] = (bf16_t)(o1.x & 0xffff); w1[16] = (bf16_t)(o1.x >> 16); w1[32] = (bf16_t)(o1.y & 0xffff); w1[48] = (bf16_t)(o1.y >> 16);
;             LAS bf16_t* w2 = w1 + 16 * 16;
;             w2[0] = (bf16_t)(o2.x & 0xffff); w2[16] = (bf16_t)(o2.x >> 16); w2[32] = (bf16_t)(o2.y & 0xffff); w2[48] = (bf16_t)(o2.y >> 16);
;             asm volatile("s_waitcnt lgkmcnt(0)" ::: "memory");
;             const int dl = lane >> 1, th = lane & 1;
;             const u32x4 kv = *(const LAS u32x4*)(tb + dl * 32 + th * 16);
;             asm volatile("" ::: "memory");
;             const int dd = dl < 16 ? 16 * wc + dl : 48 + 16 * wc + dl;
;             const int tb0 = t0 + 128 * ai + 64 * wr + 16 * m + 8 * th, tl = tb0 & 127;
;             *(u32x4*)(krt + ((long)((b * 4 + h) * 64 + (tb0 >> 7))) * 16384 + (((dd >> 4) * 4 + (tl >> 5)) * 64 + ((tl >> 3) & 3) * 16 + (dd & 15)) * 8) = kv;
.LBB0_393:
	v_add_u32_e32 v24, 0xb0, v176
	v_or_b32_e32 v25, v24, v168
	v_add_u32_e32 v26, s59, v25
	v_lshlrev_b32_e32 v16, 6, v26
	v_ashrrev_i32_e32 v17, 31, v16
	v_lshlrev_b64 v[16:17], 2, v[16:17]
	v_lshl_add_u64 v[18:19], v[154:155], 0, v[16:17]
	global_load_dwordx4 v[20:23], v[18:19], off
	v_lshl_add_u64 v[16:17], v[152:153], 0, v[16:17]
	global_load_dwordx4 v[16:19], v[16:17], off
	v_bitop3_b32 v27, v24, s93, v168 bitop3:0xc8
	v_lshrrev_b32_e32 v24, 2, v24
	v_cvt_f32_ubyte0_e32 v27, v27
	v_lshrrev_b32_e32 v28, 1, v25
	v_and_or_b32 v29, v24, 28, v174
	v_and_or_b32 v30, v24, 24, v175
	v_cndmask_b32_e64 v25, v27, -v27, s[6:7]
	v_and_or_b32 v27, v28, 12, v173
	v_cndmask_b32_e64 v28, v29, v30, s[6:7]
	v_mul_f32_e32 v29, v177, v25
	v_exp_f32_e32 v29, v29
	v_cndmask_b32_e64 v27, v168, v27, s[6:7]
	v_ashrrev_i32_e32 v24, 7, v26
	v_lshlrev_b32_e32 v28, 9, v28
	v_or_b32_e32 v30, v27, v172
	v_add_u32_e32 v26, s58, v24
	v_lshl_or_b32 v28, v30, 3, v28
	v_ashrrev_i32_e32 v27, 31, v26
	v_lshlrev_b32_e32 v148, 1, v28
	v_mul_f32_e32 v28, v67, v29
	v_lshlrev_b64 v[26:27], 15, v[26:27]
	v_pk_mul_f32 v[14:15], v[14:15], v[28:29] op_sel_hi:[1,0]
	v_pk_mul_f32 v[12:13], v[12:13], v[28:29] op_sel_hi:[1,0]
	v_pk_mul_f32 v[10:11], v[10:11], v[28:29] op_sel_hi:[1,0]
	v_pk_mul_f32 v[8:9], v[8:9], v[28:29] op_sel_hi:[1,0]
	v_lshl_add_u64 v[26:27], s[56:57], 0, v[26:27]
	v_mov_b32_e32 v125, v149
	v_lshl_add_u64 v[26:27], v[26:27], 0, v[148:149]
	s_and_b64 vcc, exec, s[8:9]
	v_lshl_add_u64 v[26:27], v[26:27], 0, v[124:125]
	s_waitcnt vmcnt(1)
	v_pk_mul_f32 v[28:29], v[10:11], v[22:23]
	v_pk_mul_f32 v[30:31], v[8:9], v[20:21]
	v_pk_mul_f32 v[32:33], v[14:15], v[22:23]
	v_pk_mul_f32 v[34:35], v[12:13], v[20:21]
	s_waitcnt vmcnt(0)
	v_pk_fma_f32 v[14:15], v[14:15], v[18:19], v[28:29] neg_lo:[0,0,1] neg_hi:[0,0,1]
	v_pk_fma_f32 v[12:13], v[12:13], v[16:17], v[30:31] neg_lo:[0,0,1] neg_hi:[0,0,1]
	v_pk_fma_f32 v[28:29], v[10:11], v[18:19], v[32:33]
	v_pk_fma_f32 v[8:9], v[8:9], v[16:17], v[34:35]
	v_cvt_pk_bf16_f32 v10, v12, v13
	v_cvt_pk_bf16_f32 v11, v14, v15
	v_cvt_pk_bf16_f32 v8, v8, v9
	v_cvt_pk_bf16_f32 v9, v28, v29
	global_store_dwordx2 v[26:27], v[10:11], off
	global_store_dwordx2 v[26:27], v[8:9], off offset:2048
	s_cbranch_vccnz .LBB0_395
	ds_write_b16 v169, v10
	ds_write_b16_d16_hi v169, v10 offset:32
	ds_write_b16 v169, v11 offset:64
	ds_write_b16_d16_hi v169, v11 offset:96
	ds_write_b16 v169, v8 offset:512
	ds_write_b16_d16_hi v169, v8 offset:544
	ds_write_b16 v169, v9 offset:576
	ds_write_b16_d16_hi v169, v9 offset:608
	s_waitcnt lgkmcnt(0)
	v_add_u32_e32 v8, v170, v171
	ds_read_b128 v[8:11], v8
	v_add_u32_e32 v12, s58, v76
	v_ashrrev_i32_e32 v13, 31, v12
	v_lshlrev_b64 v[12:13], 15, v[12:13]
	v_lshl_add_u64 v[12:13], v[92:93], 0, v[12:13]
	s_waitcnt lgkmcnt(0)
	global_store_dwordx4 v[12:13], v[8:11], off nt
.LBB0_395:
	s_nop 1
	v_mul_f32_e32 v8, v126, v25
	v_exp_f32_e32 v8, v8
	s_and_b64 vcc, exec, s[8:9]
	v_mul_f32_e32 v8, v67, v8
	v_pk_mul_f32 v[2:3], v[2:3], v[8:9] op_sel_hi:[1,0]
	v_pk_mul_f32 v[6:7], v[6:7], v[8:9] op_sel_hi:[1,0]
	v_pk_mul_f32 v[4:5], v[4:5], v[8:9] op_sel_hi:[1,0]
	v_pk_mul_f32 v[0:1], v[0:1], v[8:9] op_sel_hi:[1,0]
	v_pk_mul_f32 v[8:9], v[2:3], v[22:23]
	v_pk_mul_f32 v[10:11], v[0:1], v[20:21]
	v_pk_fma_f32 v[8:9], v[6:7], v[18:19], v[8:9] neg_lo:[0,0,1] neg_hi:[0,0,1]
	v_pk_mul_f32 v[6:7], v[6:7], v[22:23]
	v_pk_fma_f32 v[10:11], v[4:5], v[16:17], v[10:11] neg_lo:[0,0,1] neg_hi:[0,0,1]
	v_pk_fma_f32 v[6:7], v[2:3], v[18:19], v[6:7]
	v_add_u32_e32 v2, s0, v24
	v_ashrrev_i32_e32 v3, 31, v2
	v_lshlrev_b64 v[2:3], 15, v[2:3]
	v_pk_mul_f32 v[4:5], v[4:5], v[20:21]
	v_lshl_add_u64 v[2:3], s[56:57], 0, v[2:3]
	v_pk_fma_f32 v[0:1], v[0:1], v[16:17], v[4:5]
	v_lshl_add_u64 v[2:3], v[2:3], 0, v[148:149]
	v_lshl_add_u64 v[4:5], v[2:3], 0, v[124:125]
	v_cvt_pk_bf16_f32 v2, v10, v11
	v_cvt_pk_bf16_f32 v3, v8, v9
	v_cvt_pk_bf16_f32 v0, v0, v1
	v_cvt_pk_bf16_f32 v1, v6, v7
	global_store_dwordx2 v[4:5], v[2:3], off
	global_store_dwordx2 v[4:5], v[0:1], off offset:2048
	s_cbranch_vccnz .LBB0_397
	ds_write_b16 v169, v2
	ds_write_b16_d16_hi v169, v2 offset:32
	ds_write_b16 v169, v3 offset:64
	ds_write_b16_d16_hi v169, v3 offset:96
	ds_write_b16 v169, v0 offset:512
	ds_write_b16_d16_hi v169, v0 offset:544
	ds_write_b16 v169, v1 offset:576
	ds_write_b16_d16_hi v169, v1 offset:608
	s_waitcnt lgkmcnt(0)
	v_add_u32_e32 v0, v170, v171
	ds_read_b128 v[0:3], v0
	v_add_u32_e32 v4, s0, v76
	v_ashrrev_i32_e32 v5, 31, v4
	v_lshlrev_b64 v[4:5], 15, v[4:5]
	v_lshl_add_u64 v[4:5], v[92:93], 0, v[4:5]
	s_waitcnt lgkmcnt(0)
	global_store_dwordx4 v[4:5], v[0:3], off nt

; template <int REG>
; DI void epi_inproj(const Params& p, f32x4 (&acc)[2][2][4][2], int pm, int pn, LAS unsigned char* shm) {
;     ...
;     const f32x4 q0 = *(const f32x4*)((const float*)(ws + OFF_RSTD1Q) + T0 + (wr * 16 + fr) * 8), q1 = *(const f32x4*)((const float*)(ws + OFF_RSTD1Q) + T0 + (wr * 16 + fr) * 8 + 4);
; #pragma unroll
;     for (int m = 0; m < 4; ++m) { rsr[0][m] = q0[m]; rsr[1][m] = q1[m]; }
;     ...
;     const float* nw = isk ? p.k_norm_w : p.q_norm_w;
;     bf16_t* dstb = (bf16_t*)(ws + (isk ? OFF_MK : OFF_MQ));
;     const int hh = (pn & 1) * 4 + wc;
;     f32x4 w4[2][2], cs4[2][2];
; #pragma unroll
;     for (int bj = 0; bj < 2; ++bj)
; #pragma unroll
;       for (int n = 0; n < 2; ++n) { w4[bj][n] = *(const f32x4*)(nw + 32 * bj + 8 * fq + 4 * n); cs4[bj][n] = (f32x4){0.f, 0.f, 0.f, 0.f}; }
; #pragma unroll
;     for (int ai = 0; ai < 2; ++ai)
; #pragma unroll
;       for (int m = 0; m < 4; ++m) { asm volatile("" ::: "memory");
;         const int r = 128 * ai + 64 * wr + 16 * m + fr, t = t0 + r;
;         const float rs = rsr[ai][m];
;         f32x4 v[2][2]; float ss = 0.f;
; #pragma unroll
;         for (int bj = 0; bj < 2; ++bj)
; #pragma unroll
;           for (int n = 0; n < 2; ++n) { v[bj][n] = acc[ai][bj][m][n] * rs; ss += v[bj][n][0] * v[bj][n][0] + v[bj][n][1] * v[bj][n][1] + v[bj][n][2] * v[bj][n][2] + v[bj][n][3] * v[bj][n][3]; }
;         ss += __shfl_xor(ss, 16); ss += __shfl_xor(ss, 32);
;         const float rn = __builtin_amdgcn_rsqf(ss * (1.0f / 64.0f) + 1e-6f) * (isk ? 1.0f : 0.125f * 1.4426950408889634f);
.LBB0_435:
	v_mov_b32_e32 v168, v194
	s_lshl_b32 s48, s22, 8
	s_ashr_i32 s49, s48, 31
	v_and_b32_e32 v170, 15, v168
	s_and_b32 s46, s22, 31
	v_ashrrev_i32_e32 v175, 8, v168
	s_lshl_b64 s[48:49], s[48:49], 2
	v_lshlrev_b32_e32 v112, 3, v170
	s_add_u32 s48, s65, s48
	v_lshl_or_b32 v112, v175, 7, v112
	s_addc_u32 s49, s67, s49
	v_ashrrev_i32_e32 v113, 31, v112
	v_lshl_add_u64 v[112:113], v[112:113], 2, s[48:49]
	global_load_dwordx4 v[148:151], v[112:113], off
	s_nop 0
	global_load_dwordx4 v[112:115], v[112:113], off offset:16
	s_lshl_b32 s23, s40, 2
	s_cmp_gt_i32 s40, 13
	s_cselect_b64 s[48:49], -1, 0
	v_bfe_u32 v118, v168, 4, 2
	v_cndmask_b32_e64 v174, v167, 1.0, s[48:49]
	s_and_b64 s[48:49], s[48:49], exec
	v_lshlrev_b32_e32 v171, 5, v118
	s_cselect_b32 s48, s44, s42
	s_cselect_b32 s49, s45, s43
	global_load_dwordx4 v[124:127], v171, s[48:49] offset:16
	global_load_dwordx4 v[132:135], v171, s[48:49]
	v_and_b32_e32 v117, 64, v165
	v_xor_b32_e32 v116, 16, v165
	v_add_u32_e32 v172, 64, v117
	v_cmp_lt_i32_e32 vcc, v116, v172
	v_xor_b32_e32 v173, 32, v165
	v_lshlrev_b32_e32 v195, 6, v175
	v_cndmask_b32_e32 v176, v165, v116, vcc
	global_load_dwordx4 v[116:119], v171, s[48:49] offset:144
	global_load_dwordx4 v[128:131], v171, s[48:49] offset:128
	v_lshlrev_b32_e32 v176, 2, v176
	v_cmp_lt_i32_e32 vcc, v173, v172
	s_cselect_b32 s47, s76, 0x10300000
	s_add_u32 s48, s26, s47
	v_cndmask_b32_e32 v177, v165, v173, vcc
	v_lshlrev_b32_e32 v175, 2, v177
	s_addc_u32 s49, s27, 0
	s_ashr_i32 s22, s22, 2
	v_ashrrev_i32_e32 v169, 6, v168
	s_and_b32 s23, s23, 4
	s_and_b32 s22, s22, -8
	v_and_b32_e32 v173, 3, v169
	s_or_b32 s47, s22, s23
	v_lshl_or_b32 v196, s46, 8, v170
	v_and_b32_e32 v156, 48, v168
	s_cmp_gt_i32 s40, 13
	s_cselect_b32 s100, 0x3c0, 0
	s_mov_b32 s101, 0
	s_cselect_b64 s[98:99], -1, 0
	v_bfe_u32 v238, v170, 2, 1
	v_mul_u32_u24_e32 v238, 0x600, v238
	v_mad_u32_u24 v238, v156, 15, v238
	v_lshrrev_b32_e32 v240, 3, v170
	v_mul_u32_u24_e32 v240, 0x3c0, v240
	v_sub_u32_e32 v238, v238, v240
	v_and_b32_e32 v240, 3, v170
	v_mul_u32_u24_e32 v240, 0x70, v240
	v_sub_u32_e32 v238, v238, v240
	v_add_u32_e32 v240, 0xfffff880, v238
	v_cndmask_b32_e64 v238, 0, v238, s[98:99]
	v_cndmask_b32_e64 v240, 0, v240, s[98:99]
	v_ashrrev_i32_e32 v239, 31, v238
	v_ashrrev_i32_e32 v241, 31, v240
	s_cmp_lt_i32 s40, 14
	s_waitcnt vmcnt(0)
	v_pk_mul_f32 v[178:179], v[144:145], v[148:149] op_sel_hi:[1,0]
	v_pk_mul_f32 v[140:141], v[140:141], v[148:149] op_sel_hi:[1,0]
	v_pk_mul_f32 v[136:137], v[136:137], v[148:149] op_sel_hi:[1,0]
	v_pk_mul_f32 v[182:183], v[122:123], v[148:149] op_sel_hi:[1,0]
	v_pk_mul_f32 v[184:185], v[120:121], v[148:149] op_sel_hi:[1,0]
	v_mov_b32_e32 v122, v179
	v_mov_b32_e32 v123, v141
	v_pk_mul_f32 v[146:147], v[146:147], v[148:149] op_sel_hi:[1,0]
	v_pk_mul_f32 v[180:181], v[142:143], v[148:149] op_sel_hi:[1,0]
	v_mov_b32_e32 v120, v178
	v_mov_b32_e32 v121, v140
	v_mov_b32_e32 v188, v185
	v_mov_b32_e32 v189, v137
	v_pk_mul_f32 v[122:123], v[122:123], v[122:123]
	v_pk_mul_f32 v[138:139], v[138:139], v[148:149] op_sel_hi:[1,0]
	v_mov_b32_e32 v142, v146
	v_mov_b32_e32 v143, v180
	v_mov_b32_e32 v186, v184
	v_mov_b32_e32 v187, v136
	v_pk_mul_f32 v[188:189], v[188:189], v[188:189]
	v_pk_fma_f32 v[120:121], v[120:121], v[120:121], v[122:123]
	v_mov_b32_e32 v144, v147
	v_mov_b32_e32 v145, v181
	v_mov_b32_e32 v190, v182
	v_mov_b32_e32 v191, v138
	v_pk_fma_f32 v[122:123], v[186:187], v[186:187], v[188:189]
	v_pk_fma_f32 v[120:121], v[142:143], v[142:143], v[120:121]
	v_mov_b32_e32 v192, v183
	v_mov_b32_e32 v193, v139
	v_pk_fma_f32 v[122:123], v[190:191], v[190:191], v[122:123]
	v_pk_fma_f32 v[120:121], v[144:145], v[144:145], v[120:121]
	v_pk_fma_f32 v[122:123], v[192:193], v[192:193], v[122:123]
	v_add_f32_e32 v120, v120, v121
	v_add_f32_e32 v120, v123, v120
	v_add_f32_e32 v120, v122, v120
	ds_bpermute_b32 v121, v176, v120
	v_or_b32_e32 v122, s47, v173
	v_lshlrev_b32_e32 v122, 13, v122
	v_add3_u32 v144, v196, v195, v122
	v_ashrrev_i32_e32 v145, 31, v144
	s_waitcnt lgkmcnt(0)
	v_add_f32_e32 v120, v120, v121
	ds_bpermute_b32 v121, v175, v120
	v_lshl_add_u64 v[142:143], s[48:49], 0, v[156:157]
	v_pk_mul_f32 v[108:109], v[108:109], v[148:149] op_sel:[0,1]
	v_pk_mul_f32 v[100:101], v[100:101], v[148:149] op_sel:[0,1]
	v_pk_mul_f32 v[192:193], v[96:97], v[148:149] op_sel:[0,1]
	s_waitcnt lgkmcnt(0)
; DI u32x2 pk4(f32x4 v) { u32x2 r; r.x = pk2(v[0], v[1]); r.y = pk2(v[2], v[3]); return r; }
; template <int REG>
; DI void epi_inproj(const Params& p, f32x4 (&acc)[2][2][4][2], int pm, int pn, LAS unsigned char* shm) {
;     ...
;       for (int m = 0; m < 4; ++m) { asm volatile("" ::: "memory");
;         const int r = 128 * ai + 64 * wr + 16 * m + fr, t = t0 + r;
;         const float rs = rsr[ai][m];
;         f32x4 v[2][2]; float ss = 0.f;
; #pragma unroll
;         for (int bj = 0; bj < 2; ++bj)
; #pragma unroll
;           for (int n = 0; n < 2; ++n) { v[bj][n] = acc[ai][bj][m][n] * rs; ss += v[bj][n][0] * v[bj][n][0] + v[bj][n][1] * v[bj][n][1] + v[bj][n][2] * v[bj][n][2] + v[bj][n][3] * v[bj][n][3]; }
;         ss += __shfl_xor(ss, 16); ss += __shfl_xor(ss, 32);
;         const float rn = __builtin_amdgcn_rsqf(ss * (1.0f / 64.0f) + 1e-6f) * (isk ? 1.0f : 0.125f * 1.4426950408889634f);
;         bf16_t* dst = dstb + ((long)((b * 8 + hh) * SEQ + t)) * 64 + 8 * fq;
; #pragma unroll
;         for (int bj = 0; bj < 2; ++bj) {
;           const f32x4 o0 = v[bj][0] * rn * w4[bj][0], o1 = v[bj][1] * rn * w4[bj][1]; cs4[bj][0] += o0; cs4[bj][1] += o1;
;           const u32x2 h0 = pk4(o0), h1 = pk4(o1);
;           *(u32x4*)(dst + 32 * bj) = (u32x4){h0.x, h0.y, h1.x, h1.y};
;         }
	v_add_f32_e32 v120, v120, v121
	v_fmamk_f32 v120, v120, 0x3c800000, v166
	v_rsq_f32_e32 v122, v120
	v_lshlrev_b64 v[120:121], 7, v[144:145]
	v_lshl_add_u64 v[186:187], v[142:143], 0, v[120:121]
	v_lshl_add_u64 v[186:187], v[186:187], 0, v[238:239]
	v_pk_mul_f32 v[110:111], v[110:111], v[148:149] op_sel:[0,1]
	v_mul_f32_e32 v156, v174, v122
	v_pk_mul_f32 v[120:121], v[178:179], v[156:157] op_sel_hi:[1,0]
	v_pk_mul_f32 v[122:123], v[146:147], v[156:157] op_sel_hi:[1,0]
	v_pk_mul_f32 v[146:147], v[140:141], v[156:157] op_sel_hi:[1,0]
	v_pk_mul_f32 v[178:179], v[180:181], v[156:157] op_sel_hi:[1,0]
	v_pk_mul_f32 v[188:189], v[136:137], v[156:157] op_sel_hi:[1,0]
	v_pk_mul_f32 v[190:191], v[138:139], v[156:157] op_sel_hi:[1,0]
	v_pk_mul_f32 v[138:139], v[134:135], v[122:123]
	v_pk_mul_f32 v[140:141], v[132:133], v[120:121]
	v_pk_mul_f32 v[122:123], v[126:127], v[178:179]
	v_pk_mul_f32 v[136:137], v[124:125], v[146:147]
	v_cvt_pk_bf16_f32 v178, v140, v141
	v_cvt_pk_bf16_f32 v179, v138, v139
	v_cvt_pk_bf16_f32 v180, v136, v137
	v_cvt_pk_bf16_f32 v181, v122, v123
	global_store_dwordx4 v[186:187], v[178:181], off nt
	v_pk_mul_f32 v[146:147], v[106:107], v[148:149] op_sel:[0,1]
	v_mov_b32_e32 v106, v109
	v_pk_mul_f32 v[178:179], v[104:105], v[148:149] op_sel:[0,1]
	v_pk_mul_f32 v[120:121], v[130:131], v[190:191]
	v_mov_b32_e32 v107, v179
	v_mov_b32_e32 v104, v108
	v_mov_b32_e32 v105, v178
	v_pk_mul_f32 v[106:107], v[106:107], v[106:107]
	v_pk_mul_f32 v[190:191], v[98:99], v[148:149] op_sel:[0,1]
	v_mov_b32_e32 v98, v193
	v_mov_b32_e32 v99, v101
	v_pk_fma_f32 v[104:105], v[104:105], v[104:105], v[106:107]
	v_mov_b32_e32 v106, v110
	v_mov_b32_e32 v107, v146
	v_pk_mul_f32 v[180:181], v[102:103], v[148:149] op_sel:[0,1]
	v_mov_b32_e32 v96, v192
	v_mov_b32_e32 v97, v100
	v_pk_mul_f32 v[98:99], v[98:99], v[98:99]
	v_pk_fma_f32 v[104:105], v[106:107], v[106:107], v[104:105]
	v_mov_b32_e32 v106, v111
	v_mov_b32_e32 v107, v147
	v_pk_fma_f32 v[96:97], v[96:97], v[96:97], v[98:99]
	v_mov_b32_e32 v98, v190
	v_mov_b32_e32 v99, v180
	v_pk_fma_f32 v[104:105], v[106:107], v[106:107], v[104:105]
	v_pk_fma_f32 v[96:97], v[98:99], v[98:99], v[96:97]
	v_mov_b32_e32 v98, v191
	v_mov_b32_e32 v99, v181
	v_pk_fma_f32 v[96:97], v[98:99], v[98:99], v[96:97]
	v_add_f32_e32 v98, v104, v105
	v_add_f32_e32 v97, v97, v98
	v_add_f32_e32 v104, v96, v97
	ds_bpermute_b32 v105, v176, v104
	v_pk_mul_f32 v[98:99], v[184:185], v[156:157] op_sel_hi:[1,0]
	v_pk_mul_f32 v[96:97], v[182:183], v[156:157] op_sel_hi:[1,0]
	v_pk_mul_f32 v[102:103], v[128:129], v[188:189]
	v_pk_mul_f32 v[96:97], v[118:119], v[96:97]
	s_waitcnt lgkmcnt(0)
	v_add_f32_e32 v107, v104, v105
	ds_bpermute_b32 v145, v175, v107
	v_pk_mul_f32 v[98:99], v[116:117], v[98:99]
	v_cvt_pk_bf16_f32 v104, v102, v103
	v_cvt_pk_bf16_f32 v105, v120, v121
	v_cvt_pk_bf16_f32 v106, v98, v99
	s_waitcnt lgkmcnt(0)
	v_add_f32_e32 v107, v107, v145
	v_fmamk_f32 v107, v107, 0x3c800000, v166
	v_rsq_f32_e32 v145, v107
	v_cvt_pk_bf16_f32 v107, v96, v97
	v_lshl_add_u64 v[186:187], v[186:187], 0, s[100:101]
	global_store_dwordx4 v[186:187], v[104:107], off offset:64 nt
	v_pk_mul_f32 v[92:93], v[92:93], v[150:151] op_sel_hi:[1,0]
	v_mul_f32_e32 v156, v174, v145
	v_or_b32_e32 v104, 16, v144
	v_ashrrev_i32_e32 v105, 31, v104
	v_lshlrev_b64 v[104:105], 7, v[104:105]
	v_lshl_add_u64 v[182:183], v[142:143], 0, v[104:105]
	v_lshl_add_u64 v[182:183], v[182:183], 0, v[240:241]
	v_pk_mul_f32 v[104:105], v[108:109], v[156:157] op_sel_hi:[1,0]
	v_pk_mul_f32 v[106:107], v[110:111], v[156:157] op_sel_hi:[1,0]
	v_pk_mul_f32 v[110:111], v[132:133], v[104:105]
	v_pk_mul_f32 v[108:109], v[134:135], v[106:107]
	v_pk_mul_f32 v[106:107], v[178:179], v[156:157] op_sel_hi:[1,0]
	v_pk_mul_f32 v[104:105], v[146:147], v[156:157] op_sel_hi:[1,0]
	v_pk_mul_f32 v[106:107], v[124:125], v[106:107]
	v_pk_mul_f32 v[104:105], v[126:127], v[104:105]
	v_cvt_pk_bf16_f32 v146, v110, v111
	v_cvt_pk_bf16_f32 v147, v108, v109
	v_cvt_pk_bf16_f32 v148, v106, v107
	v_cvt_pk_bf16_f32 v149, v104, v105
	v_pk_mul_f32 v[178:179], v[88:89], v[150:151] op_sel_hi:[1,0]
	global_store_dwordx4 v[182:183], v[146:149], off nt
	v_pk_mul_f32 v[84:85], v[84:85], v[150:151] op_sel_hi:[1,0]
	v_pk_mul_f32 v[186:187], v[80:81], v[150:151] op_sel_hi:[1,0]
	v_pk_mul_f32 v[148:149], v[90:91], v[150:151] op_sel_hi:[1,0]
	v_mov_b32_e32 v90, v93
	v_mov_b32_e32 v91, v179
	v_pk_mul_f32 v[94:95], v[94:95], v[150:151] op_sel_hi:[1,0]
	v_mov_b32_e32 v88, v92
	v_mov_b32_e32 v89, v178
	v_pk_mul_f32 v[90:91], v[90:91], v[90:91]
	v_pk_mul_f32 v[184:185], v[82:83], v[150:151] op_sel_hi:[1,0]
	v_mov_b32_e32 v82, v187
	v_mov_b32_e32 v83, v85
	v_pk_mul_f32 v[146:147], v[100:101], v[156:157] op_sel_hi:[1,0]
	v_pk_mul_f32 v[100:101], v[180:181], v[156:157] op_sel_hi:[1,0]
	v_pk_fma_f32 v[88:89], v[88:89], v[88:89], v[90:91]
	v_mov_b32_e32 v90, v94
	v_mov_b32_e32 v91, v148
	v_pk_mul_f32 v[180:181], v[86:87], v[150:151] op_sel_hi:[1,0]
	v_mov_b32_e32 v80, v186
	v_mov_b32_e32 v81, v84
	v_pk_mul_f32 v[82:83], v[82:83], v[82:83]
	v_pk_fma_f32 v[88:89], v[90:91], v[90:91], v[88:89]
	v_mov_b32_e32 v90, v95
	v_mov_b32_e32 v91, v149
	v_pk_fma_f32 v[80:81], v[80:81], v[80:81], v[82:83]
	v_mov_b32_e32 v82, v184
	v_mov_b32_e32 v83, v180
	v_pk_fma_f32 v[88:89], v[90:91], v[90:91], v[88:89]
	v_pk_fma_f32 v[80:81], v[82:83], v[82:83], v[80:81]
	v_mov_b32_e32 v82, v185
	v_mov_b32_e32 v83, v181
	v_pk_fma_f32 v[80:81], v[82:83], v[82:83], v[80:81]
	v_add_f32_e32 v82, v88, v89
	v_add_f32_e32 v81, v81, v82
	v_add_f32_e32 v88, v80, v81
	ds_bpermute_b32 v89, v176, v88
	v_pk_mul_f32 v[82:83], v[192:193], v[156:157] op_sel_hi:[1,0]
	v_pk_mul_f32 v[80:81], v[190:191], v[156:157] op_sel_hi:[1,0]
	v_pk_mul_f32 v[100:101], v[130:131], v[100:101]
	v_pk_mul_f32 v[86:87], v[128:129], v[146:147]
	s_waitcnt lgkmcnt(0)
; DI u32x2 pk4(f32x4 v) { u32x2 r; r.x = pk2(v[0], v[1]); r.y = pk2(v[2], v[3]); return r; }
; template <int REG>
; DI void epi_inproj(const Params& p, f32x4 (&acc)[2][2][4][2], int pm, int pn, LAS unsigned char* shm) {
;     ...
;       for (int m = 0; m < 4; ++m) { asm volatile("" ::: "memory");
;         const int r = 128 * ai + 64 * wr + 16 * m + fr, t = t0 + r;
;         const float rs = rsr[ai][m];
;         f32x4 v[2][2]; float ss = 0.f;
; #pragma unroll
;         for (int bj = 0; bj < 2; ++bj)
; #pragma unroll
;           for (int n = 0; n < 2; ++n) { v[bj][n] = acc[ai][bj][m][n] * rs; ss += v[bj][n][0] * v[bj][n][0] + v[bj][n][1] * v[bj][n][1] + v[bj][n][2] * v[bj][n][2] + v[bj][n][3] * v[bj][n][3]; }
;         ss += __shfl_xor(ss, 16); ss += __shfl_xor(ss, 32);
;         const float rn = __builtin_amdgcn_rsqf(ss * (1.0f / 64.0f) + 1e-6f) * (isk ? 1.0f : 0.125f * 1.4426950408889634f);
;         bf16_t* dst = dstb + ((long)((b * 8 + hh) * SEQ + t)) * 64 + 8 * fq;
; #pragma unroll
;         for (int bj = 0; bj < 2; ++bj) {
;           const f32x4 o0 = v[bj][0] * rn * w4[bj][0], o1 = v[bj][1] * rn * w4[bj][1]; cs4[bj][0] += o0; cs4[bj][1] += o1;
;           const u32x2 h0 = pk4(o0), h1 = pk4(o1);
;           *(u32x4*)(dst + 32 * bj) = (u32x4){h0.x, h0.y, h1.x, h1.y};
;         }
	v_add_f32_e32 v91, v88, v89
	ds_bpermute_b32 v145, v175, v91
	v_pk_mul_f32 v[80:81], v[118:119], v[80:81]
	v_pk_mul_f32 v[82:83], v[116:117], v[82:83]
	v_cvt_pk_bf16_f32 v88, v86, v87
	v_cvt_pk_bf16_f32 v89, v100, v101
	s_waitcnt lgkmcnt(0)
	v_add_f32_e32 v91, v91, v145
	v_fmamk_f32 v91, v91, 0x3c800000, v166
	v_rsq_f32_e32 v145, v91
	v_cvt_pk_bf16_f32 v90, v82, v83
	v_cvt_pk_bf16_f32 v91, v80, v81
	v_lshl_add_u64 v[182:183], v[182:183], 0, s[100:101]
	global_store_dwordx4 v[182:183], v[88:91], off offset:64 nt
	v_mul_f32_e32 v150, v174, v145
	v_pk_mul_f32 v[60:61], v[60:61], v[112:113] op_sel_hi:[1,0]
	v_or_b32_e32 v88, 32, v144
	v_ashrrev_i32_e32 v89, 31, v88
	v_lshlrev_b64 v[88:89], 7, v[88:89]
	v_lshl_add_u64 v[182:183], v[142:143], 0, v[88:89]
	v_lshl_add_u64 v[182:183], v[182:183], 0, v[238:239]
	v_pk_mul_f32 v[88:89], v[92:93], v[150:151] op_sel_hi:[1,0]
	v_pk_mul_f32 v[90:91], v[94:95], v[150:151] op_sel_hi:[1,0]
	v_pk_mul_f32 v[94:95], v[132:133], v[88:89]
	v_pk_mul_f32 v[92:93], v[134:135], v[90:91]
	v_pk_mul_f32 v[90:91], v[178:179], v[150:151] op_sel_hi:[1,0]
	v_pk_mul_f32 v[88:89], v[148:149], v[150:151] op_sel_hi:[1,0]
	v_pk_mul_f32 v[90:91], v[124:125], v[90:91]
	v_pk_mul_f32 v[88:89], v[126:127], v[88:89]
	v_cvt_pk_bf16_f32 v146, v94, v95
	v_cvt_pk_bf16_f32 v147, v92, v93
	v_cvt_pk_bf16_f32 v148, v90, v91
	v_cvt_pk_bf16_f32 v149, v88, v89
	global_store_dwordx4 v[182:183], v[146:149], off nt
	v_pk_mul_f32 v[56:57], v[56:57], v[112:113] op_sel_hi:[1,0]
	v_pk_mul_f32 v[62:63], v[62:63], v[112:113] op_sel_hi:[1,0]
	v_mov_b32_e32 v148, v151
	v_pk_mul_f32 v[146:147], v[84:85], v[150:151] op_sel_hi:[1,0]
	v_pk_mul_f32 v[84:85], v[180:181], v[150:151] op_sel_hi:[1,0]
	v_pk_mul_f32 v[76:77], v[76:77], v[148:149] op_sel_hi:[1,0]
	v_pk_mul_f32 v[180:181], v[72:73], v[148:149] op_sel_hi:[1,0]
	v_pk_mul_f32 v[178:179], v[74:75], v[148:149] op_sel_hi:[1,0]
	v_mov_b32_e32 v74, v77
	v_mov_b32_e32 v75, v181
	v_pk_mul_f32 v[68:69], v[68:69], v[148:149] op_sel_hi:[1,0]
	v_pk_mul_f32 v[192:193], v[64:65], v[148:149] op_sel_hi:[1,0]
	v_pk_mul_f32 v[78:79], v[78:79], v[148:149] op_sel_hi:[1,0]
	v_mov_b32_e32 v72, v76
	v_mov_b32_e32 v73, v180
	v_pk_mul_f32 v[74:75], v[74:75], v[74:75]
	v_pk_mul_f32 v[190:191], v[66:67], v[148:149] op_sel_hi:[1,0]
	v_mov_b32_e32 v66, v193
	v_mov_b32_e32 v67, v69
	v_pk_fma_f32 v[72:73], v[72:73], v[72:73], v[74:75]
	v_mov_b32_e32 v74, v78
	v_mov_b32_e32 v75, v178
	v_pk_mul_f32 v[188:189], v[70:71], v[148:149] op_sel_hi:[1,0]
	v_mov_b32_e32 v64, v192
	v_mov_b32_e32 v65, v68
	v_pk_mul_f32 v[66:67], v[66:67], v[66:67]
	v_pk_fma_f32 v[72:73], v[74:75], v[74:75], v[72:73]
	v_mov_b32_e32 v74, v79
	v_mov_b32_e32 v75, v179
	v_pk_fma_f32 v[64:65], v[64:65], v[64:65], v[66:67]
	v_mov_b32_e32 v66, v190
	v_mov_b32_e32 v67, v188
	v_pk_fma_f32 v[72:73], v[74:75], v[74:75], v[72:73]
	v_pk_fma_f32 v[64:65], v[66:67], v[66:67], v[64:65]
	v_mov_b32_e32 v66, v191
	v_mov_b32_e32 v67, v189
	v_pk_fma_f32 v[64:65], v[66:67], v[66:67], v[64:65]
	v_add_f32_e32 v66, v72, v73
	v_add_f32_e32 v65, v65, v66
	v_add_f32_e32 v72, v64, v65
	ds_bpermute_b32 v73, v176, v72
	v_pk_mul_f32 v[66:67], v[186:187], v[150:151] op_sel_hi:[1,0]
	v_pk_mul_f32 v[64:65], v[184:185], v[150:151] op_sel_hi:[1,0]
	v_pk_mul_f32 v[84:85], v[130:131], v[84:85]
	v_pk_mul_f32 v[70:71], v[128:129], v[146:147]
	s_waitcnt lgkmcnt(0)
	v_add_f32_e32 v75, v72, v73
	ds_bpermute_b32 v145, v175, v75
	v_pk_mul_f32 v[64:65], v[118:119], v[64:65]
	v_pk_mul_f32 v[66:67], v[116:117], v[66:67]
	v_cvt_pk_bf16_f32 v72, v70, v71
	v_cvt_pk_bf16_f32 v73, v84, v85
	s_waitcnt lgkmcnt(0)
	v_add_f32_e32 v75, v75, v145
	v_fmamk_f32 v75, v75, 0x3c800000, v166
	v_rsq_f32_e32 v145, v75
	v_cvt_pk_bf16_f32 v74, v66, v67
	v_cvt_pk_bf16_f32 v75, v64, v65
	v_lshl_add_u64 v[182:183], v[182:183], 0, s[100:101]
	global_store_dwordx4 v[182:183], v[72:75], off offset:64 nt
	v_mul_f32_e32 v156, v174, v145
	v_pk_mul_f32 v[186:187], v[48:49], v[112:113] op_sel_hi:[1,0]
	v_or_b32_e32 v72, 48, v144
	v_ashrrev_i32_e32 v73, 31, v72
	v_lshlrev_b64 v[72:73], 7, v[72:73]
	v_lshl_add_u64 v[182:183], v[142:143], 0, v[72:73]
	v_lshl_add_u64 v[182:183], v[182:183], 0, v[240:241]
	v_pk_mul_f32 v[72:73], v[76:77], v[156:157] op_sel_hi:[1,0]
	v_pk_mul_f32 v[74:75], v[78:79], v[156:157] op_sel_hi:[1,0]
	v_pk_mul_f32 v[146:147], v[132:133], v[72:73]
	v_pk_mul_f32 v[78:79], v[134:135], v[74:75]
	v_pk_mul_f32 v[72:73], v[180:181], v[156:157] op_sel_hi:[1,0]
	v_pk_mul_f32 v[74:75], v[178:179], v[156:157] op_sel_hi:[1,0]
	v_pk_mul_f32 v[76:77], v[124:125], v[72:73]
	v_pk_mul_f32 v[74:75], v[126:127], v[74:75]
	v_cvt_pk_bf16_f32 v148, v146, v147
	v_cvt_pk_bf16_f32 v149, v78, v79
	v_cvt_pk_bf16_f32 v150, v76, v77
	v_cvt_pk_bf16_f32 v151, v74, v75
	global_store_dwordx4 v[182:183], v[148:151], off nt
	v_pk_mul_f32 v[180:181], v[52:53], v[112:113] op_sel_hi:[1,0]
	v_pk_mul_f32 v[184:185], v[50:51], v[112:113] op_sel_hi:[1,0]
	v_mov_b32_e32 v150, v61
	v_mov_b32_e32 v151, v57
	v_pk_mul_f32 v[148:149], v[58:59], v[112:113] op_sel_hi:[1,0]
	v_mov_b32_e32 v58, v60
	v_mov_b32_e32 v59, v56
	v_pk_mul_f32 v[150:151], v[150:151], v[150:151]
	v_mov_b32_e32 v50, v187
	v_mov_b32_e32 v51, v181
	v_pk_fma_f32 v[58:59], v[58:59], v[58:59], v[150:151]
	v_mov_b32_e32 v150, v62
	v_mov_b32_e32 v151, v148
	v_pk_mul_f32 v[178:179], v[54:55], v[112:113] op_sel_hi:[1,0]
	v_mov_b32_e32 v48, v186
	v_mov_b32_e32 v49, v180
	v_pk_mul_f32 v[50:51], v[50:51], v[50:51]
	v_pk_fma_f32 v[58:59], v[150:151], v[150:151], v[58:59]
	v_mov_b32_e32 v150, v63
	v_mov_b32_e32 v151, v149
	v_pk_fma_f32 v[48:49], v[48:49], v[48:49], v[50:51]
	v_mov_b32_e32 v50, v184
	v_mov_b32_e32 v51, v178
	v_pk_fma_f32 v[58:59], v[150:151], v[150:151], v[58:59]
	v_pk_fma_f32 v[48:49], v[50:51], v[50:51], v[48:49]
	v_mov_b32_e32 v50, v185
	v_mov_b32_e32 v51, v179
	v_pk_fma_f32 v[48:49], v[50:51], v[50:51], v[48:49]
	v_add_f32_e32 v50, v58, v59
	v_add_f32_e32 v49, v49, v50
	v_add_f32_e32 v52, v48, v49
	ds_bpermute_b32 v53, v176, v52
	v_pk_mul_f32 v[72:73], v[68:69], v[156:157] op_sel_hi:[1,0]
	v_pk_mul_f32 v[68:69], v[188:189], v[156:157] op_sel_hi:[1,0]
	v_pk_mul_f32 v[50:51], v[192:193], v[156:157] op_sel_hi:[1,0]
	v_pk_mul_f32 v[48:49], v[190:191], v[156:157] op_sel_hi:[1,0]
	s_waitcnt lgkmcnt(0)
; DI u32x2 pk4(f32x4 v) { u32x2 r; r.x = pk2(v[0], v[1]); r.y = pk2(v[2], v[3]); return r; }
; template <int REG>
; DI void epi_inproj(const Params& p, f32x4 (&acc)[2][2][4][2], int pm, int pn, LAS unsigned char* shm) {
;     ...
;       for (int m = 0; m < 4; ++m) { asm volatile("" ::: "memory");
;         const int r = 128 * ai + 64 * wr + 16 * m + fr, t = t0 + r;
;         const float rs = rsr[ai][m];
;         f32x4 v[2][2]; float ss = 0.f;
; #pragma unroll
;         for (int bj = 0; bj < 2; ++bj)
; #pragma unroll
;           for (int n = 0; n < 2; ++n) { v[bj][n] = acc[ai][bj][m][n] * rs; ss += v[bj][n][0] * v[bj][n][0] + v[bj][n][1] * v[bj][n][1] + v[bj][n][2] * v[bj][n][2] + v[bj][n][3] * v[bj][n][3]; }
;         ss += __shfl_xor(ss, 16); ss += __shfl_xor(ss, 32);
;         const float rn = __builtin_amdgcn_rsqf(ss * (1.0f / 64.0f) + 1e-6f) * (isk ? 1.0f : 0.125f * 1.4426950408889634f);
;         bf16_t* dst = dstb + ((long)((b * 8 + hh) * SEQ + t)) * 64 + 8 * fq;
; #pragma unroll
;         for (int bj = 0; bj < 2; ++bj) {
;           const f32x4 o0 = v[bj][0] * rn * w4[bj][0], o1 = v[bj][1] * rn * w4[bj][1]; cs4[bj][0] += o0; cs4[bj][1] += o1;
;           const u32x2 h0 = pk4(o0), h1 = pk4(o1);
;           *(u32x4*)(dst + 32 * bj) = (u32x4){h0.x, h0.y, h1.x, h1.y};
;         }
	v_add_f32_e32 v58, v52, v53
	ds_bpermute_b32 v59, v175, v58
	v_pk_mul_f32 v[68:69], v[130:131], v[68:69]
	v_pk_mul_f32 v[72:73], v[128:129], v[72:73]
	v_pk_mul_f32 v[48:49], v[118:119], v[48:49]
	v_pk_mul_f32 v[50:51], v[116:117], v[50:51]
	s_waitcnt lgkmcnt(0)
	v_add_f32_e32 v58, v58, v59
	v_fmamk_f32 v58, v58, 0x3c800000, v166
	v_rsq_f32_e32 v58, v58
	v_cvt_pk_bf16_f32 v52, v72, v73
	v_cvt_pk_bf16_f32 v53, v68, v69
	v_cvt_pk_bf16_f32 v54, v50, v51
	v_cvt_pk_bf16_f32 v55, v48, v49
	v_lshl_add_u64 v[182:183], v[182:183], 0, s[100:101]
	global_store_dwordx4 v[182:183], v[52:55], off offset:64 nt
	v_mul_f32_e32 v156, v174, v58
	v_pk_mul_f32 v[44:45], v[44:45], v[112:113] op_sel:[0,1]
	v_add_u32_e32 v52, 0x80, v144
	v_ashrrev_i32_e32 v53, 31, v52
	v_lshlrev_b64 v[52:53], 7, v[52:53]
	v_lshl_add_u64 v[182:183], v[142:143], 0, v[52:53]
	v_lshl_add_u64 v[182:183], v[182:183], 0, v[238:239]
	v_pk_mul_f32 v[52:53], v[60:61], v[156:157] op_sel_hi:[1,0]
	v_pk_mul_f32 v[54:55], v[62:63], v[156:157] op_sel_hi:[1,0]
	v_pk_mul_f32 v[60:61], v[132:133], v[52:53]
	v_pk_mul_f32 v[58:59], v[134:135], v[54:55]
	v_pk_mul_f32 v[52:53], v[56:57], v[156:157] op_sel_hi:[1,0]
	v_pk_mul_f32 v[54:55], v[148:149], v[156:157] op_sel_hi:[1,0]
	v_pk_mul_f32 v[56:57], v[124:125], v[52:53]
	v_pk_mul_f32 v[54:55], v[126:127], v[54:55]
	v_cvt_pk_bf16_f32 v148, v60, v61
	v_cvt_pk_bf16_f32 v149, v58, v59
	v_cvt_pk_bf16_f32 v150, v56, v57
	v_cvt_pk_bf16_f32 v151, v54, v55
	global_store_dwordx4 v[182:183], v[148:151], off nt
	v_pk_mul_f32 v[62:63], v[180:181], v[156:157] op_sel_hi:[1,0]
	v_pk_mul_f32 v[52:53], v[178:179], v[156:157] op_sel_hi:[1,0]
	v_pk_mul_f32 v[150:151], v[40:41], v[112:113] op_sel:[0,1]
	v_pk_mul_f32 v[46:47], v[46:47], v[112:113] op_sel:[0,1]
	v_pk_mul_f32 v[148:149], v[42:43], v[112:113] op_sel:[0,1]
	v_mov_b32_e32 v42, v45
	v_mov_b32_e32 v43, v151
	v_pk_mul_f32 v[178:179], v[38:39], v[112:113] op_sel:[0,1]
	v_pk_mul_f32 v[36:37], v[36:37], v[112:113] op_sel:[0,1]
	v_pk_mul_f32 v[180:181], v[34:35], v[112:113] op_sel:[0,1]
	v_pk_mul_f32 v[112:113], v[32:33], v[112:113] op_sel:[0,1]
	v_mov_b32_e32 v40, v44
	v_mov_b32_e32 v41, v150
	v_pk_mul_f32 v[42:43], v[42:43], v[42:43]
	v_mov_b32_e32 v34, v113
	v_mov_b32_e32 v35, v37
	v_pk_fma_f32 v[40:41], v[40:41], v[40:41], v[42:43]
	v_mov_b32_e32 v42, v46
	v_mov_b32_e32 v43, v148
	v_mov_b32_e32 v32, v112
	v_mov_b32_e32 v33, v36
	v_pk_mul_f32 v[34:35], v[34:35], v[34:35]
	v_pk_fma_f32 v[40:41], v[42:43], v[42:43], v[40:41]
	v_mov_b32_e32 v42, v47
	v_mov_b32_e32 v43, v149
	v_pk_fma_f32 v[32:33], v[32:33], v[32:33], v[34:35]
	v_mov_b32_e32 v34, v180
	v_mov_b32_e32 v35, v178
	v_pk_fma_f32 v[40:41], v[42:43], v[42:43], v[40:41]
	v_pk_fma_f32 v[32:33], v[34:35], v[34:35], v[32:33]
	v_mov_b32_e32 v34, v181
	v_mov_b32_e32 v35, v179
	v_pk_fma_f32 v[32:33], v[34:35], v[34:35], v[32:33]
	v_add_f32_e32 v34, v40, v41
	v_add_f32_e32 v33, v33, v34
	v_add_f32_e32 v40, v32, v33
	ds_bpermute_b32 v41, v176, v40
	v_pk_mul_f32 v[38:39], v[128:129], v[62:63]
	v_pk_mul_f32 v[34:35], v[186:187], v[156:157] op_sel_hi:[1,0]
	v_pk_mul_f32 v[32:33], v[184:185], v[156:157] op_sel_hi:[1,0]
	v_pk_mul_f32 v[52:53], v[130:131], v[52:53]
	s_waitcnt lgkmcnt(0)
	v_add_f32_e32 v43, v40, v41
	ds_bpermute_b32 v62, v175, v43
	v_pk_mul_f32 v[32:33], v[118:119], v[32:33]
	v_pk_mul_f32 v[34:35], v[116:117], v[34:35]
	v_cvt_pk_bf16_f32 v40, v38, v39
	v_cvt_pk_bf16_f32 v41, v52, v53
	s_waitcnt lgkmcnt(0)
	v_add_f32_e32 v43, v43, v62
	v_fmamk_f32 v43, v43, 0x3c800000, v166
	v_rsq_f32_e32 v62, v43
	v_cvt_pk_bf16_f32 v42, v34, v35
	v_cvt_pk_bf16_f32 v43, v32, v33
	v_lshl_add_u64 v[182:183], v[182:183], 0, s[100:101]
	global_store_dwordx4 v[182:183], v[40:43], off offset:64 nt
	v_mul_f32_e32 v62, v174, v62
	v_pk_mul_f32 v[28:29], v[28:29], v[114:115] op_sel_hi:[1,0]
	v_add_u32_e32 v40, 0x90, v144
	v_ashrrev_i32_e32 v41, 31, v40
	v_lshlrev_b64 v[40:41], 7, v[40:41]
	v_lshl_add_u64 v[182:183], v[142:143], 0, v[40:41]
	v_lshl_add_u64 v[182:183], v[182:183], 0, v[240:241]
	v_pk_mul_f32 v[40:41], v[44:45], v[62:63] op_sel_hi:[1,0]
	v_pk_mul_f32 v[42:43], v[46:47], v[62:63] op_sel_hi:[1,0]
	v_pk_mul_f32 v[46:47], v[132:133], v[40:41]
	v_pk_mul_f32 v[44:45], v[134:135], v[42:43]
	v_pk_mul_f32 v[42:43], v[150:151], v[62:63] op_sel_hi:[1,0]
	v_pk_mul_f32 v[40:41], v[148:149], v[62:63] op_sel_hi:[1,0]
	v_pk_mul_f32 v[42:43], v[124:125], v[42:43]
	v_pk_mul_f32 v[40:41], v[126:127], v[40:41]
	v_cvt_pk_bf16_f32 v148, v46, v47
	v_cvt_pk_bf16_f32 v149, v44, v45
	v_cvt_pk_bf16_f32 v150, v42, v43
	v_cvt_pk_bf16_f32 v151, v40, v41
	global_store_dwordx4 v[182:183], v[148:151], off nt
	v_pk_mul_f32 v[20:21], v[20:21], v[114:115] op_sel_hi:[1,0]
	v_pk_mul_f32 v[188:189], v[16:17], v[114:115] op_sel_hi:[1,0]
	v_pk_mul_f32 v[148:149], v[36:37], v[62:63] op_sel_hi:[1,0]
	v_pk_mul_f32 v[36:37], v[178:179], v[62:63] op_sel_hi:[1,0]
	v_pk_mul_f32 v[178:179], v[24:25], v[114:115] op_sel_hi:[1,0]
	v_pk_mul_f32 v[150:151], v[26:27], v[114:115] op_sel_hi:[1,0]
	v_mov_b32_e32 v26, v29
	v_mov_b32_e32 v27, v179
	v_pk_mul_f32 v[30:31], v[30:31], v[114:115] op_sel_hi:[1,0]
	v_mov_b32_e32 v24, v28
	v_mov_b32_e32 v25, v178
	v_pk_mul_f32 v[26:27], v[26:27], v[26:27]
	v_pk_mul_f32 v[186:187], v[18:19], v[114:115] op_sel_hi:[1,0]
	v_mov_b32_e32 v18, v189
	v_mov_b32_e32 v19, v21
	v_pk_fma_f32 v[24:25], v[24:25], v[24:25], v[26:27]
	v_mov_b32_e32 v26, v30
	v_mov_b32_e32 v27, v150
	v_pk_mul_f32 v[184:185], v[22:23], v[114:115] op_sel_hi:[1,0]
	v_mov_b32_e32 v16, v188
	v_mov_b32_e32 v17, v20
	v_pk_mul_f32 v[18:19], v[18:19], v[18:19]
	v_pk_fma_f32 v[24:25], v[26:27], v[26:27], v[24:25]
	v_mov_b32_e32 v26, v31
	v_mov_b32_e32 v27, v151
	v_pk_fma_f32 v[16:17], v[16:17], v[16:17], v[18:19]
	v_mov_b32_e32 v18, v186
	v_mov_b32_e32 v19, v184
	v_pk_fma_f32 v[24:25], v[26:27], v[26:27], v[24:25]
	v_pk_fma_f32 v[16:17], v[18:19], v[18:19], v[16:17]
	v_mov_b32_e32 v18, v187
	v_mov_b32_e32 v19, v185
	v_pk_fma_f32 v[16:17], v[18:19], v[18:19], v[16:17]
	v_add_f32_e32 v18, v24, v25
	v_add_f32_e32 v17, v17, v18
	v_add_f32_e32 v24, v16, v17
	ds_bpermute_b32 v25, v176, v24
	v_pk_mul_f32 v[18:19], v[112:113], v[62:63] op_sel_hi:[1,0]
	v_pk_mul_f32 v[16:17], v[180:181], v[62:63] op_sel_hi:[1,0]
	v_pk_mul_f32 v[36:37], v[130:131], v[36:37]
	v_pk_mul_f32 v[22:23], v[128:129], v[148:149]
	s_waitcnt lgkmcnt(0)
; DI u32x2 pk4(f32x4 v) { u32x2 r; r.x = pk2(v[0], v[1]); r.y = pk2(v[2], v[3]); return r; }
; template <int REG>
; DI void epi_inproj(const Params& p, f32x4 (&acc)[2][2][4][2], int pm, int pn, LAS unsigned char* shm) {
;     ...
;       for (int m = 0; m < 4; ++m) { asm volatile("" ::: "memory");
;         const int r = 128 * ai + 64 * wr + 16 * m + fr, t = t0 + r;
;         const float rs = rsr[ai][m];
;         f32x4 v[2][2]; float ss = 0.f;
; #pragma unroll
;         for (int bj = 0; bj < 2; ++bj)
; #pragma unroll
;           for (int n = 0; n < 2; ++n) { v[bj][n] = acc[ai][bj][m][n] * rs; ss += v[bj][n][0] * v[bj][n][0] + v[bj][n][1] * v[bj][n][1] + v[bj][n][2] * v[bj][n][2] + v[bj][n][3] * v[bj][n][3]; }
;         ss += __shfl_xor(ss, 16); ss += __shfl_xor(ss, 32);
;         const float rn = __builtin_amdgcn_rsqf(ss * (1.0f / 64.0f) + 1e-6f) * (isk ? 1.0f : 0.125f * 1.4426950408889634f);
;         bf16_t* dst = dstb + ((long)((b * 8 + hh) * SEQ + t)) * 64 + 8 * fq;
; #pragma unroll
;         for (int bj = 0; bj < 2; ++bj) {
;           const f32x4 o0 = v[bj][0] * rn * w4[bj][0], o1 = v[bj][1] * rn * w4[bj][1]; cs4[bj][0] += o0; cs4[bj][1] += o1;
;           const u32x2 h0 = pk4(o0), h1 = pk4(o1);
;           *(u32x4*)(dst + 32 * bj) = (u32x4){h0.x, h0.y, h1.x, h1.y};
;         }
	v_add_f32_e32 v27, v24, v25
	ds_bpermute_b32 v62, v175, v27
	v_pk_mul_f32 v[16:17], v[118:119], v[16:17]
	v_pk_mul_f32 v[18:19], v[116:117], v[18:19]
	v_cvt_pk_bf16_f32 v24, v22, v23
	v_cvt_pk_bf16_f32 v25, v36, v37
	s_waitcnt lgkmcnt(0)
	v_add_f32_e32 v27, v27, v62
	v_fmamk_f32 v27, v27, 0x3c800000, v166
	v_rsq_f32_e32 v62, v27
	v_cvt_pk_bf16_f32 v26, v18, v19
	v_cvt_pk_bf16_f32 v27, v16, v17
	v_lshl_add_u64 v[182:183], v[182:183], 0, s[100:101]
	global_store_dwordx4 v[182:183], v[24:27], off offset:64 nt
	v_mul_f32_e32 v112, v174, v62
	v_mov_b32_e32 v114, v115
	v_add_u32_e32 v24, 0xa0, v144
	v_ashrrev_i32_e32 v25, 31, v24
	v_lshlrev_b64 v[24:25], 7, v[24:25]
	v_lshl_add_u64 v[180:181], v[142:143], 0, v[24:25]
	v_lshl_add_u64 v[180:181], v[180:181], 0, v[238:239]
	v_pk_mul_f32 v[24:25], v[28:29], v[112:113] op_sel_hi:[1,0]
	v_pk_mul_f32 v[26:27], v[30:31], v[112:113] op_sel_hi:[1,0]
	v_pk_mul_f32 v[62:63], v[132:133], v[24:25]
	v_pk_mul_f32 v[28:29], v[134:135], v[26:27]
	v_pk_mul_f32 v[26:27], v[178:179], v[112:113] op_sel_hi:[1,0]
	v_pk_mul_f32 v[24:25], v[150:151], v[112:113] op_sel_hi:[1,0]
	v_pk_mul_f32 v[26:27], v[124:125], v[26:27]
	v_pk_mul_f32 v[24:25], v[126:127], v[24:25]
	v_cvt_pk_bf16_f32 v148, v62, v63
	v_cvt_pk_bf16_f32 v149, v28, v29
	v_cvt_pk_bf16_f32 v150, v26, v27
	v_cvt_pk_bf16_f32 v151, v24, v25
	global_store_dwordx4 v[180:181], v[148:151], off nt
	v_pk_mul_f32 v[12:13], v[12:13], v[114:115] op_sel_hi:[1,0]
	v_pk_mul_f32 v[30:31], v[20:21], v[112:113] op_sel_hi:[1,0]
	v_pk_mul_f32 v[150:151], v[8:9], v[114:115] op_sel_hi:[1,0]
	v_pk_mul_f32 v[20:21], v[184:185], v[112:113] op_sel_hi:[1,0]
	v_pk_mul_f32 v[148:149], v[10:11], v[114:115] op_sel_hi:[1,0]
	v_mov_b32_e32 v10, v13
	v_mov_b32_e32 v11, v151
	v_pk_mul_f32 v[182:183], v[4:5], v[114:115] op_sel_hi:[1,0]
	v_pk_mul_f32 v[184:185], v[0:1], v[114:115] op_sel_hi:[1,0]
	v_pk_mul_f32 v[14:15], v[14:15], v[114:115] op_sel_hi:[1,0]
	v_mov_b32_e32 v8, v12
	v_mov_b32_e32 v9, v150
	v_pk_mul_f32 v[10:11], v[10:11], v[10:11]
	v_mov_b32_e32 v4, v185
	v_mov_b32_e32 v5, v183
	v_pk_fma_f32 v[8:9], v[8:9], v[8:9], v[10:11]
	v_mov_b32_e32 v10, v14
	v_mov_b32_e32 v11, v148
	v_pk_mul_f32 v[178:179], v[6:7], v[114:115] op_sel_hi:[1,0]
	v_pk_mul_f32 v[2:3], v[2:3], v[114:115] op_sel_hi:[1,0]
	v_mov_b32_e32 v0, v184
	v_mov_b32_e32 v1, v182
	v_pk_mul_f32 v[4:5], v[4:5], v[4:5]
	v_pk_fma_f32 v[8:9], v[10:11], v[10:11], v[8:9]
	v_mov_b32_e32 v10, v15
	v_mov_b32_e32 v11, v149
	v_pk_fma_f32 v[0:1], v[0:1], v[0:1], v[4:5]
	v_mov_b32_e32 v4, v2
	v_mov_b32_e32 v5, v178
	v_pk_fma_f32 v[8:9], v[10:11], v[10:11], v[8:9]
	v_pk_fma_f32 v[0:1], v[4:5], v[4:5], v[0:1]
	v_mov_b32_e32 v4, v3
	v_mov_b32_e32 v5, v179
	v_pk_fma_f32 v[0:1], v[4:5], v[4:5], v[0:1]
	v_add_f32_e32 v4, v8, v9
	v_add_f32_e32 v1, v1, v4
	v_add_f32_e32 v6, v0, v1
	ds_bpermute_b32 v7, v176, v6
	v_pk_mul_f32 v[10:11], v[128:129], v[30:31]
	v_pk_mul_f32 v[4:5], v[188:189], v[112:113] op_sel_hi:[1,0]
	v_pk_mul_f32 v[0:1], v[186:187], v[112:113] op_sel_hi:[1,0]
	v_pk_mul_f32 v[20:21], v[130:131], v[20:21]
	s_waitcnt lgkmcnt(0)
	v_add_f32_e32 v9, v6, v7
	ds_bpermute_b32 v30, v175, v9
	v_pk_mul_f32 v[0:1], v[118:119], v[0:1]
	v_pk_mul_f32 v[4:5], v[116:117], v[4:5]
	v_cvt_pk_bf16_f32 v6, v10, v11
	v_cvt_pk_bf16_f32 v7, v20, v21
	s_waitcnt lgkmcnt(0)
	v_add_f32_e32 v9, v9, v30
	v_fmamk_f32 v9, v9, 0x3c800000, v166
	v_rsq_f32_e32 v30, v9
	v_cvt_pk_bf16_f32 v8, v4, v5
	v_cvt_pk_bf16_f32 v9, v0, v1
	v_lshl_add_u64 v[180:181], v[180:181], 0, s[100:101]
	global_store_dwordx4 v[180:181], v[6:9], off offset:64 nt
	v_mul_f32_e32 v156, v174, v30
	v_pk_mul_f32 v[2:3], v[2:3], v[156:157] op_sel_hi:[1,0]
	v_add_u32_e32 v6, 0xb0, v144
	v_ashrrev_i32_e32 v7, 31, v6
	v_lshlrev_b64 v[6:7], 7, v[6:7]
	v_lshl_add_u64 v[142:143], v[142:143], 0, v[6:7]
	v_lshl_add_u64 v[142:143], v[142:143], 0, v[240:241]
	v_pk_mul_f32 v[6:7], v[12:13], v[156:157] op_sel_hi:[1,0]
	v_pk_mul_f32 v[8:9], v[14:15], v[156:157] op_sel_hi:[1,0]
	v_pk_mul_f32 v[114:115], v[132:133], v[6:7]
	v_pk_mul_f32 v[112:113], v[134:135], v[8:9]
	v_pk_mul_f32 v[6:7], v[150:151], v[156:157] op_sel_hi:[1,0]
	v_pk_mul_f32 v[8:9], v[148:149], v[156:157] op_sel_hi:[1,0]
	v_pk_mul_f32 v[30:31], v[124:125], v[6:7]
	v_pk_mul_f32 v[14:15], v[126:127], v[8:9]
	v_cvt_pk_bf16_f32 v6, v114, v115
	v_cvt_pk_bf16_f32 v7, v112, v113
	v_cvt_pk_bf16_f32 v8, v30, v31
	v_cvt_pk_bf16_f32 v9, v14, v15
	global_store_dwordx4 v[142:143], v[6:9], off nt
	v_pk_mul_f32 v[2:3], v[118:119], v[2:3]
	s_nop 0
	v_pk_mul_f32 v[6:7], v[182:183], v[156:157] op_sel_hi:[1,0]
	v_pk_mul_f32 v[8:9], v[178:179], v[156:157] op_sel_hi:[1,0]
	v_pk_mul_f32 v[12:13], v[128:129], v[6:7]
	v_pk_mul_f32 v[6:7], v[184:185], v[156:157] op_sel_hi:[1,0]
	v_pk_mul_f32 v[8:9], v[130:131], v[8:9]
	v_pk_mul_f32 v[6:7], v[116:117], v[6:7]
	v_cvt_pk_bf16_f32 v116, v12, v13
	v_cvt_pk_bf16_f32 v117, v8, v9
	v_cvt_pk_bf16_f32 v118, v6, v7
	v_cvt_pk_bf16_f32 v119, v2, v3
	v_lshl_add_u64 v[142:143], v[142:143], 0, s[100:101]
	global_store_dwordx4 v[142:143], v[116:119], off offset:64 nt
	s_cbranch_scc1 .LBB0_471
; #define LAS __attribute__((address_space(3)))
; template <int REG>
; DI void epi_inproj(const Params& p, f32x4 (&acc)[2][2][4][2], int pm, int pn, LAS unsigned char* shm) {
;     ...
;     if (isk) {
;       LAS float* red = (LAS float*)(shm + 131072);
; #pragma unroll
;       for (int bj = 0; bj < 2; ++bj)
; #pragma unroll
;         for (int n = 0; n < 2; ++n)
; #pragma unroll
;           for (int j = 0; j < 4; ++j) {
;             float s = cs4[bj][n][j];
;             s += __shfl_xor(s, 1); s += __shfl_xor(s, 2); s += __shfl_xor(s, 4); s += __shfl_xor(s, 8);
;             if (fr == 0) red[wr * 256 + wc * 64 + 32 * bj + 8 * fq + 4 * n + j] = s;
;           }
	s_nop 1
	v_pk_add_f32 v[116:117], v[140:141], 0 op_sel_hi:[1,0]
	s_nop 0
	v_pk_add_f32 v[110:111], v[116:117], v[110:111]
	s_nop 0
	v_pk_add_f32 v[94:95], v[110:111], v[94:95]
	s_nop 0
	v_pk_add_f32 v[94:95], v[94:95], v[146:147]
	s_nop 0
	v_pk_add_f32 v[60:61], v[94:95], v[60:61]
	s_nop 0
	v_pk_add_f32 v[46:47], v[60:61], v[46:47]
	s_nop 0
	v_pk_add_f32 v[46:47], v[46:47], v[62:63]
	s_nop 0
	v_pk_add_f32 v[46:47], v[46:47], v[114:115]
	s_nop 0
	v_lshlrev_b32_e32 v110, 8, v173
	v_and_b32_e32 v63, 0x3fffff00, v168
	v_lshlrev_b32_e32 v63, 2, v63
	v_add3_u32 v63, s77, v63, v110
	v_add_u32_e32 v63, v63, v171
	v_cmp_eq_u32_e32 vcc, 0, v170
	v_add_f32_dpp v46, v46, v46 quad_perm:[1,0,3,2] row_mask:0xf bank_mask:0xf
	v_add_f32_dpp v47, v47, v47 quad_perm:[1,0,3,2] row_mask:0xf bank_mask:0xf
	s_nop 0
	v_add_f32_dpp v46, v46, v46 quad_perm:[2,3,0,1] row_mask:0xf bank_mask:0xf
	v_add_f32_dpp v47, v47, v47 quad_perm:[2,3,0,1] row_mask:0xf bank_mask:0xf
	s_nop 0
	v_add_f32_dpp v46, v46, v46 row_half_mirror row_mask:0xf bank_mask:0xf
	v_add_f32_dpp v47, v47, v47 row_half_mirror row_mask:0xf bank_mask:0xf
	s_nop 0
	v_add_f32_dpp v46, v46, v46 row_mirror row_mask:0xf bank_mask:0xf
	v_add_f32_dpp v47, v47, v47 row_mirror row_mask:0xf bank_mask:0xf
	s_nop 0
	s_and_saveexec_b64 s[22:23], vcc
	ds_write_b64 v63, v[46:47]
	s_or_b64 exec, exec, s[22:23]
	v_pk_add_f32 v[94:95], v[138:139], 0 op_sel_hi:[1,0]
	s_nop 0
	v_pk_add_f32 v[94:95], v[94:95], v[108:109]
	s_nop 0
	v_pk_add_f32 v[92:93], v[94:95], v[92:93]
	s_nop 0
	v_pk_add_f32 v[92:93], v[92:93], v[78:79]
	s_nop 0
	v_pk_add_f32 v[58:59], v[92:93], v[58:59]
	s_nop 0
	v_pk_add_f32 v[44:45], v[58:59], v[44:45]
	s_nop 0
	v_pk_add_f32 v[28:29], v[44:45], v[28:29]
	s_nop 0
	v_pk_add_f32 v[28:29], v[28:29], v[112:113]
	s_nop 0
	s_nop 0
	v_add_f32_dpp v28, v28, v28 quad_perm:[1,0,3,2] row_mask:0xf bank_mask:0xf
	v_add_f32_dpp v29, v29, v29 quad_perm:[1,0,3,2] row_mask:0xf bank_mask:0xf
	s_nop 0
	v_add_f32_dpp v28, v28, v28 quad_perm:[2,3,0,1] row_mask:0xf bank_mask:0xf
	v_add_f32_dpp v29, v29, v29 quad_perm:[2,3,0,1] row_mask:0xf bank_mask:0xf
	s_nop 0
	v_add_f32_dpp v28, v28, v28 row_half_mirror row_mask:0xf bank_mask:0xf
	v_add_f32_dpp v29, v29, v29 row_half_mirror row_mask:0xf bank_mask:0xf
	s_nop 0
	v_add_f32_dpp v28, v28, v28 row_mirror row_mask:0xf bank_mask:0xf
	v_add_f32_dpp v29, v29, v29 row_mirror row_mask:0xf bank_mask:0xf
	s_nop 0
	s_and_saveexec_b64 s[22:23], vcc
	ds_write_b64 v63, v[28:29] offset:8
	s_or_b64 exec, exec, s[22:23]
	v_pk_add_f32 v[28:29], v[136:137], 0 op_sel_hi:[1,0]
	s_nop 0
	v_pk_add_f32 v[28:29], v[28:29], v[106:107]
	s_nop 0
	v_pk_add_f32 v[28:29], v[28:29], v[90:91]
	s_nop 0
	v_pk_add_f32 v[28:29], v[28:29], v[76:77]
	s_nop 0
	v_pk_add_f32 v[28:29], v[28:29], v[56:57]
	s_nop 0
	v_pk_add_f32 v[28:29], v[28:29], v[42:43]
	s_nop 0
	v_pk_add_f32 v[26:27], v[28:29], v[26:27]
	s_nop 0
	v_pk_add_f32 v[26:27], v[26:27], v[30:31]
	s_nop 0
	s_nop 0
	v_add_f32_dpp v26, v26, v26 quad_perm:[1,0,3,2] row_mask:0xf bank_mask:0xf
	v_add_f32_dpp v27, v27, v27 quad_perm:[1,0,3,2] row_mask:0xf bank_mask:0xf
	s_nop 0
	v_add_f32_dpp v26, v26, v26 quad_perm:[2,3,0,1] row_mask:0xf bank_mask:0xf
	v_add_f32_dpp v27, v27, v27 quad_perm:[2,3,0,1] row_mask:0xf bank_mask:0xf
	s_nop 0
	v_add_f32_dpp v26, v26, v26 row_half_mirror row_mask:0xf bank_mask:0xf
	v_add_f32_dpp v27, v27, v27 row_half_mirror row_mask:0xf bank_mask:0xf
	s_nop 0
	v_add_f32_dpp v26, v26, v26 row_mirror row_mask:0xf bank_mask:0xf
	v_add_f32_dpp v27, v27, v27 row_mirror row_mask:0xf bank_mask:0xf
	s_nop 0
	s_and_saveexec_b64 s[22:23], vcc
	ds_write_b64 v63, v[26:27] offset:16
	s_or_b64 exec, exec, s[22:23]
	v_pk_add_f32 v[26:27], v[122:123], 0 op_sel_hi:[1,0]
	s_nop 0
	v_pk_add_f32 v[26:27], v[26:27], v[104:105]
	s_nop 0
	v_pk_add_f32 v[26:27], v[26:27], v[88:89]
	s_nop 0
	v_pk_add_f32 v[28:29], v[26:27], v[74:75]
	s_nop 0
	v_pk_add_f32 v[28:29], v[28:29], v[54:55]
	s_nop 0
	v_pk_add_f32 v[28:29], v[28:29], v[40:41]
	s_nop 0
	v_pk_add_f32 v[24:25], v[28:29], v[24:25]
	s_nop 0
	v_pk_add_f32 v[14:15], v[24:25], v[14:15]
	s_nop 0
	s_nop 0
	v_add_f32_dpp v14, v14, v14 quad_perm:[1,0,3,2] row_mask:0xf bank_mask:0xf
	v_add_f32_dpp v15, v15, v15 quad_perm:[1,0,3,2] row_mask:0xf bank_mask:0xf
	s_nop 0
	v_add_f32_dpp v14, v14, v14 quad_perm:[2,3,0,1] row_mask:0xf bank_mask:0xf
	v_add_f32_dpp v15, v15, v15 quad_perm:[2,3,0,1] row_mask:0xf bank_mask:0xf
	s_nop 0
	v_add_f32_dpp v14, v14, v14 row_half_mirror row_mask:0xf bank_mask:0xf
	v_add_f32_dpp v15, v15, v15 row_half_mirror row_mask:0xf bank_mask:0xf
	s_nop 0
	v_add_f32_dpp v14, v14, v14 row_mirror row_mask:0xf bank_mask:0xf
	v_add_f32_dpp v15, v15, v15 row_mirror row_mask:0xf bank_mask:0xf
	s_nop 0
	s_and_saveexec_b64 s[22:23], vcc
	ds_write_b64 v63, v[14:15] offset:24
	s_or_b64 exec, exec, s[22:23]
	v_pk_add_f32 v[14:15], v[102:103], 0 op_sel_hi:[1,0]
	s_nop 0
	v_pk_add_f32 v[14:15], v[14:15], v[86:87]
	s_nop 0
; #define LAS __attribute__((address_space(3)))
; template <int REG>
; DI void epi_inproj(const Params& p, f32x4 (&acc)[2][2][4][2], int pm, int pn, LAS unsigned char* shm) {
;     ...
;     if (isk) {
;       LAS float* red = (LAS float*)(shm + 131072);
; #pragma unroll
;       for (int bj = 0; bj < 2; ++bj)
; #pragma unroll
;         for (int n = 0; n < 2; ++n)
; #pragma unroll
;           for (int j = 0; j < 4; ++j) {
;             float s = cs4[bj][n][j];
;             s += __shfl_xor(s, 1); s += __shfl_xor(s, 2); s += __shfl_xor(s, 4); s += __shfl_xor(s, 8);
;             if (fr == 0) red[wr * 256 + wc * 64 + 32 * bj + 8 * fq + 4 * n + j] = s;
;           }
;       __syncthreads();
;       if (tid < 256) {
;         float* kbar = (float*)(ws + OFF_KBAR);
;         kbar[((long)((b * 8 + (pn & 1) * 4 + (tid >> 6)) * 32 + blk)) * 64 + (tid & 63)] = (red[tid] + red[256 + tid]) * (1.0f / 256.0f);
;       }
	v_pk_add_f32 v[14:15], v[14:15], v[70:71]
	s_nop 0
	v_pk_add_f32 v[14:15], v[14:15], v[72:73]
	s_nop 0
	v_pk_add_f32 v[14:15], v[14:15], v[38:39]
	s_nop 0
	v_pk_add_f32 v[14:15], v[14:15], v[22:23]
	s_nop 0
	v_pk_add_f32 v[10:11], v[14:15], v[10:11]
	s_nop 0
	v_pk_add_f32 v[10:11], v[10:11], v[12:13]
	s_nop 0
	s_nop 0
	v_add_f32_dpp v10, v10, v10 quad_perm:[1,0,3,2] row_mask:0xf bank_mask:0xf
	v_add_f32_dpp v11, v11, v11 quad_perm:[1,0,3,2] row_mask:0xf bank_mask:0xf
	s_nop 0
	v_add_f32_dpp v10, v10, v10 quad_perm:[2,3,0,1] row_mask:0xf bank_mask:0xf
	v_add_f32_dpp v11, v11, v11 quad_perm:[2,3,0,1] row_mask:0xf bank_mask:0xf
	s_nop 0
	v_add_f32_dpp v10, v10, v10 row_half_mirror row_mask:0xf bank_mask:0xf
	v_add_f32_dpp v11, v11, v11 row_half_mirror row_mask:0xf bank_mask:0xf
	s_nop 0
	v_add_f32_dpp v10, v10, v10 row_mirror row_mask:0xf bank_mask:0xf
	v_add_f32_dpp v11, v11, v11 row_mirror row_mask:0xf bank_mask:0xf
	s_nop 0
	s_and_saveexec_b64 s[22:23], vcc
	ds_write_b64 v63, v[10:11] offset:128
	s_or_b64 exec, exec, s[22:23]
	v_pk_add_f32 v[10:11], v[120:121], 0 op_sel_hi:[1,0]
	s_nop 0
	v_pk_add_f32 v[10:11], v[10:11], v[100:101]
	s_nop 0
	v_pk_add_f32 v[10:11], v[10:11], v[84:85]
	s_nop 0
	v_pk_add_f32 v[12:13], v[10:11], v[68:69]
	s_nop 0
	v_pk_add_f32 v[12:13], v[12:13], v[52:53]
	s_nop 0
	v_pk_add_f32 v[12:13], v[12:13], v[36:37]
	s_nop 0
	v_pk_add_f32 v[12:13], v[12:13], v[20:21]
	s_nop 0
	v_pk_add_f32 v[8:9], v[12:13], v[8:9]
	s_nop 0
	s_nop 0
	v_add_f32_dpp v8, v8, v8 quad_perm:[1,0,3,2] row_mask:0xf bank_mask:0xf
	v_add_f32_dpp v9, v9, v9 quad_perm:[1,0,3,2] row_mask:0xf bank_mask:0xf
	s_nop 0
	v_add_f32_dpp v8, v8, v8 quad_perm:[2,3,0,1] row_mask:0xf bank_mask:0xf
	v_add_f32_dpp v9, v9, v9 quad_perm:[2,3,0,1] row_mask:0xf bank_mask:0xf
	s_nop 0
	v_add_f32_dpp v8, v8, v8 row_half_mirror row_mask:0xf bank_mask:0xf
	v_add_f32_dpp v9, v9, v9 row_half_mirror row_mask:0xf bank_mask:0xf
	s_nop 0
	v_add_f32_dpp v8, v8, v8 row_mirror row_mask:0xf bank_mask:0xf
	v_add_f32_dpp v9, v9, v9 row_mirror row_mask:0xf bank_mask:0xf
	s_nop 0
	s_and_saveexec_b64 s[22:23], vcc
	ds_write_b64 v63, v[8:9] offset:136
	s_or_b64 exec, exec, s[22:23]
	v_pk_add_f32 v[8:9], v[98:99], 0 op_sel_hi:[1,0]
	s_nop 0
	v_pk_add_f32 v[8:9], v[8:9], v[82:83]
	s_nop 0
	v_pk_add_f32 v[8:9], v[8:9], v[66:67]
	s_nop 0
	v_pk_add_f32 v[8:9], v[8:9], v[50:51]
	s_nop 0
	v_pk_add_f32 v[8:9], v[8:9], v[34:35]
	s_nop 0
	v_pk_add_f32 v[8:9], v[8:9], v[18:19]
	s_nop 0
	v_pk_add_f32 v[4:5], v[8:9], v[4:5]
	s_nop 0
	v_pk_add_f32 v[4:5], v[4:5], v[6:7]
	s_nop 0
	s_nop 0
	v_add_f32_dpp v4, v4, v4 quad_perm:[1,0,3,2] row_mask:0xf bank_mask:0xf
	v_add_f32_dpp v5, v5, v5 quad_perm:[1,0,3,2] row_mask:0xf bank_mask:0xf
	s_nop 0
	v_add_f32_dpp v4, v4, v4 quad_perm:[2,3,0,1] row_mask:0xf bank_mask:0xf
	v_add_f32_dpp v5, v5, v5 quad_perm:[2,3,0,1] row_mask:0xf bank_mask:0xf
	s_nop 0
	v_add_f32_dpp v4, v4, v4 row_half_mirror row_mask:0xf bank_mask:0xf
	v_add_f32_dpp v5, v5, v5 row_half_mirror row_mask:0xf bank_mask:0xf
	s_nop 0
	v_add_f32_dpp v4, v4, v4 row_mirror row_mask:0xf bank_mask:0xf
	v_add_f32_dpp v5, v5, v5 row_mirror row_mask:0xf bank_mask:0xf
	s_nop 0
	s_and_saveexec_b64 s[22:23], vcc
	ds_write_b64 v63, v[4:5] offset:144
	s_or_b64 exec, exec, s[22:23]
	v_pk_add_f32 v[4:5], v[96:97], 0 op_sel_hi:[1,0]
	s_nop 0
	v_pk_add_f32 v[4:5], v[4:5], v[80:81]
	s_nop 0
	v_pk_add_f32 v[4:5], v[4:5], v[64:65]
	s_nop 0
	v_pk_add_f32 v[6:7], v[4:5], v[48:49]
	s_nop 0
	v_pk_add_f32 v[6:7], v[6:7], v[32:33]
	s_nop 0
	v_pk_add_f32 v[6:7], v[6:7], v[16:17]
	s_nop 0
	v_pk_add_f32 v[0:1], v[6:7], v[0:1]
	s_nop 0
	v_pk_add_f32 v[0:1], v[0:1], v[2:3]
	s_nop 0
	s_nop 0
	v_add_f32_dpp v0, v0, v0 quad_perm:[1,0,3,2] row_mask:0xf bank_mask:0xf
	v_add_f32_dpp v1, v1, v1 quad_perm:[1,0,3,2] row_mask:0xf bank_mask:0xf
	s_nop 0
	v_add_f32_dpp v0, v0, v0 quad_perm:[2,3,0,1] row_mask:0xf bank_mask:0xf
	v_add_f32_dpp v1, v1, v1 quad_perm:[2,3,0,1] row_mask:0xf bank_mask:0xf
	s_nop 0
	v_add_f32_dpp v0, v0, v0 row_half_mirror row_mask:0xf bank_mask:0xf
	v_add_f32_dpp v1, v1, v1 row_half_mirror row_mask:0xf bank_mask:0xf
	s_nop 0
	v_add_f32_dpp v0, v0, v0 row_mirror row_mask:0xf bank_mask:0xf
	v_add_f32_dpp v1, v1, v1 row_mirror row_mask:0xf bank_mask:0xf
	s_nop 0
	s_and_saveexec_b64 s[22:23], vcc
	ds_write_b64 v63, v[0:1] offset:152
	s_or_b64 exec, exec, s[22:23]
	v_cmp_gt_i32_e32 vcc, s64, v168
	s_waitcnt lgkmcnt(0)
	s_barrier
	s_and_saveexec_b64 s[22:23], vcc
	s_cbranch_execz .LBB0_470
	v_lshl_add_u32 v0, v168, 2, 0
	v_add_u32_e32 v0, 0x20000, v0
	ds_read2st64_b32 v[0:1], v0 offset1:4
	v_add_u32_e32 v2, s47, v169
	v_lshl_or_b32 v2, v2, 5, s46
	v_ashrrev_i32_e32 v3, 31, v2
	v_and_b32_e32 v4, 63, v168
	s_waitcnt lgkmcnt(0)
	v_add_f32_e32 v0, v0, v1
	v_mul_f32_e32 v5, 0x3b800000, v0
	v_lshlrev_b64 v[0:1], 8, v[2:3]
	v_lshl_add_u64 v[0:1], s[8:9], 0, v[0:1]
	v_lshlrev_b32_e32 v156, 2, v4
	v_lshl_add_u64 v[0:1], v[0:1], 0, v[156:157]
	global_store_dword v[0:1], v5, off
